# back-edge rotation: K-loop scalar updates and exit test moved in front of the loop-back barrier (all GEMM loops); attention: first K-fragment reads issued before the next tile's DMA block
# baseline (speedup 1.0000x reference)
.LBB0_117:
	ds_read_b128 v[130:133], v161
	ds_read_b128 v[134:137], v161 offset:1024
	ds_read_b128 v[170:173], v161 offset:2048
	ds_read_b128 v[174:177], v161 offset:3072
	ds_read_b128 v[178:181], v163
	ds_read_b128 v[182:185], v163 offset:1024
	ds_read_b128 v[186:189], v163 offset:2048
	ds_read_b128 v[190:193], v163 offset:3072
	s_add_u32 s50, s48, 0xfff80080
	s_addc_u32 s51, s49, -1
	s_cmp_eq_u32 s74, 28
	s_cselect_b32 s53, s9, s51
	s_cselect_b32 s52, s43, s50
	s_cselect_b32 s51, s41, s73
	s_cselect_b32 s50, s71, s72
	v_lshl_add_u64 v[154:155], s[48:49], 0, v[146:147]
	s_add_i32 m0, s56, 0xc000
	ds_read_b128 v[194:197], v165
	ds_read_b128 v[198:201], v165 offset:1024
	ds_read_b128 v[202:205], v165 offset:2048
	ds_read_b128 v[206:209], v165 offset:3072
	ds_read_b128 v[210:213], v165 offset:4096
	ds_read_b128 v[214:217], v165 offset:5120
	ds_read_b128 v[218:221], v165 offset:6144
	ds_read_b128 v[222:225], v165 offset:7168
	global_load_lds_dwordx4 v[154:155], off
	v_lshl_add_u64 v[154:155], s[48:49], 0, v[148:149]
	s_add_i32 m0, s56, 0xe000
	s_nop 0
	global_load_lds_dwordx4 v[154:155], off
	s_waitcnt vmcnt(8)
	s_waitcnt lgkmcnt(0)
	s_barrier
	s_setprio 1
	s_waitcnt lgkmcnt(0)
	v_mfma_f32_16x16x32_bf16 v[126:129], v[130:133], v[194:197], v[126:129]
	v_mfma_f32_16x16x32_bf16 v[122:125], v[170:173], v[194:197], v[122:125]
	v_mfma_f32_16x16x32_bf16 v[118:121], v[130:133], v[202:205], v[118:121]
	v_mfma_f32_16x16x32_bf16 v[110:113], v[170:173], v[202:205], v[110:113]
	v_mfma_f32_16x16x32_bf16 v[102:105], v[130:133], v[210:213], v[102:105]
	v_mfma_f32_16x16x32_bf16 v[94:97], v[170:173], v[210:213], v[94:97]
	v_mfma_f32_16x16x32_bf16 v[86:89], v[130:133], v[218:221], v[86:89]
	v_mfma_f32_16x16x32_bf16 v[78:81], v[170:173], v[218:221], v[78:81]
	v_mfma_f32_16x16x32_bf16 v[126:129], v[134:137], v[198:201], v[126:129]
	v_mfma_f32_16x16x32_bf16 v[122:125], v[174:177], v[198:201], v[122:125]
	v_mfma_f32_16x16x32_bf16 v[118:121], v[134:137], v[206:209], v[118:121]
	v_mfma_f32_16x16x32_bf16 v[110:113], v[174:177], v[206:209], v[110:113]
	v_mfma_f32_16x16x32_bf16 v[102:105], v[134:137], v[214:217], v[102:105]
	v_mfma_f32_16x16x32_bf16 v[94:97], v[174:177], v[214:217], v[94:97]
	v_mfma_f32_16x16x32_bf16 v[86:89], v[134:137], v[222:225], v[86:89]
	v_mfma_f32_16x16x32_bf16 v[78:81], v[174:177], v[222:225], v[78:81]
	s_setprio 0
	s_setprio 1
	v_mfma_f32_16x16x32_bf16 v[114:117], v[178:181], v[194:197], v[114:117]
	v_mfma_f32_16x16x32_bf16 v[106:109], v[186:189], v[194:197], v[106:109]
	v_mfma_f32_16x16x32_bf16 v[98:101], v[178:181], v[202:205], v[98:101]
	v_mfma_f32_16x16x32_bf16 v[90:93], v[186:189], v[202:205], v[90:93]
	v_mfma_f32_16x16x32_bf16 v[82:85], v[178:181], v[210:213], v[82:85]
	v_mfma_f32_16x16x32_bf16 v[74:77], v[186:189], v[210:213], v[74:77]
	v_mfma_f32_16x16x32_bf16 v[70:73], v[178:181], v[218:221], v[70:73]
	v_mfma_f32_16x16x32_bf16 v[66:69], v[186:189], v[218:221], v[66:69]
	v_mfma_f32_16x16x32_bf16 v[114:117], v[182:185], v[198:201], v[114:117]
	v_mfma_f32_16x16x32_bf16 v[106:109], v[190:193], v[198:201], v[106:109]
	v_mfma_f32_16x16x32_bf16 v[98:101], v[182:185], v[206:209], v[98:101]
	v_mfma_f32_16x16x32_bf16 v[90:93], v[190:193], v[206:209], v[90:93]
	v_mfma_f32_16x16x32_bf16 v[82:85], v[182:185], v[214:217], v[82:85]
	v_mfma_f32_16x16x32_bf16 v[74:77], v[190:193], v[214:217], v[74:77]
	v_mfma_f32_16x16x32_bf16 v[70:73], v[182:185], v[222:225], v[70:73]
	v_mfma_f32_16x16x32_bf16 v[66:69], v[190:193], v[222:225], v[66:69]
	s_setprio 0
	s_barrier
	s_add_i32 s75, s67, s55
	v_lshl_add_u64 v[154:155], s[50:51], 0, v[140:141]
	s_mov_b32 m0, s75
	ds_read_b128 v[194:197], v165 offset:16384
	ds_read_b128 v[198:201], v165 offset:17408
	ds_read_b128 v[202:205], v165 offset:18432
	ds_read_b128 v[206:209], v165 offset:19456
	ds_read_b128 v[210:213], v165 offset:20480
	ds_read_b128 v[214:217], v165 offset:21504
	ds_read_b128 v[218:221], v165 offset:22528
	ds_read_b128 v[222:225], v165 offset:23552
	global_load_lds_dwordx4 v[154:155], off
	s_add_i32 m0, s75, 0x2000
	s_add_u32 s76, s50, 0x80000
	v_lshl_add_u64 v[166:167], s[50:51], 0, v[144:145]
	s_addc_u32 s77, s51, 0
	s_add_i32 s75, s68, s55
	global_load_lds_dwordx4 v[166:167], off
	v_lshl_add_u64 v[226:227], s[76:77], 0, v[140:141]
	s_mov_b32 m0, s75
	v_lshl_add_u64 v[228:229], s[52:53], 0, v[142:143]
	global_load_lds_dwordx4 v[226:227], off
	v_lshl_add_u64 v[226:227], s[76:77], 0, v[144:145]
	s_add_i32 m0, s75, 0x2000
	s_nop 0
	global_load_lds_dwordx4 v[226:227], off
	v_lshl_add_u64 v[226:227], s[52:53], 0, v[138:139]
	s_mov_b32 m0, s56
	s_nop 0
	global_load_lds_dwordx4 v[226:227], off
	s_mov_b32 m0, s57
	s_nop 0
	global_load_lds_dwordx4 v[228:229], off
	s_waitcnt vmcnt(8)
	s_waitcnt lgkmcnt(0)
	s_barrier
	s_setprio 1
	s_waitcnt lgkmcnt(0)
	v_mfma_f32_16x16x32_bf16 v[62:65], v[130:133], v[194:197], v[62:65]
	v_mfma_f32_16x16x32_bf16 v[58:61], v[170:173], v[194:197], v[58:61]
	v_mfma_f32_16x16x32_bf16 v[54:57], v[130:133], v[202:205], v[54:57]
	v_mfma_f32_16x16x32_bf16 v[46:49], v[170:173], v[202:205], v[46:49]
	v_mfma_f32_16x16x32_bf16 v[38:41], v[130:133], v[210:213], v[38:41]
	v_mfma_f32_16x16x32_bf16 v[30:33], v[170:173], v[210:213], v[30:33]
	v_mfma_f32_16x16x32_bf16 v[22:25], v[130:133], v[218:221], v[22:25]
	v_mfma_f32_16x16x32_bf16 v[14:17], v[170:173], v[218:221], v[14:17]
	v_mfma_f32_16x16x32_bf16 v[62:65], v[134:137], v[198:201], v[62:65]
	v_mfma_f32_16x16x32_bf16 v[58:61], v[174:177], v[198:201], v[58:61]
	v_mfma_f32_16x16x32_bf16 v[54:57], v[134:137], v[206:209], v[54:57]
	v_mfma_f32_16x16x32_bf16 v[46:49], v[174:177], v[206:209], v[46:49]
	v_mfma_f32_16x16x32_bf16 v[38:41], v[134:137], v[214:217], v[38:41]
	v_mfma_f32_16x16x32_bf16 v[30:33], v[174:177], v[214:217], v[30:33]
	v_mfma_f32_16x16x32_bf16 v[22:25], v[134:137], v[222:225], v[22:25]
	v_mfma_f32_16x16x32_bf16 v[14:17], v[174:177], v[222:225], v[14:17]
	s_setprio 0
	s_setprio 1
	v_mfma_f32_16x16x32_bf16 v[50:53], v[178:181], v[194:197], v[50:53]
	v_mfma_f32_16x16x32_bf16 v[42:45], v[186:189], v[194:197], v[42:45]
	v_mfma_f32_16x16x32_bf16 v[34:37], v[178:181], v[202:205], v[34:37]
	v_mfma_f32_16x16x32_bf16 v[26:29], v[186:189], v[202:205], v[26:29]
	v_mfma_f32_16x16x32_bf16 v[18:21], v[178:181], v[210:213], v[18:21]
	v_mfma_f32_16x16x32_bf16 v[10:13], v[186:189], v[210:213], v[10:13]
	v_mfma_f32_16x16x32_bf16 v[6:9], v[178:181], v[218:221], v[6:9]
	v_mfma_f32_16x16x32_bf16 v[2:5], v[186:189], v[218:221], v[2:5]
	v_mfma_f32_16x16x32_bf16 v[50:53], v[182:185], v[198:201], v[50:53]
	v_mfma_f32_16x16x32_bf16 v[42:45], v[190:193], v[198:201], v[42:45]
	v_mfma_f32_16x16x32_bf16 v[34:37], v[182:185], v[206:209], v[34:37]
	v_mfma_f32_16x16x32_bf16 v[26:29], v[190:193], v[206:209], v[26:29]
	v_mfma_f32_16x16x32_bf16 v[18:21], v[182:185], v[214:217], v[18:21]
	v_mfma_f32_16x16x32_bf16 v[10:13], v[190:193], v[214:217], v[10:13]
	v_mfma_f32_16x16x32_bf16 v[6:9], v[182:185], v[222:225], v[6:9]
	v_mfma_f32_16x16x32_bf16 v[2:5], v[190:193], v[222:225], v[2:5]
	s_setprio 0
	s_barrier
	s_add_i32 s75, 0, 0x18000
	v_add_u32_e32 v156, s75, v159
	s_add_i32 s76, 0, 0x1c000
	ds_read_b128 v[130:133], v156
	ds_read_b128 v[134:137], v156 offset:1024
	ds_read_b128 v[170:173], v156 offset:2048
	ds_read_b128 v[174:177], v156 offset:3072
	v_add_u32_e32 v156, s76, v159
	ds_read_b128 v[178:181], v156
	ds_read_b128 v[182:185], v156 offset:1024
	ds_read_b128 v[186:189], v156 offset:2048
	ds_read_b128 v[190:193], v156 offset:3072
	s_add_u32 s52, s52, 0x80000
	s_addc_u32 s53, s53, 0
	s_mov_b32 m0, s58
	v_lshl_add_u64 v[230:231], s[52:53], 0, v[138:139]
	ds_read_b128 v[194:197], v165 offset:32768
	ds_read_b128 v[198:201], v165 offset:33792
	ds_read_b128 v[202:205], v165 offset:34816
	ds_read_b128 v[206:209], v165 offset:35840
	ds_read_b128 v[210:213], v165 offset:36864
	ds_read_b128 v[214:217], v165 offset:37888
	ds_read_b128 v[218:221], v165 offset:38912
	ds_read_b128 v[222:225], v165 offset:39936
	global_load_lds_dwordx4 v[230:231], off
	v_lshl_add_u64 v[230:231], s[52:53], 0, v[142:143]
	s_mov_b32 m0, s59
	s_nop 0
	global_load_lds_dwordx4 v[230:231], off
	s_waitcnt vmcnt(8)
	s_waitcnt lgkmcnt(0)
	s_barrier
	s_setprio 1
	s_waitcnt lgkmcnt(0)
	v_mfma_f32_16x16x32_bf16 v[126:129], v[130:133], v[194:197], v[126:129]
	v_mfma_f32_16x16x32_bf16 v[122:125], v[170:173], v[194:197], v[122:125]
	v_mfma_f32_16x16x32_bf16 v[118:121], v[130:133], v[202:205], v[118:121]
	v_mfma_f32_16x16x32_bf16 v[110:113], v[170:173], v[202:205], v[110:113]
	v_mfma_f32_16x16x32_bf16 v[102:105], v[130:133], v[210:213], v[102:105]
	v_mfma_f32_16x16x32_bf16 v[94:97], v[170:173], v[210:213], v[94:97]
	v_mfma_f32_16x16x32_bf16 v[86:89], v[130:133], v[218:221], v[86:89]
	v_mfma_f32_16x16x32_bf16 v[78:81], v[170:173], v[218:221], v[78:81]
	v_mfma_f32_16x16x32_bf16 v[126:129], v[134:137], v[198:201], v[126:129]
	v_mfma_f32_16x16x32_bf16 v[122:125], v[174:177], v[198:201], v[122:125]
	v_mfma_f32_16x16x32_bf16 v[118:121], v[134:137], v[206:209], v[118:121]
	v_mfma_f32_16x16x32_bf16 v[110:113], v[174:177], v[206:209], v[110:113]
	v_mfma_f32_16x16x32_bf16 v[102:105], v[134:137], v[214:217], v[102:105]
	v_mfma_f32_16x16x32_bf16 v[94:97], v[174:177], v[214:217], v[94:97]
	v_mfma_f32_16x16x32_bf16 v[86:89], v[134:137], v[222:225], v[86:89]
	v_mfma_f32_16x16x32_bf16 v[78:81], v[174:177], v[222:225], v[78:81]
	s_setprio 0
	s_setprio 1
	v_mfma_f32_16x16x32_bf16 v[114:117], v[178:181], v[194:197], v[114:117]
	v_mfma_f32_16x16x32_bf16 v[106:109], v[186:189], v[194:197], v[106:109]
	v_mfma_f32_16x16x32_bf16 v[98:101], v[178:181], v[202:205], v[98:101]
	v_mfma_f32_16x16x32_bf16 v[90:93], v[186:189], v[202:205], v[90:93]
	v_mfma_f32_16x16x32_bf16 v[82:85], v[178:181], v[210:213], v[82:85]
	v_mfma_f32_16x16x32_bf16 v[74:77], v[186:189], v[210:213], v[74:77]
	v_mfma_f32_16x16x32_bf16 v[70:73], v[178:181], v[218:221], v[70:73]
	v_mfma_f32_16x16x32_bf16 v[66:69], v[186:189], v[218:221], v[66:69]
	v_mfma_f32_16x16x32_bf16 v[114:117], v[182:185], v[198:201], v[114:117]
	v_mfma_f32_16x16x32_bf16 v[106:109], v[190:193], v[198:201], v[106:109]
	v_mfma_f32_16x16x32_bf16 v[98:101], v[182:185], v[206:209], v[98:101]
	v_mfma_f32_16x16x32_bf16 v[90:93], v[190:193], v[206:209], v[90:93]
	v_mfma_f32_16x16x32_bf16 v[82:85], v[182:185], v[214:217], v[82:85]
	v_mfma_f32_16x16x32_bf16 v[74:77], v[190:193], v[214:217], v[74:77]
	v_mfma_f32_16x16x32_bf16 v[70:73], v[182:185], v[222:225], v[70:73]
	v_mfma_f32_16x16x32_bf16 v[66:69], v[190:193], v[222:225], v[66:69]
	s_setprio 0
	s_barrier
	s_add_i32 s52, s75, s55
	v_lshl_add_u64 v[154:155], v[154:155], 0, s[12:13]
	s_mov_b32 m0, s52
	ds_read_b128 v[194:197], v165 offset:49152
	ds_read_b128 v[198:201], v165 offset:50176
	ds_read_b128 v[202:205], v165 offset:51200
	ds_read_b128 v[206:209], v165 offset:52224
	ds_read_b128 v[210:213], v165 offset:53248
	ds_read_b128 v[214:217], v165 offset:54272
	ds_read_b128 v[218:221], v165 offset:55296
	ds_read_b128 v[222:225], v165 offset:56320
	global_load_lds_dwordx4 v[154:155], off
	s_add_i32 m0, s52, 0x2000
	s_add_u32 s50, s50, 0x80080
	v_lshl_add_u64 v[154:155], v[166:167], 0, s[12:13]
	s_addc_u32 s51, s51, 0
	s_add_i32 s52, s76, s55
	global_load_lds_dwordx4 v[154:155], off
	v_lshl_add_u64 v[154:155], s[50:51], 0, v[140:141]
	s_mov_b32 m0, s52
	s_nop 0
	global_load_lds_dwordx4 v[154:155], off
	v_lshl_add_u64 v[154:155], s[50:51], 0, v[144:145]
	s_add_i32 m0, s52, 0x2000
	s_nop 0
	global_load_lds_dwordx4 v[154:155], off
	v_lshl_add_u64 v[154:155], v[226:227], 0, s[12:13]
	s_mov_b32 m0, s64
	s_nop 0
	global_load_lds_dwordx4 v[154:155], off
	v_lshl_add_u64 v[154:155], v[228:229], 0, s[12:13]
	s_mov_b32 m0, s65
	s_nop 0
	global_load_lds_dwordx4 v[154:155], off
	s_waitcnt vmcnt(8)
	s_waitcnt lgkmcnt(0)
	s_barrier
	s_setprio 1
	s_waitcnt lgkmcnt(0)
	v_mfma_f32_16x16x32_bf16 v[62:65], v[130:133], v[194:197], v[62:65]
	v_mfma_f32_16x16x32_bf16 v[58:61], v[170:173], v[194:197], v[58:61]
	v_mfma_f32_16x16x32_bf16 v[54:57], v[130:133], v[202:205], v[54:57]
	v_mfma_f32_16x16x32_bf16 v[46:49], v[170:173], v[202:205], v[46:49]
	v_mfma_f32_16x16x32_bf16 v[38:41], v[130:133], v[210:213], v[38:41]
	v_mfma_f32_16x16x32_bf16 v[30:33], v[170:173], v[210:213], v[30:33]
	v_mfma_f32_16x16x32_bf16 v[22:25], v[130:133], v[218:221], v[22:25]
	v_mfma_f32_16x16x32_bf16 v[14:17], v[170:173], v[218:221], v[14:17]
	v_mfma_f32_16x16x32_bf16 v[62:65], v[134:137], v[198:201], v[62:65]
	v_mfma_f32_16x16x32_bf16 v[58:61], v[174:177], v[198:201], v[58:61]
	v_mfma_f32_16x16x32_bf16 v[54:57], v[134:137], v[206:209], v[54:57]
	v_mfma_f32_16x16x32_bf16 v[46:49], v[174:177], v[206:209], v[46:49]
	v_mfma_f32_16x16x32_bf16 v[38:41], v[134:137], v[214:217], v[38:41]
	v_mfma_f32_16x16x32_bf16 v[30:33], v[174:177], v[214:217], v[30:33]
	v_mfma_f32_16x16x32_bf16 v[22:25], v[134:137], v[222:225], v[22:25]
	v_mfma_f32_16x16x32_bf16 v[14:17], v[174:177], v[222:225], v[14:17]
	s_setprio 0
	s_setprio 1
	v_mfma_f32_16x16x32_bf16 v[50:53], v[178:181], v[194:197], v[50:53]
	v_mfma_f32_16x16x32_bf16 v[42:45], v[186:189], v[194:197], v[42:45]
	v_mfma_f32_16x16x32_bf16 v[34:37], v[178:181], v[202:205], v[34:37]
	v_mfma_f32_16x16x32_bf16 v[26:29], v[186:189], v[202:205], v[26:29]
	v_mfma_f32_16x16x32_bf16 v[18:21], v[178:181], v[210:213], v[18:21]
	v_mfma_f32_16x16x32_bf16 v[10:13], v[186:189], v[210:213], v[10:13]
	v_mfma_f32_16x16x32_bf16 v[6:9], v[178:181], v[218:221], v[6:9]
	v_mfma_f32_16x16x32_bf16 v[2:5], v[186:189], v[218:221], v[2:5]
	v_mfma_f32_16x16x32_bf16 v[50:53], v[182:185], v[198:201], v[50:53]
	v_mfma_f32_16x16x32_bf16 v[42:45], v[190:193], v[198:201], v[42:45]
	v_mfma_f32_16x16x32_bf16 v[34:37], v[182:185], v[206:209], v[34:37]
	v_mfma_f32_16x16x32_bf16 v[26:29], v[190:193], v[206:209], v[26:29]
	v_mfma_f32_16x16x32_bf16 v[18:21], v[182:185], v[214:217], v[18:21]
	v_mfma_f32_16x16x32_bf16 v[10:13], v[190:193], v[214:217], v[10:13]
	v_mfma_f32_16x16x32_bf16 v[6:9], v[182:185], v[222:225], v[6:9]
	v_mfma_f32_16x16x32_bf16 v[2:5], v[190:193], v[222:225], v[2:5]
	s_setprio 0
	s_add_i32 s74, s74, 2
	s_add_u32 s48, s48, 0x100
	s_addc_u32 s49, s49, 0
	s_add_u32 s72, s72, 0x100
	s_addc_u32 s73, s73, 0
	s_cmp_gt_u32 s74, 29
	s_barrier
	s_cbranch_scc0 .LBB0_117
	s_and_b64 vcc, exec, s[28:29]
	s_cbranch_vccz .LBB0_120
	s_barrier

.LBB0_806:
	ds_read_b128 v[138:141], v144
	ds_read_b128 v[148:151], v144 offset:1024
	ds_read_b128 v[152:155], v144 offset:2048
	ds_read_b128 v[156:159], v144 offset:3072
	ds_read_b128 v[160:163], v145
	ds_read_b128 v[164:167], v145 offset:1024
	ds_read_b128 v[168:171], v145 offset:2048
	ds_read_b128 v[172:175], v145 offset:3072
	s_add_u32 s30, s28, 0x100
	s_addc_u32 s31, s29, 0
	s_add_u32 s34, s54, s28
	s_addc_u32 s35, s55, s29
	s_cmp_eq_u32 s56, 60
	s_cselect_b32 s36, 0, s30
	s_cselect_b32 s37, 0, s31
	s_cselect_b32 s34, s21, s34
	s_cselect_b32 s35, s8, s35
	s_add_u32 s36, s2, s36
	s_addc_u32 s37, s3, s37
	s_mov_b32 m0, s50
	v_lshl_add_u64 v[208:209], v[134:135], 0, s[28:29]
	ds_read_b128 v[176:179], v146
	ds_read_b128 v[180:183], v146 offset:1024
	ds_read_b128 v[184:187], v146 offset:2048
	ds_read_b128 v[188:191], v146 offset:3072
	ds_read_b128 v[192:195], v146 offset:4096
	ds_read_b128 v[196:199], v146 offset:5120
	ds_read_b128 v[200:203], v146 offset:6144
	ds_read_b128 v[204:207], v146 offset:7168
	global_load_lds_dwordx4 v[208:209], off
	v_lshl_add_u64 v[208:209], v[136:137], 0, s[28:29]
	s_mov_b32 m0, s51
	s_nop 0
	global_load_lds_dwordx4 v[208:209], off
	s_waitcnt vmcnt(8)
	s_waitcnt lgkmcnt(0)
	s_barrier
	s_setprio 1
	s_waitcnt lgkmcnt(0)
	v_mfma_f32_16x16x32_bf16 v[126:129], v[138:141], v[176:179], v[126:129]
	v_mfma_f32_16x16x32_bf16 v[122:125], v[152:155], v[176:179], v[122:125]
	v_mfma_f32_16x16x32_bf16 v[110:113], v[138:141], v[184:187], v[110:113]
	v_mfma_f32_16x16x32_bf16 v[106:109], v[152:155], v[184:187], v[106:109]
	v_mfma_f32_16x16x32_bf16 v[94:97], v[138:141], v[192:195], v[94:97]
	v_mfma_f32_16x16x32_bf16 v[90:93], v[152:155], v[192:195], v[90:93]
	v_mfma_f32_16x16x32_bf16 v[78:81], v[138:141], v[200:203], v[78:81]
	v_mfma_f32_16x16x32_bf16 v[74:77], v[152:155], v[200:203], v[74:77]
	v_mfma_f32_16x16x32_bf16 v[126:129], v[148:151], v[180:183], v[126:129]
	v_mfma_f32_16x16x32_bf16 v[122:125], v[156:159], v[180:183], v[122:125]
	v_mfma_f32_16x16x32_bf16 v[110:113], v[148:151], v[188:191], v[110:113]
	v_mfma_f32_16x16x32_bf16 v[106:109], v[156:159], v[188:191], v[106:109]
	v_mfma_f32_16x16x32_bf16 v[94:97], v[148:151], v[196:199], v[94:97]
	v_mfma_f32_16x16x32_bf16 v[90:93], v[156:159], v[196:199], v[90:93]
	v_mfma_f32_16x16x32_bf16 v[78:81], v[148:151], v[204:207], v[78:81]
	v_mfma_f32_16x16x32_bf16 v[74:77], v[156:159], v[204:207], v[74:77]
	s_setprio 0
	s_setprio 1
	v_mfma_f32_16x16x32_bf16 v[118:121], v[160:163], v[176:179], v[118:121]
	v_mfma_f32_16x16x32_bf16 v[114:117], v[168:171], v[176:179], v[114:117]
	v_mfma_f32_16x16x32_bf16 v[102:105], v[160:163], v[184:187], v[102:105]
	v_mfma_f32_16x16x32_bf16 v[98:101], v[168:171], v[184:187], v[98:101]
	v_mfma_f32_16x16x32_bf16 v[86:89], v[160:163], v[192:195], v[86:89]
	v_mfma_f32_16x16x32_bf16 v[82:85], v[168:171], v[192:195], v[82:85]
	v_mfma_f32_16x16x32_bf16 v[70:73], v[160:163], v[200:203], v[70:73]
	v_mfma_f32_16x16x32_bf16 v[66:69], v[168:171], v[200:203], v[66:69]
	v_mfma_f32_16x16x32_bf16 v[118:121], v[164:167], v[180:183], v[118:121]
	v_mfma_f32_16x16x32_bf16 v[114:117], v[172:175], v[180:183], v[114:117]
	v_mfma_f32_16x16x32_bf16 v[102:105], v[164:167], v[188:191], v[102:105]
	v_mfma_f32_16x16x32_bf16 v[98:101], v[172:175], v[188:191], v[98:101]
	v_mfma_f32_16x16x32_bf16 v[86:89], v[164:167], v[196:199], v[86:89]
	v_mfma_f32_16x16x32_bf16 v[82:85], v[172:175], v[196:199], v[82:85]
	v_mfma_f32_16x16x32_bf16 v[70:73], v[164:167], v[204:207], v[70:73]
	v_mfma_f32_16x16x32_bf16 v[66:69], v[172:175], v[204:207], v[66:69]
	s_setprio 0
	s_barrier
	s_add_i32 s28, s48, s33
	v_lshl_add_u64 v[208:209], s[34:35], 0, v[132:133]
	s_mov_b32 m0, s28
	ds_read_b128 v[176:179], v146 offset:16384
	ds_read_b128 v[180:183], v146 offset:17408
	ds_read_b128 v[184:187], v146 offset:18432
	ds_read_b128 v[188:191], v146 offset:19456
	ds_read_b128 v[192:195], v146 offset:20480
	ds_read_b128 v[196:199], v146 offset:21504
	ds_read_b128 v[200:203], v146 offset:22528
	ds_read_b128 v[204:207], v146 offset:23552
	global_load_lds_dwordx4 v[208:209], off
	s_add_i32 m0, s28, 0x2000
	s_add_u32 s28, s34, 0x100000
	v_lshl_add_u64 v[210:211], s[34:35], 0, v[130:131]
	s_addc_u32 s29, s35, 0
	s_add_i32 s57, s49, s33
	global_load_lds_dwordx4 v[210:211], off
	v_lshl_add_u64 v[212:213], s[28:29], 0, v[132:133]
	s_mov_b32 m0, s57
	v_lshl_add_u64 v[214:215], s[36:37], 0, v[130:131]
	global_load_lds_dwordx4 v[212:213], off
	v_lshl_add_u64 v[212:213], s[28:29], 0, v[130:131]
	s_add_i32 m0, s57, 0x2000
	s_nop 0
	global_load_lds_dwordx4 v[212:213], off
	v_lshl_add_u64 v[212:213], s[36:37], 0, v[132:133]
	s_mov_b32 m0, s39
	s_nop 0
	global_load_lds_dwordx4 v[212:213], off
	s_mov_b32 m0, s40
	s_nop 0
	global_load_lds_dwordx4 v[214:215], off
	s_waitcnt vmcnt(8)
	s_waitcnt lgkmcnt(0)
	s_barrier
	s_setprio 1
	s_waitcnt lgkmcnt(0)
	v_mfma_f32_16x16x32_bf16 v[62:65], v[138:141], v[176:179], v[62:65]
	v_mfma_f32_16x16x32_bf16 v[58:61], v[152:155], v[176:179], v[58:61]
	v_mfma_f32_16x16x32_bf16 v[46:49], v[138:141], v[184:187], v[46:49]
	v_mfma_f32_16x16x32_bf16 v[42:45], v[152:155], v[184:187], v[42:45]
	v_mfma_f32_16x16x32_bf16 v[30:33], v[138:141], v[192:195], v[30:33]
	v_mfma_f32_16x16x32_bf16 v[26:29], v[152:155], v[192:195], v[26:29]
	v_mfma_f32_16x16x32_bf16 v[14:17], v[138:141], v[200:203], v[14:17]
	v_mfma_f32_16x16x32_bf16 v[10:13], v[152:155], v[200:203], v[10:13]
	v_mfma_f32_16x16x32_bf16 v[62:65], v[148:151], v[180:183], v[62:65]
	v_mfma_f32_16x16x32_bf16 v[58:61], v[156:159], v[180:183], v[58:61]
	v_mfma_f32_16x16x32_bf16 v[46:49], v[148:151], v[188:191], v[46:49]
	v_mfma_f32_16x16x32_bf16 v[42:45], v[156:159], v[188:191], v[42:45]
	v_mfma_f32_16x16x32_bf16 v[30:33], v[148:151], v[196:199], v[30:33]
	v_mfma_f32_16x16x32_bf16 v[26:29], v[156:159], v[196:199], v[26:29]
	v_mfma_f32_16x16x32_bf16 v[14:17], v[148:151], v[204:207], v[14:17]
	v_mfma_f32_16x16x32_bf16 v[10:13], v[156:159], v[204:207], v[10:13]
	s_setprio 0
	s_setprio 1
	v_mfma_f32_16x16x32_bf16 v[54:57], v[160:163], v[176:179], v[54:57]
	v_mfma_f32_16x16x32_bf16 v[50:53], v[168:171], v[176:179], v[50:53]
	v_mfma_f32_16x16x32_bf16 v[38:41], v[160:163], v[184:187], v[38:41]
	v_mfma_f32_16x16x32_bf16 v[34:37], v[168:171], v[184:187], v[34:37]
	v_mfma_f32_16x16x32_bf16 v[22:25], v[160:163], v[192:195], v[22:25]
	v_mfma_f32_16x16x32_bf16 v[18:21], v[168:171], v[192:195], v[18:21]
	v_mfma_f32_16x16x32_bf16 v[6:9], v[160:163], v[200:203], v[6:9]
	v_mfma_f32_16x16x32_bf16 v[2:5], v[168:171], v[200:203], v[2:5]
	v_mfma_f32_16x16x32_bf16 v[54:57], v[164:167], v[180:183], v[54:57]
	v_mfma_f32_16x16x32_bf16 v[50:53], v[172:175], v[180:183], v[50:53]
	v_mfma_f32_16x16x32_bf16 v[38:41], v[164:167], v[188:191], v[38:41]
	v_mfma_f32_16x16x32_bf16 v[34:37], v[172:175], v[188:191], v[34:37]
	v_mfma_f32_16x16x32_bf16 v[22:25], v[164:167], v[196:199], v[22:25]
	v_mfma_f32_16x16x32_bf16 v[18:21], v[172:175], v[196:199], v[18:21]
	v_mfma_f32_16x16x32_bf16 v[6:9], v[164:167], v[204:207], v[6:9]
	v_mfma_f32_16x16x32_bf16 v[2:5], v[172:175], v[204:207], v[2:5]
	s_setprio 0
	s_barrier
	s_add_i32 s57, 0, 0x18000
	s_add_i32 s58, 0, 0x1c000
	v_add_u32_e32 v156, s57, v143
	v_add_u32_e32 v172, s58, v143
	ds_read_b128 v[138:141], v156
	ds_read_b128 v[148:151], v156 offset:1024
	ds_read_b128 v[152:155], v156 offset:2048
	ds_read_b128 v[156:159], v156 offset:3072
	ds_read_b128 v[160:163], v172
	ds_read_b128 v[164:167], v172 offset:1024
	ds_read_b128 v[168:171], v172 offset:2048
	ds_read_b128 v[172:175], v172 offset:3072
	s_add_u32 s28, s36, 0x100000
	s_addc_u32 s29, s37, 0
	s_mov_b32 m0, s41
	v_lshl_add_u64 v[216:217], s[28:29], 0, v[132:133]
	ds_read_b128 v[176:179], v146 offset:32768
	ds_read_b128 v[180:183], v146 offset:33792
	ds_read_b128 v[184:187], v146 offset:34816
	ds_read_b128 v[188:191], v146 offset:35840
	ds_read_b128 v[192:195], v146 offset:36864
	ds_read_b128 v[196:199], v146 offset:37888
	ds_read_b128 v[200:203], v146 offset:38912
	ds_read_b128 v[204:207], v146 offset:39936
	global_load_lds_dwordx4 v[216:217], off
	v_lshl_add_u64 v[216:217], s[28:29], 0, v[130:131]
	s_mov_b32 m0, s42
	s_nop 0
	global_load_lds_dwordx4 v[216:217], off
	s_waitcnt vmcnt(8)
	s_waitcnt lgkmcnt(0)
	s_barrier
	s_setprio 1
	s_waitcnt lgkmcnt(0)
	v_mfma_f32_16x16x32_bf16 v[126:129], v[138:141], v[176:179], v[126:129]
	v_mfma_f32_16x16x32_bf16 v[122:125], v[152:155], v[176:179], v[122:125]
	v_mfma_f32_16x16x32_bf16 v[110:113], v[138:141], v[184:187], v[110:113]
	v_mfma_f32_16x16x32_bf16 v[106:109], v[152:155], v[184:187], v[106:109]
	v_mfma_f32_16x16x32_bf16 v[94:97], v[138:141], v[192:195], v[94:97]
	v_mfma_f32_16x16x32_bf16 v[90:93], v[152:155], v[192:195], v[90:93]
	v_mfma_f32_16x16x32_bf16 v[78:81], v[138:141], v[200:203], v[78:81]
	v_mfma_f32_16x16x32_bf16 v[74:77], v[152:155], v[200:203], v[74:77]
	v_mfma_f32_16x16x32_bf16 v[126:129], v[148:151], v[180:183], v[126:129]
	v_mfma_f32_16x16x32_bf16 v[122:125], v[156:159], v[180:183], v[122:125]
	v_mfma_f32_16x16x32_bf16 v[110:113], v[148:151], v[188:191], v[110:113]
	v_mfma_f32_16x16x32_bf16 v[106:109], v[156:159], v[188:191], v[106:109]
	v_mfma_f32_16x16x32_bf16 v[94:97], v[148:151], v[196:199], v[94:97]
	v_mfma_f32_16x16x32_bf16 v[90:93], v[156:159], v[196:199], v[90:93]
	v_mfma_f32_16x16x32_bf16 v[78:81], v[148:151], v[204:207], v[78:81]
	v_mfma_f32_16x16x32_bf16 v[74:77], v[156:159], v[204:207], v[74:77]
	s_setprio 0
	s_setprio 1
	v_mfma_f32_16x16x32_bf16 v[118:121], v[160:163], v[176:179], v[118:121]
	v_mfma_f32_16x16x32_bf16 v[114:117], v[168:171], v[176:179], v[114:117]
	v_mfma_f32_16x16x32_bf16 v[102:105], v[160:163], v[184:187], v[102:105]
	v_mfma_f32_16x16x32_bf16 v[98:101], v[168:171], v[184:187], v[98:101]
	v_mfma_f32_16x16x32_bf16 v[86:89], v[160:163], v[192:195], v[86:89]
	v_mfma_f32_16x16x32_bf16 v[82:85], v[168:171], v[192:195], v[82:85]
	v_mfma_f32_16x16x32_bf16 v[70:73], v[160:163], v[200:203], v[70:73]
	v_mfma_f32_16x16x32_bf16 v[66:69], v[168:171], v[200:203], v[66:69]
	v_mfma_f32_16x16x32_bf16 v[118:121], v[164:167], v[180:183], v[118:121]
	v_mfma_f32_16x16x32_bf16 v[114:117], v[172:175], v[180:183], v[114:117]
	v_mfma_f32_16x16x32_bf16 v[102:105], v[164:167], v[188:191], v[102:105]
	v_mfma_f32_16x16x32_bf16 v[98:101], v[172:175], v[188:191], v[98:101]
	v_mfma_f32_16x16x32_bf16 v[86:89], v[164:167], v[196:199], v[86:89]
	v_mfma_f32_16x16x32_bf16 v[82:85], v[172:175], v[196:199], v[82:85]
	v_mfma_f32_16x16x32_bf16 v[70:73], v[164:167], v[204:207], v[70:73]
	v_mfma_f32_16x16x32_bf16 v[66:69], v[172:175], v[204:207], v[66:69]
	s_setprio 0
	s_barrier
	s_add_i32 s28, s57, s33
	v_lshl_add_u64 v[208:209], v[208:209], 0, s[16:17]
	s_mov_b32 m0, s28
	ds_read_b128 v[176:179], v146 offset:49152
	ds_read_b128 v[180:183], v146 offset:50176
	ds_read_b128 v[184:187], v146 offset:51200
	ds_read_b128 v[188:191], v146 offset:52224
	ds_read_b128 v[192:195], v146 offset:53248
	ds_read_b128 v[196:199], v146 offset:54272
	ds_read_b128 v[200:203], v146 offset:55296
	ds_read_b128 v[204:207], v146 offset:56320
	global_load_lds_dwordx4 v[208:209], off
	s_add_i32 m0, s28, 0x2000
	s_add_u32 s28, s34, 0x100080
	v_lshl_add_u64 v[208:209], v[210:211], 0, s[16:17]
	s_addc_u32 s29, s35, 0
	s_add_i32 s34, s58, s33
	global_load_lds_dwordx4 v[208:209], off
	v_lshl_add_u64 v[208:209], s[28:29], 0, v[132:133]
	s_mov_b32 m0, s34
	s_nop 0
	global_load_lds_dwordx4 v[208:209], off
	v_lshl_add_u64 v[208:209], s[28:29], 0, v[130:131]
	s_add_i32 m0, s34, 0x2000
	s_nop 0
	global_load_lds_dwordx4 v[208:209], off
	v_lshl_add_u64 v[208:209], v[212:213], 0, s[16:17]
	s_mov_b32 m0, s45
	s_nop 0
	global_load_lds_dwordx4 v[208:209], off
	v_lshl_add_u64 v[208:209], v[214:215], 0, s[16:17]
	s_mov_b32 m0, s46
	s_nop 0
	global_load_lds_dwordx4 v[208:209], off
	s_waitcnt vmcnt(8)
	s_waitcnt lgkmcnt(0)
	s_barrier
	s_setprio 1
	s_waitcnt lgkmcnt(0)
	v_mfma_f32_16x16x32_bf16 v[62:65], v[138:141], v[176:179], v[62:65]
	v_mfma_f32_16x16x32_bf16 v[58:61], v[152:155], v[176:179], v[58:61]
	v_mfma_f32_16x16x32_bf16 v[46:49], v[138:141], v[184:187], v[46:49]
	v_mfma_f32_16x16x32_bf16 v[42:45], v[152:155], v[184:187], v[42:45]
	v_mfma_f32_16x16x32_bf16 v[30:33], v[138:141], v[192:195], v[30:33]
	v_mfma_f32_16x16x32_bf16 v[26:29], v[152:155], v[192:195], v[26:29]
	v_mfma_f32_16x16x32_bf16 v[14:17], v[138:141], v[200:203], v[14:17]
	v_mfma_f32_16x16x32_bf16 v[10:13], v[152:155], v[200:203], v[10:13]
	v_mfma_f32_16x16x32_bf16 v[62:65], v[148:151], v[180:183], v[62:65]
	v_mfma_f32_16x16x32_bf16 v[58:61], v[156:159], v[180:183], v[58:61]
	v_mfma_f32_16x16x32_bf16 v[46:49], v[148:151], v[188:191], v[46:49]
	v_mfma_f32_16x16x32_bf16 v[42:45], v[156:159], v[188:191], v[42:45]
	v_mfma_f32_16x16x32_bf16 v[30:33], v[148:151], v[196:199], v[30:33]
	v_mfma_f32_16x16x32_bf16 v[26:29], v[156:159], v[196:199], v[26:29]
	v_mfma_f32_16x16x32_bf16 v[14:17], v[148:151], v[204:207], v[14:17]
	v_mfma_f32_16x16x32_bf16 v[10:13], v[156:159], v[204:207], v[10:13]
	s_setprio 0
	s_setprio 1
	v_mfma_f32_16x16x32_bf16 v[54:57], v[160:163], v[176:179], v[54:57]
	v_mfma_f32_16x16x32_bf16 v[50:53], v[168:171], v[176:179], v[50:53]
	v_mfma_f32_16x16x32_bf16 v[38:41], v[160:163], v[184:187], v[38:41]
	v_mfma_f32_16x16x32_bf16 v[34:37], v[168:171], v[184:187], v[34:37]
	v_mfma_f32_16x16x32_bf16 v[22:25], v[160:163], v[192:195], v[22:25]
	v_mfma_f32_16x16x32_bf16 v[18:21], v[168:171], v[192:195], v[18:21]
	v_mfma_f32_16x16x32_bf16 v[6:9], v[160:163], v[200:203], v[6:9]
	v_mfma_f32_16x16x32_bf16 v[2:5], v[168:171], v[200:203], v[2:5]
	v_mfma_f32_16x16x32_bf16 v[54:57], v[164:167], v[180:183], v[54:57]
	v_mfma_f32_16x16x32_bf16 v[50:53], v[172:175], v[180:183], v[50:53]
	v_mfma_f32_16x16x32_bf16 v[38:41], v[164:167], v[188:191], v[38:41]
	v_mfma_f32_16x16x32_bf16 v[34:37], v[172:175], v[188:191], v[34:37]
	v_mfma_f32_16x16x32_bf16 v[22:25], v[164:167], v[196:199], v[22:25]
	v_mfma_f32_16x16x32_bf16 v[18:21], v[172:175], v[196:199], v[18:21]
	v_mfma_f32_16x16x32_bf16 v[6:9], v[164:167], v[204:207], v[6:9]
	v_mfma_f32_16x16x32_bf16 v[2:5], v[172:175], v[204:207], v[2:5]
	s_setprio 0
	s_add_i32 s56, s56, 2
	s_cmp_gt_u32 s56, 61
	s_mov_b64 s[28:29], s[30:31]
	s_barrier
	s_cbranch_scc0 .LBB0_806
	s_and_b64 vcc, exec, s[18:19]
	s_cbranch_vccz .LBB0_809
	s_barrier

.LBB0_910:
	ds_read_b128 v[130:133], v157
	ds_read_b128 v[134:137], v157 offset:1024
	ds_read_b128 v[164:167], v157 offset:2048
	ds_read_b128 v[168:171], v157 offset:3072
	ds_read_b128 v[172:175], v159
	ds_read_b128 v[176:179], v159 offset:1024
	ds_read_b128 v[180:183], v159 offset:2048
	ds_read_b128 v[184:187], v159 offset:3072
	s_add_u32 s30, s6, 0xfff80080
	s_addc_u32 s31, s7, -1
	s_cmp_eq_u32 s58, 28
	s_cselect_b32 s35, s13, s31
	s_cselect_b32 s34, s12, s30
	s_cselect_b32 s31, s1, s57
	s_cselect_b32 s30, s55, s56
	s_mov_b32 m0, s49
	v_lshl_add_u64 v[154:155], s[6:7], 0, v[146:147]
	ds_read_b128 v[188:191], v161
	ds_read_b128 v[192:195], v161 offset:1024
	ds_read_b128 v[196:199], v161 offset:2048
	ds_read_b128 v[200:203], v161 offset:3072
	ds_read_b128 v[204:207], v161 offset:4096
	ds_read_b128 v[208:211], v161 offset:5120
	ds_read_b128 v[212:215], v161 offset:6144
	ds_read_b128 v[216:219], v161 offset:7168
	global_load_lds_dwordx4 v[154:155], off
	v_lshl_add_u64 v[154:155], s[6:7], 0, v[148:149]
	s_mov_b32 m0, s50
	s_nop 0
	global_load_lds_dwordx4 v[154:155], off
	s_waitcnt vmcnt(8)
	s_waitcnt lgkmcnt(0)
	s_barrier
	s_setprio 1
	s_waitcnt lgkmcnt(0)
	v_mfma_f32_16x16x32_bf16 v[126:129], v[130:133], v[188:191], v[126:129]
	v_mfma_f32_16x16x32_bf16 v[122:125], v[164:167], v[188:191], v[122:125]
	v_mfma_f32_16x16x32_bf16 v[118:121], v[130:133], v[196:199], v[118:121]
	v_mfma_f32_16x16x32_bf16 v[110:113], v[164:167], v[196:199], v[110:113]
	v_mfma_f32_16x16x32_bf16 v[102:105], v[130:133], v[204:207], v[102:105]
	v_mfma_f32_16x16x32_bf16 v[94:97], v[164:167], v[204:207], v[94:97]
	v_mfma_f32_16x16x32_bf16 v[86:89], v[130:133], v[212:215], v[86:89]
	v_mfma_f32_16x16x32_bf16 v[78:81], v[164:167], v[212:215], v[78:81]
	v_mfma_f32_16x16x32_bf16 v[126:129], v[134:137], v[192:195], v[126:129]
	v_mfma_f32_16x16x32_bf16 v[122:125], v[168:171], v[192:195], v[122:125]
	v_mfma_f32_16x16x32_bf16 v[118:121], v[134:137], v[200:203], v[118:121]
	v_mfma_f32_16x16x32_bf16 v[110:113], v[168:171], v[200:203], v[110:113]
	v_mfma_f32_16x16x32_bf16 v[102:105], v[134:137], v[208:211], v[102:105]
	v_mfma_f32_16x16x32_bf16 v[94:97], v[168:171], v[208:211], v[94:97]
	v_mfma_f32_16x16x32_bf16 v[86:89], v[134:137], v[216:219], v[86:89]
	v_mfma_f32_16x16x32_bf16 v[78:81], v[168:171], v[216:219], v[78:81]
	s_setprio 0
	s_setprio 1
	v_mfma_f32_16x16x32_bf16 v[114:117], v[172:175], v[188:191], v[114:117]
	v_mfma_f32_16x16x32_bf16 v[106:109], v[180:183], v[188:191], v[106:109]
	v_mfma_f32_16x16x32_bf16 v[98:101], v[172:175], v[196:199], v[98:101]
	v_mfma_f32_16x16x32_bf16 v[90:93], v[180:183], v[196:199], v[90:93]
	v_mfma_f32_16x16x32_bf16 v[82:85], v[172:175], v[204:207], v[82:85]
	v_mfma_f32_16x16x32_bf16 v[74:77], v[180:183], v[204:207], v[74:77]
	v_mfma_f32_16x16x32_bf16 v[70:73], v[172:175], v[212:215], v[70:73]
	v_mfma_f32_16x16x32_bf16 v[66:69], v[180:183], v[212:215], v[66:69]
	v_mfma_f32_16x16x32_bf16 v[114:117], v[176:179], v[192:195], v[114:117]
	v_mfma_f32_16x16x32_bf16 v[106:109], v[184:187], v[192:195], v[106:109]
	v_mfma_f32_16x16x32_bf16 v[98:101], v[176:179], v[200:203], v[98:101]
	v_mfma_f32_16x16x32_bf16 v[90:93], v[184:187], v[200:203], v[90:93]
	v_mfma_f32_16x16x32_bf16 v[82:85], v[176:179], v[208:211], v[82:85]
	v_mfma_f32_16x16x32_bf16 v[74:77], v[184:187], v[208:211], v[74:77]
	v_mfma_f32_16x16x32_bf16 v[70:73], v[176:179], v[216:219], v[70:73]
	v_mfma_f32_16x16x32_bf16 v[66:69], v[184:187], v[216:219], v[66:69]
	s_setprio 0
	s_barrier
	s_mov_b32 m0, s51
	v_lshl_add_u64 v[154:155], s[30:31], 0, v[142:143]
	ds_read_b128 v[188:191], v161 offset:16384
	ds_read_b128 v[192:195], v161 offset:17408
	ds_read_b128 v[196:199], v161 offset:18432
	ds_read_b128 v[200:203], v161 offset:19456
	ds_read_b128 v[204:207], v161 offset:20480
	ds_read_b128 v[208:211], v161 offset:21504
	ds_read_b128 v[212:215], v161 offset:22528
	ds_read_b128 v[216:219], v161 offset:23552
	global_load_lds_dwordx4 v[154:155], off
	s_add_i32 m0, s51, 0x2000
	s_add_u32 s60, s30, 0x80000
	v_lshl_add_u64 v[220:221], s[30:31], 0, v[138:139]
	s_addc_u32 s61, s31, 0
	s_add_i32 s59, s48, s36
	global_load_lds_dwordx4 v[220:221], off
	v_lshl_add_u64 v[222:223], s[60:61], 0, v[142:143]
	s_mov_b32 m0, s59
	v_lshl_add_u64 v[224:225], s[34:35], 0, v[140:141]
	global_load_lds_dwordx4 v[222:223], off
	v_lshl_add_u64 v[222:223], s[60:61], 0, v[138:139]
	s_add_i32 m0, s59, 0x2000
	s_nop 0
	global_load_lds_dwordx4 v[222:223], off
	v_lshl_add_u64 v[222:223], s[34:35], 0, v[144:145]
	s_mov_b32 m0, s37
	s_nop 0
	global_load_lds_dwordx4 v[222:223], off
	s_mov_b32 m0, s40
	s_nop 0
	global_load_lds_dwordx4 v[224:225], off
	s_waitcnt vmcnt(8)
	s_waitcnt lgkmcnt(0)
	s_barrier
	s_setprio 1
	s_waitcnt lgkmcnt(0)
	v_mfma_f32_16x16x32_bf16 v[62:65], v[130:133], v[188:191], v[62:65]
	v_mfma_f32_16x16x32_bf16 v[58:61], v[164:167], v[188:191], v[58:61]
	v_mfma_f32_16x16x32_bf16 v[54:57], v[130:133], v[196:199], v[54:57]
	v_mfma_f32_16x16x32_bf16 v[46:49], v[164:167], v[196:199], v[46:49]
	v_mfma_f32_16x16x32_bf16 v[38:41], v[130:133], v[204:207], v[38:41]
	v_mfma_f32_16x16x32_bf16 v[30:33], v[164:167], v[204:207], v[30:33]
	v_mfma_f32_16x16x32_bf16 v[22:25], v[130:133], v[212:215], v[22:25]
	v_mfma_f32_16x16x32_bf16 v[14:17], v[164:167], v[212:215], v[14:17]
	v_mfma_f32_16x16x32_bf16 v[62:65], v[134:137], v[192:195], v[62:65]
	v_mfma_f32_16x16x32_bf16 v[58:61], v[168:171], v[192:195], v[58:61]
	v_mfma_f32_16x16x32_bf16 v[54:57], v[134:137], v[200:203], v[54:57]
	v_mfma_f32_16x16x32_bf16 v[46:49], v[168:171], v[200:203], v[46:49]
	v_mfma_f32_16x16x32_bf16 v[38:41], v[134:137], v[208:211], v[38:41]
	v_mfma_f32_16x16x32_bf16 v[30:33], v[168:171], v[208:211], v[30:33]
	v_mfma_f32_16x16x32_bf16 v[22:25], v[134:137], v[216:219], v[22:25]
	v_mfma_f32_16x16x32_bf16 v[14:17], v[168:171], v[216:219], v[14:17]
	s_setprio 0
	s_setprio 1
	v_mfma_f32_16x16x32_bf16 v[50:53], v[172:175], v[188:191], v[50:53]
	v_mfma_f32_16x16x32_bf16 v[42:45], v[180:183], v[188:191], v[42:45]
	v_mfma_f32_16x16x32_bf16 v[34:37], v[172:175], v[196:199], v[34:37]
	v_mfma_f32_16x16x32_bf16 v[26:29], v[180:183], v[196:199], v[26:29]
	v_mfma_f32_16x16x32_bf16 v[18:21], v[172:175], v[204:207], v[18:21]
	v_mfma_f32_16x16x32_bf16 v[10:13], v[180:183], v[204:207], v[10:13]
	v_mfma_f32_16x16x32_bf16 v[6:9], v[172:175], v[212:215], v[6:9]
	v_mfma_f32_16x16x32_bf16 v[2:5], v[180:183], v[212:215], v[2:5]
	v_mfma_f32_16x16x32_bf16 v[50:53], v[176:179], v[192:195], v[50:53]
	v_mfma_f32_16x16x32_bf16 v[42:45], v[184:187], v[192:195], v[42:45]
	v_mfma_f32_16x16x32_bf16 v[34:37], v[176:179], v[200:203], v[34:37]
	v_mfma_f32_16x16x32_bf16 v[26:29], v[184:187], v[200:203], v[26:29]
	v_mfma_f32_16x16x32_bf16 v[18:21], v[176:179], v[208:211], v[18:21]
	v_mfma_f32_16x16x32_bf16 v[10:13], v[184:187], v[208:211], v[10:13]
	v_mfma_f32_16x16x32_bf16 v[6:9], v[176:179], v[216:219], v[6:9]
	v_mfma_f32_16x16x32_bf16 v[2:5], v[184:187], v[216:219], v[2:5]
	s_setprio 0
	s_barrier
	s_add_i32 s59, 0, 0x18000
	v_add_u32_e32 v150, s59, v153
	s_add_i32 s60, 0, 0x1c000
	ds_read_b128 v[130:133], v150
	ds_read_b128 v[134:137], v150 offset:1024
	ds_read_b128 v[164:167], v150 offset:2048
	ds_read_b128 v[168:171], v150 offset:3072
	v_add_u32_e32 v150, s60, v153
	ds_read_b128 v[172:175], v150
	ds_read_b128 v[176:179], v150 offset:1024
	ds_read_b128 v[180:183], v150 offset:2048
	ds_read_b128 v[184:187], v150 offset:3072
	s_add_u32 s34, s34, 0x80000
	s_addc_u32 s35, s35, 0
	s_mov_b32 m0, s41
	v_lshl_add_u64 v[226:227], s[34:35], 0, v[144:145]
	ds_read_b128 v[188:191], v161 offset:32768
	ds_read_b128 v[192:195], v161 offset:33792
	ds_read_b128 v[196:199], v161 offset:34816
	ds_read_b128 v[200:203], v161 offset:35840
	ds_read_b128 v[204:207], v161 offset:36864
	ds_read_b128 v[208:211], v161 offset:37888
	ds_read_b128 v[212:215], v161 offset:38912
	ds_read_b128 v[216:219], v161 offset:39936
	global_load_lds_dwordx4 v[226:227], off
	v_lshl_add_u64 v[226:227], s[34:35], 0, v[140:141]
	s_mov_b32 m0, s42
	s_nop 0
	global_load_lds_dwordx4 v[226:227], off
	s_waitcnt vmcnt(8)
	s_waitcnt lgkmcnt(0)
	s_barrier
	s_setprio 1
	s_waitcnt lgkmcnt(0)
	v_mfma_f32_16x16x32_bf16 v[126:129], v[130:133], v[188:191], v[126:129]
	v_mfma_f32_16x16x32_bf16 v[122:125], v[164:167], v[188:191], v[122:125]
	v_mfma_f32_16x16x32_bf16 v[118:121], v[130:133], v[196:199], v[118:121]
	v_mfma_f32_16x16x32_bf16 v[110:113], v[164:167], v[196:199], v[110:113]
	v_mfma_f32_16x16x32_bf16 v[102:105], v[130:133], v[204:207], v[102:105]
	v_mfma_f32_16x16x32_bf16 v[94:97], v[164:167], v[204:207], v[94:97]
	v_mfma_f32_16x16x32_bf16 v[86:89], v[130:133], v[212:215], v[86:89]
	v_mfma_f32_16x16x32_bf16 v[78:81], v[164:167], v[212:215], v[78:81]
	v_mfma_f32_16x16x32_bf16 v[126:129], v[134:137], v[192:195], v[126:129]
	v_mfma_f32_16x16x32_bf16 v[122:125], v[168:171], v[192:195], v[122:125]
	v_mfma_f32_16x16x32_bf16 v[118:121], v[134:137], v[200:203], v[118:121]
	v_mfma_f32_16x16x32_bf16 v[110:113], v[168:171], v[200:203], v[110:113]
	v_mfma_f32_16x16x32_bf16 v[102:105], v[134:137], v[208:211], v[102:105]
	v_mfma_f32_16x16x32_bf16 v[94:97], v[168:171], v[208:211], v[94:97]
	v_mfma_f32_16x16x32_bf16 v[86:89], v[134:137], v[216:219], v[86:89]
	v_mfma_f32_16x16x32_bf16 v[78:81], v[168:171], v[216:219], v[78:81]
	s_setprio 0
	s_setprio 1
	v_mfma_f32_16x16x32_bf16 v[114:117], v[172:175], v[188:191], v[114:117]
	v_mfma_f32_16x16x32_bf16 v[106:109], v[180:183], v[188:191], v[106:109]
	v_mfma_f32_16x16x32_bf16 v[98:101], v[172:175], v[196:199], v[98:101]
	v_mfma_f32_16x16x32_bf16 v[90:93], v[180:183], v[196:199], v[90:93]
	v_mfma_f32_16x16x32_bf16 v[82:85], v[172:175], v[204:207], v[82:85]
	v_mfma_f32_16x16x32_bf16 v[74:77], v[180:183], v[204:207], v[74:77]
	v_mfma_f32_16x16x32_bf16 v[70:73], v[172:175], v[212:215], v[70:73]
	v_mfma_f32_16x16x32_bf16 v[66:69], v[180:183], v[212:215], v[66:69]
	v_mfma_f32_16x16x32_bf16 v[114:117], v[176:179], v[192:195], v[114:117]
	v_mfma_f32_16x16x32_bf16 v[106:109], v[184:187], v[192:195], v[106:109]
	v_mfma_f32_16x16x32_bf16 v[98:101], v[176:179], v[200:203], v[98:101]
	v_mfma_f32_16x16x32_bf16 v[90:93], v[184:187], v[200:203], v[90:93]
	v_mfma_f32_16x16x32_bf16 v[82:85], v[176:179], v[208:211], v[82:85]
	v_mfma_f32_16x16x32_bf16 v[74:77], v[184:187], v[208:211], v[74:77]
	v_mfma_f32_16x16x32_bf16 v[70:73], v[176:179], v[216:219], v[70:73]
	v_mfma_f32_16x16x32_bf16 v[66:69], v[184:187], v[216:219], v[66:69]
	s_setprio 0
	s_barrier
	s_add_i32 s34, s59, s36
	v_lshl_add_u64 v[154:155], v[154:155], 0, s[16:17]
	s_mov_b32 m0, s34
	ds_read_b128 v[188:191], v161 offset:49152
	ds_read_b128 v[192:195], v161 offset:50176
	ds_read_b128 v[196:199], v161 offset:51200
	ds_read_b128 v[200:203], v161 offset:52224
	ds_read_b128 v[204:207], v161 offset:53248
	ds_read_b128 v[208:211], v161 offset:54272
	ds_read_b128 v[212:215], v161 offset:55296
	ds_read_b128 v[216:219], v161 offset:56320
	global_load_lds_dwordx4 v[154:155], off
	s_add_i32 m0, s34, 0x2000
	s_add_u32 s30, s30, 0x80080
	v_lshl_add_u64 v[154:155], v[220:221], 0, s[16:17]
	s_addc_u32 s31, s31, 0
	s_add_i32 s34, s60, s36
	global_load_lds_dwordx4 v[154:155], off
	v_lshl_add_u64 v[154:155], s[30:31], 0, v[142:143]
	s_mov_b32 m0, s34
	s_nop 0
	global_load_lds_dwordx4 v[154:155], off
	v_lshl_add_u64 v[154:155], s[30:31], 0, v[138:139]
	s_add_i32 m0, s34, 0x2000
	s_nop 0
	global_load_lds_dwordx4 v[154:155], off
	v_lshl_add_u64 v[154:155], v[222:223], 0, s[16:17]
	s_mov_b32 m0, s45
	s_nop 0
	global_load_lds_dwordx4 v[154:155], off
	v_lshl_add_u64 v[154:155], v[224:225], 0, s[16:17]
	s_mov_b32 m0, s46
	s_nop 0
	global_load_lds_dwordx4 v[154:155], off
	s_waitcnt vmcnt(8)
	s_waitcnt lgkmcnt(0)
	s_barrier
	s_setprio 1
	s_waitcnt lgkmcnt(0)
	v_mfma_f32_16x16x32_bf16 v[62:65], v[130:133], v[188:191], v[62:65]
	v_mfma_f32_16x16x32_bf16 v[58:61], v[164:167], v[188:191], v[58:61]
	v_mfma_f32_16x16x32_bf16 v[54:57], v[130:133], v[196:199], v[54:57]
	v_mfma_f32_16x16x32_bf16 v[46:49], v[164:167], v[196:199], v[46:49]
	v_mfma_f32_16x16x32_bf16 v[38:41], v[130:133], v[204:207], v[38:41]
	v_mfma_f32_16x16x32_bf16 v[30:33], v[164:167], v[204:207], v[30:33]
	v_mfma_f32_16x16x32_bf16 v[22:25], v[130:133], v[212:215], v[22:25]
	v_mfma_f32_16x16x32_bf16 v[14:17], v[164:167], v[212:215], v[14:17]
	v_mfma_f32_16x16x32_bf16 v[62:65], v[134:137], v[192:195], v[62:65]
	v_mfma_f32_16x16x32_bf16 v[58:61], v[168:171], v[192:195], v[58:61]
	v_mfma_f32_16x16x32_bf16 v[54:57], v[134:137], v[200:203], v[54:57]
	v_mfma_f32_16x16x32_bf16 v[46:49], v[168:171], v[200:203], v[46:49]
	v_mfma_f32_16x16x32_bf16 v[38:41], v[134:137], v[208:211], v[38:41]
	v_mfma_f32_16x16x32_bf16 v[30:33], v[168:171], v[208:211], v[30:33]
	v_mfma_f32_16x16x32_bf16 v[22:25], v[134:137], v[216:219], v[22:25]
	v_mfma_f32_16x16x32_bf16 v[14:17], v[168:171], v[216:219], v[14:17]
	s_setprio 0
	s_setprio 1
	v_mfma_f32_16x16x32_bf16 v[50:53], v[172:175], v[188:191], v[50:53]
	v_mfma_f32_16x16x32_bf16 v[42:45], v[180:183], v[188:191], v[42:45]
	v_mfma_f32_16x16x32_bf16 v[34:37], v[172:175], v[196:199], v[34:37]
	v_mfma_f32_16x16x32_bf16 v[26:29], v[180:183], v[196:199], v[26:29]
	v_mfma_f32_16x16x32_bf16 v[18:21], v[172:175], v[204:207], v[18:21]
	v_mfma_f32_16x16x32_bf16 v[10:13], v[180:183], v[204:207], v[10:13]
	v_mfma_f32_16x16x32_bf16 v[6:9], v[172:175], v[212:215], v[6:9]
	v_mfma_f32_16x16x32_bf16 v[2:5], v[180:183], v[212:215], v[2:5]
	v_mfma_f32_16x16x32_bf16 v[50:53], v[176:179], v[192:195], v[50:53]
	v_mfma_f32_16x16x32_bf16 v[42:45], v[184:187], v[192:195], v[42:45]
	v_mfma_f32_16x16x32_bf16 v[34:37], v[176:179], v[200:203], v[34:37]
	v_mfma_f32_16x16x32_bf16 v[26:29], v[184:187], v[200:203], v[26:29]
	v_mfma_f32_16x16x32_bf16 v[18:21], v[176:179], v[208:211], v[18:21]
	v_mfma_f32_16x16x32_bf16 v[10:13], v[184:187], v[208:211], v[10:13]
	v_mfma_f32_16x16x32_bf16 v[6:9], v[176:179], v[216:219], v[6:9]
	v_mfma_f32_16x16x32_bf16 v[2:5], v[184:187], v[216:219], v[2:5]
	s_setprio 0
	s_add_i32 s58, s58, 2
	s_add_u32 s6, s6, 0x100
	s_addc_u32 s7, s7, 0
	s_add_u32 s56, s56, 0x100
	s_addc_u32 s57, s57, 0
	s_cmp_gt_u32 s58, 29
	s_barrier
	s_cbranch_scc0 .LBB0_910
	s_and_b64 vcc, exec, s[18:19]
	s_cbranch_vccz .LBB0_913
	s_barrier

.LBB0_1112:
	ds_read_b128 v[138:141], v143
	ds_read_b128 v[150:153], v143 offset:1024
	ds_read_b128 v[154:157], v143 offset:2048
	ds_read_b128 v[158:161], v143 offset:3072
	ds_read_b128 v[162:165], v144
	ds_read_b128 v[166:169], v144 offset:1024
	ds_read_b128 v[170:173], v144 offset:2048
	ds_read_b128 v[174:177], v144 offset:3072
	s_add_u32 s22, s20, 0x100
	s_addc_u32 s23, s21, 0
	s_add_u32 s24, s0, s20
	s_addc_u32 s25, s1, s21
	s_cmpk_eq_i32 s6, 0x54
	s_cselect_b32 s26, 0, s22
	s_cselect_b32 s27, 0, s23
	s_cselect_b32 s24, s16, s24
	s_cselect_b32 s25, s17, s25
	s_add_u32 s26, s2, s26
	s_addc_u32 s27, s3, s27
	s_mov_b32 m0, s41
	v_lshl_add_u64 v[210:211], v[134:135], 0, s[20:21]
	ds_read_b128 v[178:181], v145
	ds_read_b128 v[182:185], v145 offset:1024
	ds_read_b128 v[186:189], v145 offset:2048
	ds_read_b128 v[190:193], v145 offset:3072
	ds_read_b128 v[194:197], v145 offset:4096
	ds_read_b128 v[198:201], v145 offset:5120
	ds_read_b128 v[202:205], v145 offset:6144
	ds_read_b128 v[206:209], v145 offset:7168
	global_load_lds_dwordx4 v[210:211], off
	v_lshl_add_u64 v[210:211], v[136:137], 0, s[20:21]
	s_mov_b32 m0, s42
	s_nop 0
	global_load_lds_dwordx4 v[210:211], off
	s_waitcnt vmcnt(8)
	s_waitcnt lgkmcnt(0)
	s_barrier
	s_setprio 1
	s_waitcnt lgkmcnt(0)
	v_mfma_f32_16x16x32_bf16 v[126:129], v[138:141], v[178:181], v[126:129]
	v_mfma_f32_16x16x32_bf16 v[122:125], v[154:157], v[178:181], v[122:125]
	v_mfma_f32_16x16x32_bf16 v[110:113], v[138:141], v[186:189], v[110:113]
	v_mfma_f32_16x16x32_bf16 v[106:109], v[154:157], v[186:189], v[106:109]
	v_mfma_f32_16x16x32_bf16 v[94:97], v[138:141], v[194:197], v[94:97]
	v_mfma_f32_16x16x32_bf16 v[90:93], v[154:157], v[194:197], v[90:93]
	v_mfma_f32_16x16x32_bf16 v[78:81], v[138:141], v[202:205], v[78:81]
	v_mfma_f32_16x16x32_bf16 v[74:77], v[154:157], v[202:205], v[74:77]
	v_mfma_f32_16x16x32_bf16 v[126:129], v[150:153], v[182:185], v[126:129]
	v_mfma_f32_16x16x32_bf16 v[122:125], v[158:161], v[182:185], v[122:125]
	v_mfma_f32_16x16x32_bf16 v[110:113], v[150:153], v[190:193], v[110:113]
	v_mfma_f32_16x16x32_bf16 v[106:109], v[158:161], v[190:193], v[106:109]
	v_mfma_f32_16x16x32_bf16 v[94:97], v[150:153], v[198:201], v[94:97]
	v_mfma_f32_16x16x32_bf16 v[90:93], v[158:161], v[198:201], v[90:93]
	v_mfma_f32_16x16x32_bf16 v[78:81], v[150:153], v[206:209], v[78:81]
	v_mfma_f32_16x16x32_bf16 v[74:77], v[158:161], v[206:209], v[74:77]
	s_setprio 0
	s_setprio 1
	v_mfma_f32_16x16x32_bf16 v[118:121], v[162:165], v[178:181], v[118:121]
	v_mfma_f32_16x16x32_bf16 v[114:117], v[170:173], v[178:181], v[114:117]
	v_mfma_f32_16x16x32_bf16 v[102:105], v[162:165], v[186:189], v[102:105]
	v_mfma_f32_16x16x32_bf16 v[98:101], v[170:173], v[186:189], v[98:101]
	v_mfma_f32_16x16x32_bf16 v[86:89], v[162:165], v[194:197], v[86:89]
	v_mfma_f32_16x16x32_bf16 v[82:85], v[170:173], v[194:197], v[82:85]
	v_mfma_f32_16x16x32_bf16 v[70:73], v[162:165], v[202:205], v[70:73]
	v_mfma_f32_16x16x32_bf16 v[66:69], v[170:173], v[202:205], v[66:69]
	v_mfma_f32_16x16x32_bf16 v[118:121], v[166:169], v[182:185], v[118:121]
	v_mfma_f32_16x16x32_bf16 v[114:117], v[174:177], v[182:185], v[114:117]
	v_mfma_f32_16x16x32_bf16 v[102:105], v[166:169], v[190:193], v[102:105]
	v_mfma_f32_16x16x32_bf16 v[98:101], v[174:177], v[190:193], v[98:101]
	v_mfma_f32_16x16x32_bf16 v[86:89], v[166:169], v[198:201], v[86:89]
	v_mfma_f32_16x16x32_bf16 v[82:85], v[174:177], v[198:201], v[82:85]
	v_mfma_f32_16x16x32_bf16 v[70:73], v[166:169], v[206:209], v[70:73]
	v_mfma_f32_16x16x32_bf16 v[66:69], v[174:177], v[206:209], v[66:69]
	s_setprio 0
	s_barrier
	s_mov_b32 m0, s43
	v_lshl_add_u64 v[210:211], s[24:25], 0, v[132:133]
	s_add_u32 s20, s24, 0x160000
	ds_read_b128 v[178:181], v145 offset:16384
	ds_read_b128 v[182:185], v145 offset:17408
	ds_read_b128 v[186:189], v145 offset:18432
	ds_read_b128 v[190:193], v145 offset:19456
	ds_read_b128 v[194:197], v145 offset:20480
	ds_read_b128 v[198:201], v145 offset:21504
	ds_read_b128 v[202:205], v145 offset:22528
	ds_read_b128 v[206:209], v145 offset:23552
	global_load_lds_dwordx4 v[210:211], off
	v_lshl_add_u64 v[212:213], s[24:25], 0, v[130:131]
	s_mov_b32 m0, s44
	s_addc_u32 s21, s25, 0
	global_load_lds_dwordx4 v[212:213], off
	v_lshl_add_u64 v[214:215], s[20:21], 0, v[132:133]
	s_mov_b32 m0, s45
	v_lshl_add_u64 v[216:217], s[26:27], 0, v[130:131]
	global_load_lds_dwordx4 v[214:215], off
	v_lshl_add_u64 v[214:215], s[20:21], 0, v[130:131]
	s_mov_b32 m0, s46
	s_nop 0
	global_load_lds_dwordx4 v[214:215], off
	v_lshl_add_u64 v[214:215], s[26:27], 0, v[132:133]
	s_mov_b32 m0, s30
	s_nop 0
	global_load_lds_dwordx4 v[214:215], off
	s_mov_b32 m0, s31
	s_nop 0
	global_load_lds_dwordx4 v[216:217], off
	s_waitcnt vmcnt(8)
	s_waitcnt lgkmcnt(0)
	s_barrier
	s_setprio 1
	s_waitcnt lgkmcnt(0)
	v_mfma_f32_16x16x32_bf16 v[62:65], v[138:141], v[178:181], v[62:65]
	v_mfma_f32_16x16x32_bf16 v[58:61], v[154:157], v[178:181], v[58:61]
	v_mfma_f32_16x16x32_bf16 v[46:49], v[138:141], v[186:189], v[46:49]
	v_mfma_f32_16x16x32_bf16 v[42:45], v[154:157], v[186:189], v[42:45]
	v_mfma_f32_16x16x32_bf16 v[30:33], v[138:141], v[194:197], v[30:33]
	v_mfma_f32_16x16x32_bf16 v[26:29], v[154:157], v[194:197], v[26:29]
	v_mfma_f32_16x16x32_bf16 v[14:17], v[138:141], v[202:205], v[14:17]
	v_mfma_f32_16x16x32_bf16 v[10:13], v[154:157], v[202:205], v[10:13]
	v_mfma_f32_16x16x32_bf16 v[62:65], v[150:153], v[182:185], v[62:65]
	v_mfma_f32_16x16x32_bf16 v[58:61], v[158:161], v[182:185], v[58:61]
	v_mfma_f32_16x16x32_bf16 v[46:49], v[150:153], v[190:193], v[46:49]
	v_mfma_f32_16x16x32_bf16 v[42:45], v[158:161], v[190:193], v[42:45]
	v_mfma_f32_16x16x32_bf16 v[30:33], v[150:153], v[198:201], v[30:33]
	v_mfma_f32_16x16x32_bf16 v[26:29], v[158:161], v[198:201], v[26:29]
	v_mfma_f32_16x16x32_bf16 v[14:17], v[150:153], v[206:209], v[14:17]
	v_mfma_f32_16x16x32_bf16 v[10:13], v[158:161], v[206:209], v[10:13]
	s_setprio 0
	s_setprio 1
	v_mfma_f32_16x16x32_bf16 v[54:57], v[162:165], v[178:181], v[54:57]
	v_mfma_f32_16x16x32_bf16 v[50:53], v[170:173], v[178:181], v[50:53]
	v_mfma_f32_16x16x32_bf16 v[38:41], v[162:165], v[186:189], v[38:41]
	v_mfma_f32_16x16x32_bf16 v[34:37], v[170:173], v[186:189], v[34:37]
	v_mfma_f32_16x16x32_bf16 v[22:25], v[162:165], v[194:197], v[22:25]
	v_mfma_f32_16x16x32_bf16 v[18:21], v[170:173], v[194:197], v[18:21]
	v_mfma_f32_16x16x32_bf16 v[6:9], v[162:165], v[202:205], v[6:9]
	v_mfma_f32_16x16x32_bf16 v[2:5], v[170:173], v[202:205], v[2:5]
	v_mfma_f32_16x16x32_bf16 v[54:57], v[166:169], v[182:185], v[54:57]
	v_mfma_f32_16x16x32_bf16 v[50:53], v[174:177], v[182:185], v[50:53]
	v_mfma_f32_16x16x32_bf16 v[38:41], v[166:169], v[190:193], v[38:41]
	v_mfma_f32_16x16x32_bf16 v[34:37], v[174:177], v[190:193], v[34:37]
	v_mfma_f32_16x16x32_bf16 v[22:25], v[166:169], v[198:201], v[22:25]
	v_mfma_f32_16x16x32_bf16 v[18:21], v[174:177], v[198:201], v[18:21]
	v_mfma_f32_16x16x32_bf16 v[6:9], v[166:169], v[206:209], v[6:9]
	v_mfma_f32_16x16x32_bf16 v[2:5], v[174:177], v[206:209], v[2:5]
	s_setprio 0
	s_barrier
	ds_read_b128 v[138:141], v147
	ds_read_b128 v[150:153], v147 offset:1024
	ds_read_b128 v[154:157], v147 offset:2048
	ds_read_b128 v[158:161], v147 offset:3072
	ds_read_b128 v[162:165], v148
	ds_read_b128 v[166:169], v148 offset:1024
	ds_read_b128 v[170:173], v148 offset:2048
	ds_read_b128 v[174:177], v148 offset:3072
	s_add_u32 s20, s26, 0x160000
	s_addc_u32 s21, s27, 0
	s_mov_b32 m0, s33
	v_lshl_add_u64 v[218:219], s[20:21], 0, v[132:133]
	ds_read_b128 v[178:181], v145 offset:32768
	ds_read_b128 v[182:185], v145 offset:33792
	ds_read_b128 v[186:189], v145 offset:34816
	ds_read_b128 v[190:193], v145 offset:35840
	ds_read_b128 v[194:197], v145 offset:36864
	ds_read_b128 v[198:201], v145 offset:37888
	ds_read_b128 v[202:205], v145 offset:38912
	ds_read_b128 v[206:209], v145 offset:39936
	global_load_lds_dwordx4 v[218:219], off
	v_lshl_add_u64 v[218:219], s[20:21], 0, v[130:131]
	s_mov_b32 m0, s34
	s_nop 0
	global_load_lds_dwordx4 v[218:219], off
	s_waitcnt vmcnt(8)
	s_waitcnt lgkmcnt(0)
	s_barrier
	s_setprio 1
	s_waitcnt lgkmcnt(0)
	v_mfma_f32_16x16x32_bf16 v[126:129], v[138:141], v[178:181], v[126:129]
	v_mfma_f32_16x16x32_bf16 v[122:125], v[154:157], v[178:181], v[122:125]
	v_mfma_f32_16x16x32_bf16 v[110:113], v[138:141], v[186:189], v[110:113]
	v_mfma_f32_16x16x32_bf16 v[106:109], v[154:157], v[186:189], v[106:109]
	v_mfma_f32_16x16x32_bf16 v[94:97], v[138:141], v[194:197], v[94:97]
	v_mfma_f32_16x16x32_bf16 v[90:93], v[154:157], v[194:197], v[90:93]
	v_mfma_f32_16x16x32_bf16 v[78:81], v[138:141], v[202:205], v[78:81]
	v_mfma_f32_16x16x32_bf16 v[74:77], v[154:157], v[202:205], v[74:77]
	v_mfma_f32_16x16x32_bf16 v[126:129], v[150:153], v[182:185], v[126:129]
	v_mfma_f32_16x16x32_bf16 v[122:125], v[158:161], v[182:185], v[122:125]
	v_mfma_f32_16x16x32_bf16 v[110:113], v[150:153], v[190:193], v[110:113]
	v_mfma_f32_16x16x32_bf16 v[106:109], v[158:161], v[190:193], v[106:109]
	v_mfma_f32_16x16x32_bf16 v[94:97], v[150:153], v[198:201], v[94:97]
	v_mfma_f32_16x16x32_bf16 v[90:93], v[158:161], v[198:201], v[90:93]
	v_mfma_f32_16x16x32_bf16 v[78:81], v[150:153], v[206:209], v[78:81]
	v_mfma_f32_16x16x32_bf16 v[74:77], v[158:161], v[206:209], v[74:77]
	s_setprio 0
	s_setprio 1
	v_mfma_f32_16x16x32_bf16 v[118:121], v[162:165], v[178:181], v[118:121]
	v_mfma_f32_16x16x32_bf16 v[114:117], v[170:173], v[178:181], v[114:117]
	v_mfma_f32_16x16x32_bf16 v[102:105], v[162:165], v[186:189], v[102:105]
	v_mfma_f32_16x16x32_bf16 v[98:101], v[170:173], v[186:189], v[98:101]
	v_mfma_f32_16x16x32_bf16 v[86:89], v[162:165], v[194:197], v[86:89]
	v_mfma_f32_16x16x32_bf16 v[82:85], v[170:173], v[194:197], v[82:85]
	v_mfma_f32_16x16x32_bf16 v[70:73], v[162:165], v[202:205], v[70:73]
	v_mfma_f32_16x16x32_bf16 v[66:69], v[170:173], v[202:205], v[66:69]
	v_mfma_f32_16x16x32_bf16 v[118:121], v[166:169], v[182:185], v[118:121]
	v_mfma_f32_16x16x32_bf16 v[114:117], v[174:177], v[182:185], v[114:117]
	v_mfma_f32_16x16x32_bf16 v[102:105], v[166:169], v[190:193], v[102:105]
	v_mfma_f32_16x16x32_bf16 v[98:101], v[174:177], v[190:193], v[98:101]
	v_mfma_f32_16x16x32_bf16 v[86:89], v[166:169], v[198:201], v[86:89]
	v_mfma_f32_16x16x32_bf16 v[82:85], v[174:177], v[198:201], v[82:85]
	v_mfma_f32_16x16x32_bf16 v[70:73], v[166:169], v[206:209], v[70:73]
	v_mfma_f32_16x16x32_bf16 v[66:69], v[174:177], v[206:209], v[66:69]
	s_setprio 0
	s_barrier
	s_mov_b32 m0, s47
	v_lshl_add_u64 v[210:211], v[210:211], 0, s[12:13]
	s_add_u32 s20, s24, 0x160080
	ds_read_b128 v[178:181], v145 offset:49152
	ds_read_b128 v[182:185], v145 offset:50176
	ds_read_b128 v[186:189], v145 offset:51200
	ds_read_b128 v[190:193], v145 offset:52224
	ds_read_b128 v[194:197], v145 offset:53248
	ds_read_b128 v[198:201], v145 offset:54272
	ds_read_b128 v[202:205], v145 offset:55296
	ds_read_b128 v[206:209], v145 offset:56320
	global_load_lds_dwordx4 v[210:211], off
	v_lshl_add_u64 v[210:211], v[212:213], 0, s[12:13]
	s_mov_b32 m0, s48
	s_addc_u32 s21, s25, 0
	global_load_lds_dwordx4 v[210:211], off
	v_lshl_add_u64 v[210:211], s[20:21], 0, v[132:133]
	s_mov_b32 m0, s49
	s_nop 0
	global_load_lds_dwordx4 v[210:211], off
	v_lshl_add_u64 v[210:211], s[20:21], 0, v[130:131]
	s_mov_b32 m0, s50
	s_nop 0
	global_load_lds_dwordx4 v[210:211], off
	v_lshl_add_u64 v[210:211], v[214:215], 0, s[12:13]
	s_mov_b32 m0, s37
	s_nop 0
	global_load_lds_dwordx4 v[210:211], off
	v_lshl_add_u64 v[210:211], v[216:217], 0, s[12:13]
	s_mov_b32 m0, s39
	s_nop 0
	global_load_lds_dwordx4 v[210:211], off
	s_waitcnt vmcnt(8)
	s_waitcnt lgkmcnt(0)
	s_barrier
	s_setprio 1
	s_waitcnt lgkmcnt(0)
	v_mfma_f32_16x16x32_bf16 v[62:65], v[138:141], v[178:181], v[62:65]
	v_mfma_f32_16x16x32_bf16 v[58:61], v[154:157], v[178:181], v[58:61]
	v_mfma_f32_16x16x32_bf16 v[46:49], v[138:141], v[186:189], v[46:49]
	v_mfma_f32_16x16x32_bf16 v[42:45], v[154:157], v[186:189], v[42:45]
	v_mfma_f32_16x16x32_bf16 v[30:33], v[138:141], v[194:197], v[30:33]
	v_mfma_f32_16x16x32_bf16 v[26:29], v[154:157], v[194:197], v[26:29]
	v_mfma_f32_16x16x32_bf16 v[14:17], v[138:141], v[202:205], v[14:17]
	v_mfma_f32_16x16x32_bf16 v[10:13], v[154:157], v[202:205], v[10:13]
	v_mfma_f32_16x16x32_bf16 v[62:65], v[150:153], v[182:185], v[62:65]
	v_mfma_f32_16x16x32_bf16 v[58:61], v[158:161], v[182:185], v[58:61]
	v_mfma_f32_16x16x32_bf16 v[46:49], v[150:153], v[190:193], v[46:49]
	v_mfma_f32_16x16x32_bf16 v[42:45], v[158:161], v[190:193], v[42:45]
	v_mfma_f32_16x16x32_bf16 v[30:33], v[150:153], v[198:201], v[30:33]
	v_mfma_f32_16x16x32_bf16 v[26:29], v[158:161], v[198:201], v[26:29]
	v_mfma_f32_16x16x32_bf16 v[14:17], v[150:153], v[206:209], v[14:17]
	v_mfma_f32_16x16x32_bf16 v[10:13], v[158:161], v[206:209], v[10:13]
	s_setprio 0
	s_setprio 1
	v_mfma_f32_16x16x32_bf16 v[54:57], v[162:165], v[178:181], v[54:57]
	v_mfma_f32_16x16x32_bf16 v[50:53], v[170:173], v[178:181], v[50:53]
	v_mfma_f32_16x16x32_bf16 v[38:41], v[162:165], v[186:189], v[38:41]
	v_mfma_f32_16x16x32_bf16 v[34:37], v[170:173], v[186:189], v[34:37]
	v_mfma_f32_16x16x32_bf16 v[22:25], v[162:165], v[194:197], v[22:25]
	v_mfma_f32_16x16x32_bf16 v[18:21], v[170:173], v[194:197], v[18:21]
	v_mfma_f32_16x16x32_bf16 v[6:9], v[162:165], v[202:205], v[6:9]
	v_mfma_f32_16x16x32_bf16 v[2:5], v[170:173], v[202:205], v[2:5]
	v_mfma_f32_16x16x32_bf16 v[54:57], v[166:169], v[182:185], v[54:57]
	v_mfma_f32_16x16x32_bf16 v[50:53], v[174:177], v[182:185], v[50:53]
	v_mfma_f32_16x16x32_bf16 v[38:41], v[166:169], v[190:193], v[38:41]
	v_mfma_f32_16x16x32_bf16 v[34:37], v[174:177], v[190:193], v[34:37]
	v_mfma_f32_16x16x32_bf16 v[22:25], v[166:169], v[198:201], v[22:25]
	v_mfma_f32_16x16x32_bf16 v[18:21], v[174:177], v[198:201], v[18:21]
	v_mfma_f32_16x16x32_bf16 v[6:9], v[166:169], v[206:209], v[6:9]
	v_mfma_f32_16x16x32_bf16 v[2:5], v[174:177], v[206:209], v[2:5]
	s_setprio 0
	s_add_i32 s6, s6, 2
	s_cmpk_gt_u32 s6, 0x55
	s_mov_b64 s[20:21], s[22:23]
	s_barrier
	s_cbranch_scc0 .LBB0_1112
	s_and_b64 vcc, exec, s[14:15]
	s_cbranch_vccz .LBB0_1115
	s_barrier

.LBB0_1199:
	ds_read_b128 v[130:133], v169
	ds_read_b128 v[134:137], v169 offset:1024
	ds_read_b128 v[150:153], v169 offset:2048
	ds_read_b128 v[154:157], v169 offset:3072
	ds_read_b128 v[158:161], v170
	ds_read_b128 v[162:165], v170 offset:1024
	ds_read_b128 v[174:177], v170 offset:2048
	ds_read_b128 v[178:181], v170 offset:3072
	s_add_u32 s6, s0, 0xfff80080
	s_addc_u32 s7, s1, -1
	s_cmp_eq_u32 s54, 28
	s_cselect_b32 s27, s11, s7
	s_cselect_b32 s26, s10, s6
	s_cselect_b32 s7, s29, s53
	s_cselect_b32 s6, s30, s31
	s_mov_b32 m0, s48
	v_lshl_add_u64 v[166:167], s[0:1], 0, v[144:145]
	ds_read_b128 v[182:185], v171
	ds_read_b128 v[186:189], v171 offset:1024
	ds_read_b128 v[190:193], v171 offset:2048
	ds_read_b128 v[194:197], v171 offset:3072
	ds_read_b128 v[198:201], v171 offset:4096
	ds_read_b128 v[202:205], v171 offset:5120
	ds_read_b128 v[206:209], v171 offset:6144
	ds_read_b128 v[210:213], v171 offset:7168
	global_load_lds_dwordx4 v[166:167], off
	v_lshl_add_u64 v[166:167], s[0:1], 0, v[146:147]
	s_mov_b32 m0, s49
	s_nop 0
	global_load_lds_dwordx4 v[166:167], off
	s_waitcnt vmcnt(8)
	s_waitcnt lgkmcnt(0)
	s_barrier
	s_setprio 1
	s_waitcnt lgkmcnt(0)
	v_mfma_f32_16x16x32_bf16 v[126:129], v[130:133], v[182:185], v[126:129]
	v_mfma_f32_16x16x32_bf16 v[122:125], v[150:153], v[182:185], v[122:125]
	v_mfma_f32_16x16x32_bf16 v[110:113], v[130:133], v[190:193], v[110:113]
	v_mfma_f32_16x16x32_bf16 v[106:109], v[150:153], v[190:193], v[106:109]
	v_mfma_f32_16x16x32_bf16 v[94:97], v[130:133], v[198:201], v[94:97]
	v_mfma_f32_16x16x32_bf16 v[90:93], v[150:153], v[198:201], v[90:93]
	v_mfma_f32_16x16x32_bf16 v[78:81], v[130:133], v[206:209], v[78:81]
	v_mfma_f32_16x16x32_bf16 v[74:77], v[150:153], v[206:209], v[74:77]
	v_mfma_f32_16x16x32_bf16 v[126:129], v[134:137], v[186:189], v[126:129]
	v_mfma_f32_16x16x32_bf16 v[122:125], v[154:157], v[186:189], v[122:125]
	v_mfma_f32_16x16x32_bf16 v[110:113], v[134:137], v[194:197], v[110:113]
	v_mfma_f32_16x16x32_bf16 v[106:109], v[154:157], v[194:197], v[106:109]
	v_mfma_f32_16x16x32_bf16 v[94:97], v[134:137], v[202:205], v[94:97]
	v_mfma_f32_16x16x32_bf16 v[90:93], v[154:157], v[202:205], v[90:93]
	v_mfma_f32_16x16x32_bf16 v[78:81], v[134:137], v[210:213], v[78:81]
	v_mfma_f32_16x16x32_bf16 v[74:77], v[154:157], v[210:213], v[74:77]
	s_setprio 0
	s_setprio 1
	v_mfma_f32_16x16x32_bf16 v[118:121], v[158:161], v[182:185], v[118:121]
	v_mfma_f32_16x16x32_bf16 v[114:117], v[174:177], v[182:185], v[114:117]
	v_mfma_f32_16x16x32_bf16 v[102:105], v[158:161], v[190:193], v[102:105]
	v_mfma_f32_16x16x32_bf16 v[98:101], v[174:177], v[190:193], v[98:101]
	v_mfma_f32_16x16x32_bf16 v[86:89], v[158:161], v[198:201], v[86:89]
	v_mfma_f32_16x16x32_bf16 v[82:85], v[174:177], v[198:201], v[82:85]
	v_mfma_f32_16x16x32_bf16 v[70:73], v[158:161], v[206:209], v[70:73]
	v_mfma_f32_16x16x32_bf16 v[66:69], v[174:177], v[206:209], v[66:69]
	v_mfma_f32_16x16x32_bf16 v[118:121], v[162:165], v[186:189], v[118:121]
	v_mfma_f32_16x16x32_bf16 v[114:117], v[178:181], v[186:189], v[114:117]
	v_mfma_f32_16x16x32_bf16 v[102:105], v[162:165], v[194:197], v[102:105]
	v_mfma_f32_16x16x32_bf16 v[98:101], v[178:181], v[194:197], v[98:101]
	v_mfma_f32_16x16x32_bf16 v[86:89], v[162:165], v[202:205], v[86:89]
	v_mfma_f32_16x16x32_bf16 v[82:85], v[178:181], v[202:205], v[82:85]
	v_mfma_f32_16x16x32_bf16 v[70:73], v[162:165], v[210:213], v[70:73]
	v_mfma_f32_16x16x32_bf16 v[66:69], v[178:181], v[210:213], v[66:69]
	s_setprio 0
	s_barrier
	s_add_i32 s55, s46, s34
	v_lshl_add_u64 v[166:167], s[6:7], 0, v[140:141]
	s_mov_b32 m0, s55
	ds_read_b128 v[182:185], v171 offset:16384
	ds_read_b128 v[186:189], v171 offset:17408
	ds_read_b128 v[190:193], v171 offset:18432
	ds_read_b128 v[194:197], v171 offset:19456
	ds_read_b128 v[198:201], v171 offset:20480
	ds_read_b128 v[202:205], v171 offset:21504
	ds_read_b128 v[206:209], v171 offset:22528
	ds_read_b128 v[210:213], v171 offset:23552
	global_load_lds_dwordx4 v[166:167], off
	s_add_i32 m0, s55, 0x2000
	s_add_u32 s56, s6, 0x80000
	v_lshl_add_u64 v[214:215], s[6:7], 0, v[138:139]
	s_addc_u32 s57, s7, 0
	s_add_i32 s55, s47, s34
	global_load_lds_dwordx4 v[214:215], off
	v_lshl_add_u64 v[216:217], s[56:57], 0, v[140:141]
	s_mov_b32 m0, s55
	v_lshl_add_u64 v[218:219], s[26:27], 0, v[138:139]
	global_load_lds_dwordx4 v[216:217], off
	v_lshl_add_u64 v[216:217], s[56:57], 0, v[138:139]
	s_add_i32 m0, s55, 0x2000
	s_nop 0
	global_load_lds_dwordx4 v[216:217], off
	v_lshl_add_u64 v[216:217], s[26:27], 0, v[140:141]
	s_mov_b32 m0, s35
	s_nop 0
	global_load_lds_dwordx4 v[216:217], off
	s_mov_b32 m0, s36
	s_nop 0
	global_load_lds_dwordx4 v[218:219], off
	s_waitcnt vmcnt(8)
	s_waitcnt lgkmcnt(0)
	s_barrier
	s_setprio 1
	s_waitcnt lgkmcnt(0)
	v_mfma_f32_16x16x32_bf16 v[62:65], v[130:133], v[182:185], v[62:65]
	v_mfma_f32_16x16x32_bf16 v[58:61], v[150:153], v[182:185], v[58:61]
	v_mfma_f32_16x16x32_bf16 v[46:49], v[130:133], v[190:193], v[46:49]
	v_mfma_f32_16x16x32_bf16 v[42:45], v[150:153], v[190:193], v[42:45]
	v_mfma_f32_16x16x32_bf16 v[30:33], v[130:133], v[198:201], v[30:33]
	v_mfma_f32_16x16x32_bf16 v[26:29], v[150:153], v[198:201], v[26:29]
	v_mfma_f32_16x16x32_bf16 v[14:17], v[130:133], v[206:209], v[14:17]
	v_mfma_f32_16x16x32_bf16 v[10:13], v[150:153], v[206:209], v[10:13]
	v_mfma_f32_16x16x32_bf16 v[62:65], v[134:137], v[186:189], v[62:65]
	v_mfma_f32_16x16x32_bf16 v[58:61], v[154:157], v[186:189], v[58:61]
	v_mfma_f32_16x16x32_bf16 v[46:49], v[134:137], v[194:197], v[46:49]
	v_mfma_f32_16x16x32_bf16 v[42:45], v[154:157], v[194:197], v[42:45]
	v_mfma_f32_16x16x32_bf16 v[30:33], v[134:137], v[202:205], v[30:33]
	v_mfma_f32_16x16x32_bf16 v[26:29], v[154:157], v[202:205], v[26:29]
	v_mfma_f32_16x16x32_bf16 v[14:17], v[134:137], v[210:213], v[14:17]
	v_mfma_f32_16x16x32_bf16 v[10:13], v[154:157], v[210:213], v[10:13]
	s_setprio 0
	s_setprio 1
	v_mfma_f32_16x16x32_bf16 v[54:57], v[158:161], v[182:185], v[54:57]
	v_mfma_f32_16x16x32_bf16 v[50:53], v[174:177], v[182:185], v[50:53]
	v_mfma_f32_16x16x32_bf16 v[38:41], v[158:161], v[190:193], v[38:41]
	v_mfma_f32_16x16x32_bf16 v[34:37], v[174:177], v[190:193], v[34:37]
	v_mfma_f32_16x16x32_bf16 v[22:25], v[158:161], v[198:201], v[22:25]
	v_mfma_f32_16x16x32_bf16 v[18:21], v[174:177], v[198:201], v[18:21]
	v_mfma_f32_16x16x32_bf16 v[6:9], v[158:161], v[206:209], v[6:9]
	v_mfma_f32_16x16x32_bf16 v[2:5], v[174:177], v[206:209], v[2:5]
	v_mfma_f32_16x16x32_bf16 v[54:57], v[162:165], v[186:189], v[54:57]
	v_mfma_f32_16x16x32_bf16 v[50:53], v[178:181], v[186:189], v[50:53]
	v_mfma_f32_16x16x32_bf16 v[38:41], v[162:165], v[194:197], v[38:41]
	v_mfma_f32_16x16x32_bf16 v[34:37], v[178:181], v[194:197], v[34:37]
	v_mfma_f32_16x16x32_bf16 v[22:25], v[162:165], v[202:205], v[22:25]
	v_mfma_f32_16x16x32_bf16 v[18:21], v[178:181], v[202:205], v[18:21]
	v_mfma_f32_16x16x32_bf16 v[6:9], v[162:165], v[210:213], v[6:9]
	v_mfma_f32_16x16x32_bf16 v[2:5], v[178:181], v[210:213], v[2:5]
	s_setprio 0
	s_barrier
	s_add_i32 s55, 0, 0x18000
	v_add_u32_e32 v142, s55, v168
	s_add_i32 s56, 0, 0x1c000
	ds_read_b128 v[130:133], v142
	ds_read_b128 v[134:137], v142 offset:1024
	ds_read_b128 v[150:153], v142 offset:2048
	ds_read_b128 v[154:157], v142 offset:3072
	v_add_u32_e32 v142, s56, v168
	ds_read_b128 v[158:161], v142
	ds_read_b128 v[162:165], v142 offset:1024
	ds_read_b128 v[174:177], v142 offset:2048
	ds_read_b128 v[178:181], v142 offset:3072
	s_add_u32 s26, s26, 0x80000
	s_addc_u32 s27, s27, 0
	s_mov_b32 m0, s37
	v_lshl_add_u64 v[220:221], s[26:27], 0, v[140:141]
	ds_read_b128 v[182:185], v171 offset:32768
	ds_read_b128 v[186:189], v171 offset:33792
	ds_read_b128 v[190:193], v171 offset:34816
	ds_read_b128 v[194:197], v171 offset:35840
	ds_read_b128 v[198:201], v171 offset:36864
	ds_read_b128 v[202:205], v171 offset:37888
	ds_read_b128 v[206:209], v171 offset:38912
	ds_read_b128 v[210:213], v171 offset:39936
	global_load_lds_dwordx4 v[220:221], off
	v_lshl_add_u64 v[220:221], s[26:27], 0, v[138:139]
	s_mov_b32 m0, s39
	s_nop 0
	global_load_lds_dwordx4 v[220:221], off
	s_waitcnt vmcnt(8)
	s_waitcnt lgkmcnt(0)
	s_barrier
	s_setprio 1
	s_waitcnt lgkmcnt(0)
	v_mfma_f32_16x16x32_bf16 v[126:129], v[130:133], v[182:185], v[126:129]
	v_mfma_f32_16x16x32_bf16 v[122:125], v[150:153], v[182:185], v[122:125]
	v_mfma_f32_16x16x32_bf16 v[110:113], v[130:133], v[190:193], v[110:113]
	v_mfma_f32_16x16x32_bf16 v[106:109], v[150:153], v[190:193], v[106:109]
	v_mfma_f32_16x16x32_bf16 v[94:97], v[130:133], v[198:201], v[94:97]
	v_mfma_f32_16x16x32_bf16 v[90:93], v[150:153], v[198:201], v[90:93]
	v_mfma_f32_16x16x32_bf16 v[78:81], v[130:133], v[206:209], v[78:81]
	v_mfma_f32_16x16x32_bf16 v[74:77], v[150:153], v[206:209], v[74:77]
	v_mfma_f32_16x16x32_bf16 v[126:129], v[134:137], v[186:189], v[126:129]
	v_mfma_f32_16x16x32_bf16 v[122:125], v[154:157], v[186:189], v[122:125]
	v_mfma_f32_16x16x32_bf16 v[110:113], v[134:137], v[194:197], v[110:113]
	v_mfma_f32_16x16x32_bf16 v[106:109], v[154:157], v[194:197], v[106:109]
	v_mfma_f32_16x16x32_bf16 v[94:97], v[134:137], v[202:205], v[94:97]
	v_mfma_f32_16x16x32_bf16 v[90:93], v[154:157], v[202:205], v[90:93]
	v_mfma_f32_16x16x32_bf16 v[78:81], v[134:137], v[210:213], v[78:81]
	v_mfma_f32_16x16x32_bf16 v[74:77], v[154:157], v[210:213], v[74:77]
	s_setprio 0
	s_setprio 1
	v_mfma_f32_16x16x32_bf16 v[118:121], v[158:161], v[182:185], v[118:121]
	v_mfma_f32_16x16x32_bf16 v[114:117], v[174:177], v[182:185], v[114:117]
	v_mfma_f32_16x16x32_bf16 v[102:105], v[158:161], v[190:193], v[102:105]
	v_mfma_f32_16x16x32_bf16 v[98:101], v[174:177], v[190:193], v[98:101]
	v_mfma_f32_16x16x32_bf16 v[86:89], v[158:161], v[198:201], v[86:89]
	v_mfma_f32_16x16x32_bf16 v[82:85], v[174:177], v[198:201], v[82:85]
	v_mfma_f32_16x16x32_bf16 v[70:73], v[158:161], v[206:209], v[70:73]
	v_mfma_f32_16x16x32_bf16 v[66:69], v[174:177], v[206:209], v[66:69]
	v_mfma_f32_16x16x32_bf16 v[118:121], v[162:165], v[186:189], v[118:121]
	v_mfma_f32_16x16x32_bf16 v[114:117], v[178:181], v[186:189], v[114:117]
	v_mfma_f32_16x16x32_bf16 v[102:105], v[162:165], v[194:197], v[102:105]
	v_mfma_f32_16x16x32_bf16 v[98:101], v[178:181], v[194:197], v[98:101]
	v_mfma_f32_16x16x32_bf16 v[86:89], v[162:165], v[202:205], v[86:89]
	v_mfma_f32_16x16x32_bf16 v[82:85], v[178:181], v[202:205], v[82:85]
	v_mfma_f32_16x16x32_bf16 v[70:73], v[162:165], v[210:213], v[70:73]
	v_mfma_f32_16x16x32_bf16 v[66:69], v[178:181], v[210:213], v[66:69]
	s_setprio 0
	s_barrier
	s_add_i32 s26, s55, s34
	v_lshl_add_u64 v[166:167], v[166:167], 0, s[14:15]
	s_mov_b32 m0, s26
	ds_read_b128 v[182:185], v171 offset:49152
	ds_read_b128 v[186:189], v171 offset:50176
	ds_read_b128 v[190:193], v171 offset:51200
	ds_read_b128 v[194:197], v171 offset:52224
	ds_read_b128 v[198:201], v171 offset:53248
	ds_read_b128 v[202:205], v171 offset:54272
	ds_read_b128 v[206:209], v171 offset:55296
	ds_read_b128 v[210:213], v171 offset:56320
	global_load_lds_dwordx4 v[166:167], off
	s_add_i32 m0, s26, 0x2000
	s_add_u32 s6, s6, 0x80080
	v_lshl_add_u64 v[166:167], v[214:215], 0, s[14:15]
	s_addc_u32 s7, s7, 0
	s_add_i32 s26, s56, s34
	global_load_lds_dwordx4 v[166:167], off
	v_lshl_add_u64 v[166:167], s[6:7], 0, v[140:141]
	s_mov_b32 m0, s26
	s_nop 0
	global_load_lds_dwordx4 v[166:167], off
	v_lshl_add_u64 v[166:167], s[6:7], 0, v[138:139]
	s_add_i32 m0, s26, 0x2000
	s_nop 0
	global_load_lds_dwordx4 v[166:167], off
	v_lshl_add_u64 v[166:167], v[216:217], 0, s[14:15]
	s_mov_b32 m0, s43
	s_nop 0
	global_load_lds_dwordx4 v[166:167], off
	v_lshl_add_u64 v[166:167], v[218:219], 0, s[14:15]
	s_mov_b32 m0, s44
	s_nop 0
	global_load_lds_dwordx4 v[166:167], off
	s_waitcnt vmcnt(8)
	s_waitcnt lgkmcnt(0)
	s_barrier
	s_setprio 1
	s_waitcnt lgkmcnt(0)
	v_mfma_f32_16x16x32_bf16 v[62:65], v[130:133], v[182:185], v[62:65]
	v_mfma_f32_16x16x32_bf16 v[58:61], v[150:153], v[182:185], v[58:61]
	v_mfma_f32_16x16x32_bf16 v[46:49], v[130:133], v[190:193], v[46:49]
	v_mfma_f32_16x16x32_bf16 v[42:45], v[150:153], v[190:193], v[42:45]
	v_mfma_f32_16x16x32_bf16 v[30:33], v[130:133], v[198:201], v[30:33]
	v_mfma_f32_16x16x32_bf16 v[26:29], v[150:153], v[198:201], v[26:29]
	v_mfma_f32_16x16x32_bf16 v[14:17], v[130:133], v[206:209], v[14:17]
	v_mfma_f32_16x16x32_bf16 v[10:13], v[150:153], v[206:209], v[10:13]
	v_mfma_f32_16x16x32_bf16 v[62:65], v[134:137], v[186:189], v[62:65]
	v_mfma_f32_16x16x32_bf16 v[58:61], v[154:157], v[186:189], v[58:61]
	v_mfma_f32_16x16x32_bf16 v[46:49], v[134:137], v[194:197], v[46:49]
	v_mfma_f32_16x16x32_bf16 v[42:45], v[154:157], v[194:197], v[42:45]
	v_mfma_f32_16x16x32_bf16 v[30:33], v[134:137], v[202:205], v[30:33]
	v_mfma_f32_16x16x32_bf16 v[26:29], v[154:157], v[202:205], v[26:29]
	v_mfma_f32_16x16x32_bf16 v[14:17], v[134:137], v[210:213], v[14:17]
	v_mfma_f32_16x16x32_bf16 v[10:13], v[154:157], v[210:213], v[10:13]
	s_setprio 0
	s_setprio 1
	v_mfma_f32_16x16x32_bf16 v[54:57], v[158:161], v[182:185], v[54:57]
	v_mfma_f32_16x16x32_bf16 v[50:53], v[174:177], v[182:185], v[50:53]
	v_mfma_f32_16x16x32_bf16 v[38:41], v[158:161], v[190:193], v[38:41]
	v_mfma_f32_16x16x32_bf16 v[34:37], v[174:177], v[190:193], v[34:37]
	v_mfma_f32_16x16x32_bf16 v[22:25], v[158:161], v[198:201], v[22:25]
	v_mfma_f32_16x16x32_bf16 v[18:21], v[174:177], v[198:201], v[18:21]
	v_mfma_f32_16x16x32_bf16 v[6:9], v[158:161], v[206:209], v[6:9]
	v_mfma_f32_16x16x32_bf16 v[2:5], v[174:177], v[206:209], v[2:5]
	v_mfma_f32_16x16x32_bf16 v[54:57], v[162:165], v[186:189], v[54:57]
	v_mfma_f32_16x16x32_bf16 v[50:53], v[178:181], v[186:189], v[50:53]
	v_mfma_f32_16x16x32_bf16 v[38:41], v[162:165], v[194:197], v[38:41]
	v_mfma_f32_16x16x32_bf16 v[34:37], v[178:181], v[194:197], v[34:37]
	v_mfma_f32_16x16x32_bf16 v[22:25], v[162:165], v[202:205], v[22:25]
	v_mfma_f32_16x16x32_bf16 v[18:21], v[178:181], v[202:205], v[18:21]
	v_mfma_f32_16x16x32_bf16 v[6:9], v[162:165], v[210:213], v[6:9]
	v_mfma_f32_16x16x32_bf16 v[2:5], v[178:181], v[210:213], v[2:5]
	s_setprio 0
	s_add_i32 s54, s54, 2
	s_add_u32 s0, s0, 0x100
	s_addc_u32 s1, s1, 0
	s_add_u32 s31, s31, 0x100
	s_addc_u32 s53, s53, 0
	s_cmp_gt_u32 s54, 29
	s_barrier
	s_cbranch_scc0 .LBB0_1199
	s_and_b64 vcc, exec, s[16:17]
	s_cbranch_vccz .LBB0_1202
	s_barrier

.LBB0_1855:
	ds_read_b128 v[142:145], v148
	ds_read_b128 v[152:155], v148 offset:1024
	ds_read_b128 v[156:159], v148 offset:2048
	ds_read_b128 v[160:163], v148 offset:3072
	ds_read_b128 v[164:167], v149
	ds_read_b128 v[168:171], v149 offset:1024
	ds_read_b128 v[172:175], v149 offset:2048
	ds_read_b128 v[176:179], v149 offset:3072
	s_add_u32 s26, s24, 0x100
	s_addc_u32 s27, s25, 0
	s_cmp_eq_u32 s55, 60
	s_cselect_b32 s31, s19, s27
	s_cselect_b32 s30, s51, s26
	s_cselect_b32 s29, s17, s54
	s_cselect_b32 s28, s52, s53
	v_lshl_add_u64 v[212:213], s[24:25], 0, v[134:135]
	s_add_i32 m0, s5, 0xc000
	ds_read_b128 v[180:183], v150
	ds_read_b128 v[184:187], v150 offset:1024
	ds_read_b128 v[188:191], v150 offset:2048
	ds_read_b128 v[192:195], v150 offset:3072
	ds_read_b128 v[196:199], v150 offset:4096
	ds_read_b128 v[200:203], v150 offset:5120
	ds_read_b128 v[204:207], v150 offset:6144
	ds_read_b128 v[208:211], v150 offset:7168
	global_load_lds_dwordx4 v[212:213], off
	v_lshl_add_u64 v[212:213], s[24:25], 0, v[136:137]
	s_add_i32 m0, s5, 0xe000
	s_nop 0
	global_load_lds_dwordx4 v[212:213], off
	s_waitcnt vmcnt(8)
	s_waitcnt lgkmcnt(0)
	s_barrier
	s_setprio 1
	s_waitcnt lgkmcnt(0)
	v_mfma_f32_16x16x32_bf16 v[126:129], v[142:145], v[180:183], v[126:129]
	v_mfma_f32_16x16x32_bf16 v[122:125], v[156:159], v[180:183], v[122:125]
	v_mfma_f32_16x16x32_bf16 v[110:113], v[142:145], v[188:191], v[110:113]
	v_mfma_f32_16x16x32_bf16 v[106:109], v[156:159], v[188:191], v[106:109]
	v_mfma_f32_16x16x32_bf16 v[94:97], v[142:145], v[196:199], v[94:97]
	v_mfma_f32_16x16x32_bf16 v[90:93], v[156:159], v[196:199], v[90:93]
	v_mfma_f32_16x16x32_bf16 v[78:81], v[142:145], v[204:207], v[78:81]
	v_mfma_f32_16x16x32_bf16 v[74:77], v[156:159], v[204:207], v[74:77]
	v_mfma_f32_16x16x32_bf16 v[126:129], v[152:155], v[184:187], v[126:129]
	v_mfma_f32_16x16x32_bf16 v[122:125], v[160:163], v[184:187], v[122:125]
	v_mfma_f32_16x16x32_bf16 v[110:113], v[152:155], v[192:195], v[110:113]
	v_mfma_f32_16x16x32_bf16 v[106:109], v[160:163], v[192:195], v[106:109]
	v_mfma_f32_16x16x32_bf16 v[94:97], v[152:155], v[200:203], v[94:97]
	v_mfma_f32_16x16x32_bf16 v[90:93], v[160:163], v[200:203], v[90:93]
	v_mfma_f32_16x16x32_bf16 v[78:81], v[152:155], v[208:211], v[78:81]
	v_mfma_f32_16x16x32_bf16 v[74:77], v[160:163], v[208:211], v[74:77]
	s_setprio 0
	s_setprio 1
	v_mfma_f32_16x16x32_bf16 v[118:121], v[164:167], v[180:183], v[118:121]
	v_mfma_f32_16x16x32_bf16 v[114:117], v[172:175], v[180:183], v[114:117]
	v_mfma_f32_16x16x32_bf16 v[102:105], v[164:167], v[188:191], v[102:105]
	v_mfma_f32_16x16x32_bf16 v[98:101], v[172:175], v[188:191], v[98:101]
	v_mfma_f32_16x16x32_bf16 v[86:89], v[164:167], v[196:199], v[86:89]
	v_mfma_f32_16x16x32_bf16 v[82:85], v[172:175], v[196:199], v[82:85]
	v_mfma_f32_16x16x32_bf16 v[70:73], v[164:167], v[204:207], v[70:73]
	v_mfma_f32_16x16x32_bf16 v[66:69], v[172:175], v[204:207], v[66:69]
	v_mfma_f32_16x16x32_bf16 v[118:121], v[168:171], v[184:187], v[118:121]
	v_mfma_f32_16x16x32_bf16 v[114:117], v[176:179], v[184:187], v[114:117]
	v_mfma_f32_16x16x32_bf16 v[102:105], v[168:171], v[192:195], v[102:105]
	v_mfma_f32_16x16x32_bf16 v[98:101], v[176:179], v[192:195], v[98:101]
	v_mfma_f32_16x16x32_bf16 v[86:89], v[168:171], v[200:203], v[86:89]
	v_mfma_f32_16x16x32_bf16 v[82:85], v[176:179], v[200:203], v[82:85]
	v_mfma_f32_16x16x32_bf16 v[70:73], v[168:171], v[208:211], v[70:73]
	v_mfma_f32_16x16x32_bf16 v[66:69], v[176:179], v[208:211], v[66:69]
	s_setprio 0
	s_barrier
	s_add_i32 s24, s48, s37
	v_lshl_add_u64 v[212:213], s[28:29], 0, v[130:131]
	s_mov_b32 m0, s24
	ds_read_b128 v[180:183], v150 offset:16384
	ds_read_b128 v[184:187], v150 offset:17408
	ds_read_b128 v[188:191], v150 offset:18432
	ds_read_b128 v[192:195], v150 offset:19456
	ds_read_b128 v[196:199], v150 offset:20480
	ds_read_b128 v[200:203], v150 offset:21504
	ds_read_b128 v[204:207], v150 offset:22528
	ds_read_b128 v[208:211], v150 offset:23552
	global_load_lds_dwordx4 v[212:213], off
	s_add_i32 m0, s24, 0x2000
	s_add_u32 s24, s28, 0x100000
	v_lshl_add_u64 v[214:215], s[28:29], 0, v[132:133]
	s_addc_u32 s25, s29, 0
	s_add_i32 s56, s49, s37
	global_load_lds_dwordx4 v[214:215], off
	v_lshl_add_u64 v[216:217], s[24:25], 0, v[130:131]
	s_mov_b32 m0, s56
	v_lshl_add_u64 v[218:219], s[30:31], 0, v[132:133]
	global_load_lds_dwordx4 v[216:217], off
	v_lshl_add_u64 v[216:217], s[24:25], 0, v[132:133]
	s_add_i32 m0, s56, 0x2000
	s_nop 0
	global_load_lds_dwordx4 v[216:217], off
	v_lshl_add_u64 v[216:217], s[30:31], 0, v[130:131]
	s_mov_b32 m0, s5
	s_nop 0
	global_load_lds_dwordx4 v[216:217], off
	s_mov_b32 m0, s38
	s_nop 0
	global_load_lds_dwordx4 v[218:219], off
	s_waitcnt vmcnt(8)
	s_waitcnt lgkmcnt(0)
	s_barrier
	s_setprio 1
	s_waitcnt lgkmcnt(0)
	v_mfma_f32_16x16x32_bf16 v[62:65], v[142:145], v[180:183], v[62:65]
	v_mfma_f32_16x16x32_bf16 v[58:61], v[156:159], v[180:183], v[58:61]
	v_mfma_f32_16x16x32_bf16 v[46:49], v[142:145], v[188:191], v[46:49]
	v_mfma_f32_16x16x32_bf16 v[42:45], v[156:159], v[188:191], v[42:45]
	v_mfma_f32_16x16x32_bf16 v[30:33], v[142:145], v[196:199], v[30:33]
	v_mfma_f32_16x16x32_bf16 v[26:29], v[156:159], v[196:199], v[26:29]
	v_mfma_f32_16x16x32_bf16 v[14:17], v[142:145], v[204:207], v[14:17]
	v_mfma_f32_16x16x32_bf16 v[10:13], v[156:159], v[204:207], v[10:13]
	v_mfma_f32_16x16x32_bf16 v[62:65], v[152:155], v[184:187], v[62:65]
	v_mfma_f32_16x16x32_bf16 v[58:61], v[160:163], v[184:187], v[58:61]
	v_mfma_f32_16x16x32_bf16 v[46:49], v[152:155], v[192:195], v[46:49]
	v_mfma_f32_16x16x32_bf16 v[42:45], v[160:163], v[192:195], v[42:45]
	v_mfma_f32_16x16x32_bf16 v[30:33], v[152:155], v[200:203], v[30:33]
	v_mfma_f32_16x16x32_bf16 v[26:29], v[160:163], v[200:203], v[26:29]
	v_mfma_f32_16x16x32_bf16 v[14:17], v[152:155], v[208:211], v[14:17]
	v_mfma_f32_16x16x32_bf16 v[10:13], v[160:163], v[208:211], v[10:13]
	s_setprio 0
	s_setprio 1
	v_mfma_f32_16x16x32_bf16 v[54:57], v[164:167], v[180:183], v[54:57]
	v_mfma_f32_16x16x32_bf16 v[50:53], v[172:175], v[180:183], v[50:53]
	v_mfma_f32_16x16x32_bf16 v[38:41], v[164:167], v[188:191], v[38:41]
	v_mfma_f32_16x16x32_bf16 v[34:37], v[172:175], v[188:191], v[34:37]
	v_mfma_f32_16x16x32_bf16 v[22:25], v[164:167], v[196:199], v[22:25]
	v_mfma_f32_16x16x32_bf16 v[18:21], v[172:175], v[196:199], v[18:21]
	v_mfma_f32_16x16x32_bf16 v[6:9], v[164:167], v[204:207], v[6:9]
	v_mfma_f32_16x16x32_bf16 v[2:5], v[172:175], v[204:207], v[2:5]
	v_mfma_f32_16x16x32_bf16 v[54:57], v[168:171], v[184:187], v[54:57]
	v_mfma_f32_16x16x32_bf16 v[50:53], v[176:179], v[184:187], v[50:53]
	v_mfma_f32_16x16x32_bf16 v[38:41], v[168:171], v[192:195], v[38:41]
	v_mfma_f32_16x16x32_bf16 v[34:37], v[176:179], v[192:195], v[34:37]
	v_mfma_f32_16x16x32_bf16 v[22:25], v[168:171], v[200:203], v[22:25]
	v_mfma_f32_16x16x32_bf16 v[18:21], v[176:179], v[200:203], v[18:21]
	v_mfma_f32_16x16x32_bf16 v[6:9], v[168:171], v[208:211], v[6:9]
	v_mfma_f32_16x16x32_bf16 v[2:5], v[176:179], v[208:211], v[2:5]
	s_setprio 0
	s_barrier
	s_add_i32 s56, 0, 0x18000
	s_add_i32 s57, 0, 0x1c000
	v_add_u32_e32 v160, s56, v147
	v_add_u32_e32 v176, s57, v147
	ds_read_b128 v[142:145], v160
	ds_read_b128 v[152:155], v160 offset:1024
	ds_read_b128 v[156:159], v160 offset:2048
	ds_read_b128 v[160:163], v160 offset:3072
	ds_read_b128 v[164:167], v176
	ds_read_b128 v[168:171], v176 offset:1024
	ds_read_b128 v[172:175], v176 offset:2048
	ds_read_b128 v[176:179], v176 offset:3072
	s_add_u32 s24, s30, 0x100000
	s_addc_u32 s25, s31, 0
	s_mov_b32 m0, s39
	v_lshl_add_u64 v[220:221], s[24:25], 0, v[130:131]
	ds_read_b128 v[180:183], v150 offset:32768
	ds_read_b128 v[184:187], v150 offset:33792
	ds_read_b128 v[188:191], v150 offset:34816
	ds_read_b128 v[192:195], v150 offset:35840
	ds_read_b128 v[196:199], v150 offset:36864
	ds_read_b128 v[200:203], v150 offset:37888
	ds_read_b128 v[204:207], v150 offset:38912
	ds_read_b128 v[208:211], v150 offset:39936
	global_load_lds_dwordx4 v[220:221], off
	v_lshl_add_u64 v[220:221], s[24:25], 0, v[132:133]
	s_mov_b32 m0, s40
	s_nop 0
	global_load_lds_dwordx4 v[220:221], off
	s_waitcnt vmcnt(8)
	s_waitcnt lgkmcnt(0)
	s_barrier
	s_setprio 1
	s_waitcnt lgkmcnt(0)
	v_mfma_f32_16x16x32_bf16 v[126:129], v[142:145], v[180:183], v[126:129]
	v_mfma_f32_16x16x32_bf16 v[122:125], v[156:159], v[180:183], v[122:125]
	v_mfma_f32_16x16x32_bf16 v[110:113], v[142:145], v[188:191], v[110:113]
	v_mfma_f32_16x16x32_bf16 v[106:109], v[156:159], v[188:191], v[106:109]
	v_mfma_f32_16x16x32_bf16 v[94:97], v[142:145], v[196:199], v[94:97]
	v_mfma_f32_16x16x32_bf16 v[90:93], v[156:159], v[196:199], v[90:93]
	v_mfma_f32_16x16x32_bf16 v[78:81], v[142:145], v[204:207], v[78:81]
	v_mfma_f32_16x16x32_bf16 v[74:77], v[156:159], v[204:207], v[74:77]
	v_mfma_f32_16x16x32_bf16 v[126:129], v[152:155], v[184:187], v[126:129]
	v_mfma_f32_16x16x32_bf16 v[122:125], v[160:163], v[184:187], v[122:125]
	v_mfma_f32_16x16x32_bf16 v[110:113], v[152:155], v[192:195], v[110:113]
	v_mfma_f32_16x16x32_bf16 v[106:109], v[160:163], v[192:195], v[106:109]
	v_mfma_f32_16x16x32_bf16 v[94:97], v[152:155], v[200:203], v[94:97]
	v_mfma_f32_16x16x32_bf16 v[90:93], v[160:163], v[200:203], v[90:93]
	v_mfma_f32_16x16x32_bf16 v[78:81], v[152:155], v[208:211], v[78:81]
	v_mfma_f32_16x16x32_bf16 v[74:77], v[160:163], v[208:211], v[74:77]
	s_setprio 0
	s_setprio 1
	v_mfma_f32_16x16x32_bf16 v[118:121], v[164:167], v[180:183], v[118:121]
	v_mfma_f32_16x16x32_bf16 v[114:117], v[172:175], v[180:183], v[114:117]
	v_mfma_f32_16x16x32_bf16 v[102:105], v[164:167], v[188:191], v[102:105]
	v_mfma_f32_16x16x32_bf16 v[98:101], v[172:175], v[188:191], v[98:101]
	v_mfma_f32_16x16x32_bf16 v[86:89], v[164:167], v[196:199], v[86:89]
	v_mfma_f32_16x16x32_bf16 v[82:85], v[172:175], v[196:199], v[82:85]
	v_mfma_f32_16x16x32_bf16 v[70:73], v[164:167], v[204:207], v[70:73]
	v_mfma_f32_16x16x32_bf16 v[66:69], v[172:175], v[204:207], v[66:69]
	v_mfma_f32_16x16x32_bf16 v[118:121], v[168:171], v[184:187], v[118:121]
	v_mfma_f32_16x16x32_bf16 v[114:117], v[176:179], v[184:187], v[114:117]
	v_mfma_f32_16x16x32_bf16 v[102:105], v[168:171], v[192:195], v[102:105]
	v_mfma_f32_16x16x32_bf16 v[98:101], v[176:179], v[192:195], v[98:101]
	v_mfma_f32_16x16x32_bf16 v[86:89], v[168:171], v[200:203], v[86:89]
	v_mfma_f32_16x16x32_bf16 v[82:85], v[176:179], v[200:203], v[82:85]
	v_mfma_f32_16x16x32_bf16 v[70:73], v[168:171], v[208:211], v[70:73]
	v_mfma_f32_16x16x32_bf16 v[66:69], v[176:179], v[208:211], v[66:69]
	s_setprio 0
	s_barrier
	s_add_i32 s24, s56, s37
	v_lshl_add_u64 v[212:213], v[212:213], 0, s[12:13]
	s_mov_b32 m0, s24
	ds_read_b128 v[180:183], v150 offset:49152
	ds_read_b128 v[184:187], v150 offset:50176
	ds_read_b128 v[188:191], v150 offset:51200
	ds_read_b128 v[192:195], v150 offset:52224
	ds_read_b128 v[196:199], v150 offset:53248
	ds_read_b128 v[200:203], v150 offset:54272
	ds_read_b128 v[204:207], v150 offset:55296
	ds_read_b128 v[208:211], v150 offset:56320
	global_load_lds_dwordx4 v[212:213], off
	s_add_i32 m0, s24, 0x2000
	s_add_u32 s24, s28, 0x100080
	v_lshl_add_u64 v[212:213], v[214:215], 0, s[12:13]
	s_addc_u32 s25, s29, 0
	s_add_i32 s28, s57, s37
	global_load_lds_dwordx4 v[212:213], off
	v_lshl_add_u64 v[212:213], s[24:25], 0, v[130:131]
	s_mov_b32 m0, s28
	s_nop 0
	global_load_lds_dwordx4 v[212:213], off
	v_lshl_add_u64 v[212:213], s[24:25], 0, v[132:133]
	s_add_i32 m0, s28, 0x2000
	s_nop 0
	global_load_lds_dwordx4 v[212:213], off
	v_lshl_add_u64 v[212:213], v[216:217], 0, s[12:13]
	s_mov_b32 m0, s44
	s_nop 0
	global_load_lds_dwordx4 v[212:213], off
	v_lshl_add_u64 v[212:213], v[218:219], 0, s[12:13]
	s_mov_b32 m0, s45
	s_nop 0
	global_load_lds_dwordx4 v[212:213], off
	s_waitcnt vmcnt(8)
	s_waitcnt lgkmcnt(0)
	s_barrier
	s_setprio 1
	s_waitcnt lgkmcnt(0)
	v_mfma_f32_16x16x32_bf16 v[62:65], v[142:145], v[180:183], v[62:65]
	v_mfma_f32_16x16x32_bf16 v[58:61], v[156:159], v[180:183], v[58:61]
	v_mfma_f32_16x16x32_bf16 v[46:49], v[142:145], v[188:191], v[46:49]
	v_mfma_f32_16x16x32_bf16 v[42:45], v[156:159], v[188:191], v[42:45]
	v_mfma_f32_16x16x32_bf16 v[30:33], v[142:145], v[196:199], v[30:33]
	v_mfma_f32_16x16x32_bf16 v[26:29], v[156:159], v[196:199], v[26:29]
	v_mfma_f32_16x16x32_bf16 v[14:17], v[142:145], v[204:207], v[14:17]
	v_mfma_f32_16x16x32_bf16 v[10:13], v[156:159], v[204:207], v[10:13]
	v_mfma_f32_16x16x32_bf16 v[62:65], v[152:155], v[184:187], v[62:65]
	v_mfma_f32_16x16x32_bf16 v[58:61], v[160:163], v[184:187], v[58:61]
	v_mfma_f32_16x16x32_bf16 v[46:49], v[152:155], v[192:195], v[46:49]
	v_mfma_f32_16x16x32_bf16 v[42:45], v[160:163], v[192:195], v[42:45]
	v_mfma_f32_16x16x32_bf16 v[30:33], v[152:155], v[200:203], v[30:33]
	v_mfma_f32_16x16x32_bf16 v[26:29], v[160:163], v[200:203], v[26:29]
	v_mfma_f32_16x16x32_bf16 v[14:17], v[152:155], v[208:211], v[14:17]
	v_mfma_f32_16x16x32_bf16 v[10:13], v[160:163], v[208:211], v[10:13]
	s_setprio 0
	s_setprio 1
	v_mfma_f32_16x16x32_bf16 v[54:57], v[164:167], v[180:183], v[54:57]
	v_mfma_f32_16x16x32_bf16 v[50:53], v[172:175], v[180:183], v[50:53]
	v_mfma_f32_16x16x32_bf16 v[38:41], v[164:167], v[188:191], v[38:41]
	v_mfma_f32_16x16x32_bf16 v[34:37], v[172:175], v[188:191], v[34:37]
	v_mfma_f32_16x16x32_bf16 v[22:25], v[164:167], v[196:199], v[22:25]
	v_mfma_f32_16x16x32_bf16 v[18:21], v[172:175], v[196:199], v[18:21]
	v_mfma_f32_16x16x32_bf16 v[6:9], v[164:167], v[204:207], v[6:9]
	v_mfma_f32_16x16x32_bf16 v[2:5], v[172:175], v[204:207], v[2:5]
	v_mfma_f32_16x16x32_bf16 v[54:57], v[168:171], v[184:187], v[54:57]
	v_mfma_f32_16x16x32_bf16 v[50:53], v[176:179], v[184:187], v[50:53]
	v_mfma_f32_16x16x32_bf16 v[38:41], v[168:171], v[192:195], v[38:41]
	v_mfma_f32_16x16x32_bf16 v[34:37], v[176:179], v[192:195], v[34:37]
	v_mfma_f32_16x16x32_bf16 v[22:25], v[168:171], v[200:203], v[22:25]
	v_mfma_f32_16x16x32_bf16 v[18:21], v[176:179], v[200:203], v[18:21]
	v_mfma_f32_16x16x32_bf16 v[6:9], v[168:171], v[208:211], v[6:9]
	v_mfma_f32_16x16x32_bf16 v[2:5], v[176:179], v[208:211], v[2:5]
	s_setprio 0
	s_add_i32 s55, s55, 2
	s_add_u32 s53, s53, 0x100
	s_addc_u32 s54, s54, 0
	s_cmp_gt_u32 s55, 61
	s_mov_b64 s[24:25], s[26:27]
	s_barrier
	s_cbranch_scc0 .LBB0_1855
	s_and_b64 vcc, exec, s[14:15]
	s_cbranch_vccz .LBB0_1858
	s_barrier

.LBB0_1942:
	s_waitcnt lgkmcnt(0)
	s_add_u32 s26, s8, 0xfff80080
	s_addc_u32 s27, s9, -1
	s_cmp_eq_u32 s53, 28
	s_cselect_b32 s29, s7, s27
	s_cselect_b32 s28, s21, s26
	s_cselect_b32 s27, s19, s52
	s_cselect_b32 s26, s50, s51
	v_lshl_add_u64 v[216:217], s[8:9], 0, v[190:191]
	s_add_i32 m0, s35, 0xc000
	s_nop 0
	global_load_lds_dwordx4 v[216:217], off
	v_lshl_add_u64 v[216:217], s[8:9], 0, v[192:193]
	s_add_i32 m0, s35, 0xe000
	s_nop 0
	global_load_lds_dwordx4 v[216:217], off
	ds_read_b128 v[130:133], v200
	ds_read_b128 v[134:137], v200 offset:1024
	ds_read_b128 v[138:141], v200 offset:2048
	ds_read_b128 v[142:145], v200 offset:3072
	ds_read_b128 v[146:149], v201
	ds_read_b128 v[150:153], v201 offset:1024
	ds_read_b128 v[154:157], v201 offset:2048
	ds_read_b128 v[158:161], v201 offset:3072
	ds_read_b128 v[162:165], v202
	ds_read_b128 v[166:169], v202 offset:1024
	ds_read_b128 v[170:173], v202 offset:2048
	ds_read_b128 v[174:177], v202 offset:3072
	ds_read_b128 v[178:181], v202 offset:4096
	ds_read_b128 v[204:207], v202 offset:5120
	ds_read_b128 v[208:211], v202 offset:6144
	ds_read_b128 v[212:215], v202 offset:7168
	s_waitcnt vmcnt(8)
	s_waitcnt lgkmcnt(0)
	s_barrier
	s_setprio 1
	s_waitcnt lgkmcnt(0)
	v_mfma_f32_16x16x32_bf16 v[126:129], v[130:133], v[162:165], v[126:129]
	v_mfma_f32_16x16x32_bf16 v[122:125], v[138:141], v[162:165], v[122:125]
	v_mfma_f32_16x16x32_bf16 v[118:121], v[130:133], v[170:173], v[118:121]
	v_mfma_f32_16x16x32_bf16 v[110:113], v[138:141], v[170:173], v[110:113]
	v_mfma_f32_16x16x32_bf16 v[102:105], v[130:133], v[178:181], v[102:105]
	v_mfma_f32_16x16x32_bf16 v[94:97], v[138:141], v[178:181], v[94:97]
	v_mfma_f32_16x16x32_bf16 v[86:89], v[130:133], v[208:211], v[86:89]
	v_mfma_f32_16x16x32_bf16 v[78:81], v[138:141], v[208:211], v[78:81]
	v_mfma_f32_16x16x32_bf16 v[126:129], v[134:137], v[166:169], v[126:129]
	v_mfma_f32_16x16x32_bf16 v[122:125], v[142:145], v[166:169], v[122:125]
	v_mfma_f32_16x16x32_bf16 v[118:121], v[134:137], v[174:177], v[118:121]
	v_mfma_f32_16x16x32_bf16 v[110:113], v[142:145], v[174:177], v[110:113]
	v_mfma_f32_16x16x32_bf16 v[102:105], v[134:137], v[204:207], v[102:105]
	v_mfma_f32_16x16x32_bf16 v[94:97], v[142:145], v[204:207], v[94:97]
	v_mfma_f32_16x16x32_bf16 v[86:89], v[134:137], v[212:215], v[86:89]
	v_mfma_f32_16x16x32_bf16 v[78:81], v[142:145], v[212:215], v[78:81]
	s_setprio 0
	s_setprio 1
	v_mfma_f32_16x16x32_bf16 v[114:117], v[146:149], v[162:165], v[114:117]
	v_mfma_f32_16x16x32_bf16 v[106:109], v[154:157], v[162:165], v[106:109]
	v_mfma_f32_16x16x32_bf16 v[98:101], v[146:149], v[170:173], v[98:101]
	v_mfma_f32_16x16x32_bf16 v[90:93], v[154:157], v[170:173], v[90:93]
	v_mfma_f32_16x16x32_bf16 v[82:85], v[146:149], v[178:181], v[82:85]
	v_mfma_f32_16x16x32_bf16 v[74:77], v[154:157], v[178:181], v[74:77]
	v_mfma_f32_16x16x32_bf16 v[70:73], v[146:149], v[208:211], v[70:73]
	v_mfma_f32_16x16x32_bf16 v[66:69], v[154:157], v[208:211], v[66:69]
	v_mfma_f32_16x16x32_bf16 v[114:117], v[150:153], v[166:169], v[114:117]
	v_mfma_f32_16x16x32_bf16 v[106:109], v[158:161], v[166:169], v[106:109]
	v_mfma_f32_16x16x32_bf16 v[98:101], v[150:153], v[174:177], v[98:101]
	v_mfma_f32_16x16x32_bf16 v[90:93], v[158:161], v[174:177], v[90:93]
	v_mfma_f32_16x16x32_bf16 v[82:85], v[150:153], v[204:207], v[82:85]
	v_mfma_f32_16x16x32_bf16 v[74:77], v[158:161], v[204:207], v[74:77]
	v_mfma_f32_16x16x32_bf16 v[70:73], v[150:153], v[212:215], v[70:73]
	v_mfma_f32_16x16x32_bf16 v[66:69], v[158:161], v[212:215], v[66:69]
	s_setprio 0
	s_barrier
	s_add_i32 s54, s45, s31
	v_lshl_add_u64 v[216:217], s[26:27], 0, v[186:187]
	s_mov_b32 m0, s54
	s_nop 0
	global_load_lds_dwordx4 v[216:217], off
	s_add_i32 m0, s54, 0x2000
	s_add_u32 s54, s26, 0x80000
	v_lshl_add_u64 v[218:219], s[26:27], 0, v[182:183]
	s_addc_u32 s55, s27, 0
	s_add_i32 s56, s46, s31
	global_load_lds_dwordx4 v[218:219], off
	v_lshl_add_u64 v[220:221], s[54:55], 0, v[186:187]
	s_mov_b32 m0, s56
	v_lshl_add_u64 v[222:223], s[28:29], 0, v[184:185]
	global_load_lds_dwordx4 v[220:221], off
	v_lshl_add_u64 v[220:221], s[54:55], 0, v[182:183]
	s_add_i32 m0, s56, 0x2000
	s_nop 0
	global_load_lds_dwordx4 v[220:221], off
	v_lshl_add_u64 v[220:221], s[28:29], 0, v[188:189]
	s_mov_b32 m0, s35
	s_nop 0
	global_load_lds_dwordx4 v[220:221], off
	s_mov_b32 m0, s36
	s_nop 0
	global_load_lds_dwordx4 v[222:223], off
	ds_read_b128 v[162:165], v202 offset:16384
	ds_read_b128 v[166:169], v202 offset:17408
	ds_read_b128 v[170:173], v202 offset:18432
	ds_read_b128 v[174:177], v202 offset:19456
	ds_read_b128 v[178:181], v202 offset:20480
	ds_read_b128 v[204:207], v202 offset:21504
	ds_read_b128 v[208:211], v202 offset:22528
	ds_read_b128 v[212:215], v202 offset:23552
	s_waitcnt vmcnt(8)
	s_waitcnt lgkmcnt(0)
	s_barrier
	s_setprio 1
	s_waitcnt lgkmcnt(0)
	v_mfma_f32_16x16x32_bf16 v[62:65], v[130:133], v[162:165], v[62:65]
	v_mfma_f32_16x16x32_bf16 v[58:61], v[138:141], v[162:165], v[58:61]
	v_mfma_f32_16x16x32_bf16 v[54:57], v[130:133], v[170:173], v[54:57]
	v_mfma_f32_16x16x32_bf16 v[46:49], v[138:141], v[170:173], v[46:49]
	v_mfma_f32_16x16x32_bf16 v[38:41], v[130:133], v[178:181], v[38:41]
	v_mfma_f32_16x16x32_bf16 v[30:33], v[138:141], v[178:181], v[30:33]
	v_mfma_f32_16x16x32_bf16 v[22:25], v[130:133], v[208:211], v[22:25]
	v_mfma_f32_16x16x32_bf16 v[14:17], v[138:141], v[208:211], v[14:17]
	v_mfma_f32_16x16x32_bf16 v[62:65], v[134:137], v[166:169], v[62:65]
	v_mfma_f32_16x16x32_bf16 v[58:61], v[142:145], v[166:169], v[58:61]
	v_mfma_f32_16x16x32_bf16 v[54:57], v[134:137], v[174:177], v[54:57]
	v_mfma_f32_16x16x32_bf16 v[46:49], v[142:145], v[174:177], v[46:49]
	v_mfma_f32_16x16x32_bf16 v[38:41], v[134:137], v[204:207], v[38:41]
	v_mfma_f32_16x16x32_bf16 v[30:33], v[142:145], v[204:207], v[30:33]
	v_mfma_f32_16x16x32_bf16 v[22:25], v[134:137], v[212:215], v[22:25]
	v_mfma_f32_16x16x32_bf16 v[14:17], v[142:145], v[212:215], v[14:17]
	s_setprio 0
	s_setprio 1
	v_mfma_f32_16x16x32_bf16 v[50:53], v[146:149], v[162:165], v[50:53]
	v_mfma_f32_16x16x32_bf16 v[42:45], v[154:157], v[162:165], v[42:45]
	v_mfma_f32_16x16x32_bf16 v[34:37], v[146:149], v[170:173], v[34:37]
	v_mfma_f32_16x16x32_bf16 v[26:29], v[154:157], v[170:173], v[26:29]
	v_mfma_f32_16x16x32_bf16 v[18:21], v[146:149], v[178:181], v[18:21]
	v_mfma_f32_16x16x32_bf16 v[10:13], v[154:157], v[178:181], v[10:13]
	v_mfma_f32_16x16x32_bf16 v[6:9], v[146:149], v[208:211], v[6:9]
	v_mfma_f32_16x16x32_bf16 v[2:5], v[154:157], v[208:211], v[2:5]
	v_mfma_f32_16x16x32_bf16 v[50:53], v[150:153], v[166:169], v[50:53]
	v_mfma_f32_16x16x32_bf16 v[42:45], v[158:161], v[166:169], v[42:45]
	v_mfma_f32_16x16x32_bf16 v[34:37], v[150:153], v[174:177], v[34:37]
	v_mfma_f32_16x16x32_bf16 v[26:29], v[158:161], v[174:177], v[26:29]
	v_mfma_f32_16x16x32_bf16 v[18:21], v[150:153], v[204:207], v[18:21]
	v_mfma_f32_16x16x32_bf16 v[10:13], v[158:161], v[204:207], v[10:13]
	v_mfma_f32_16x16x32_bf16 v[6:9], v[150:153], v[212:215], v[6:9]
	v_mfma_f32_16x16x32_bf16 v[2:5], v[158:161], v[212:215], v[2:5]
	s_setprio 0
	s_barrier
	s_add_i32 s54, 0, 0x18000
	s_add_i32 s55, 0, 0x1c000
	v_add_u32_e32 v142, s54, v199
	v_add_u32_e32 v158, s55, v199
	s_add_u32 s28, s28, 0x80000
	s_addc_u32 s29, s29, 0
	s_mov_b32 m0, s37
	v_lshl_add_u64 v[224:225], s[28:29], 0, v[188:189]
	global_load_lds_dwordx4 v[224:225], off
	v_lshl_add_u64 v[224:225], s[28:29], 0, v[184:185]
	s_mov_b32 m0, s38
	s_nop 0
	global_load_lds_dwordx4 v[224:225], off
	ds_read_b128 v[130:133], v142
	ds_read_b128 v[134:137], v142 offset:1024
	ds_read_b128 v[138:141], v142 offset:2048
	ds_read_b128 v[142:145], v142 offset:3072
	ds_read_b128 v[146:149], v158
	ds_read_b128 v[150:153], v158 offset:1024
	ds_read_b128 v[154:157], v158 offset:2048
	ds_read_b128 v[158:161], v158 offset:3072
	ds_read_b128 v[162:165], v202 offset:32768
	ds_read_b128 v[166:169], v202 offset:33792
	ds_read_b128 v[170:173], v202 offset:34816
	ds_read_b128 v[174:177], v202 offset:35840
	ds_read_b128 v[178:181], v202 offset:36864
	ds_read_b128 v[204:207], v202 offset:37888
	ds_read_b128 v[208:211], v202 offset:38912
	ds_read_b128 v[212:215], v202 offset:39936
	s_waitcnt vmcnt(8)
	s_waitcnt lgkmcnt(0)
	s_barrier
	s_setprio 1
	s_waitcnt lgkmcnt(0)
	v_mfma_f32_16x16x32_bf16 v[126:129], v[130:133], v[162:165], v[126:129]
	v_mfma_f32_16x16x32_bf16 v[122:125], v[138:141], v[162:165], v[122:125]
	v_mfma_f32_16x16x32_bf16 v[118:121], v[130:133], v[170:173], v[118:121]
	v_mfma_f32_16x16x32_bf16 v[110:113], v[138:141], v[170:173], v[110:113]
	v_mfma_f32_16x16x32_bf16 v[102:105], v[130:133], v[178:181], v[102:105]
	v_mfma_f32_16x16x32_bf16 v[94:97], v[138:141], v[178:181], v[94:97]
	v_mfma_f32_16x16x32_bf16 v[86:89], v[130:133], v[208:211], v[86:89]
	v_mfma_f32_16x16x32_bf16 v[78:81], v[138:141], v[208:211], v[78:81]
	v_mfma_f32_16x16x32_bf16 v[126:129], v[134:137], v[166:169], v[126:129]
	v_mfma_f32_16x16x32_bf16 v[122:125], v[142:145], v[166:169], v[122:125]
	v_mfma_f32_16x16x32_bf16 v[118:121], v[134:137], v[174:177], v[118:121]
	v_mfma_f32_16x16x32_bf16 v[110:113], v[142:145], v[174:177], v[110:113]
	v_mfma_f32_16x16x32_bf16 v[102:105], v[134:137], v[204:207], v[102:105]
	v_mfma_f32_16x16x32_bf16 v[94:97], v[142:145], v[204:207], v[94:97]
	v_mfma_f32_16x16x32_bf16 v[86:89], v[134:137], v[212:215], v[86:89]
	v_mfma_f32_16x16x32_bf16 v[78:81], v[142:145], v[212:215], v[78:81]
	s_setprio 0
	s_setprio 1
	v_mfma_f32_16x16x32_bf16 v[114:117], v[146:149], v[162:165], v[114:117]
	v_mfma_f32_16x16x32_bf16 v[106:109], v[154:157], v[162:165], v[106:109]
	v_mfma_f32_16x16x32_bf16 v[98:101], v[146:149], v[170:173], v[98:101]
	v_mfma_f32_16x16x32_bf16 v[90:93], v[154:157], v[170:173], v[90:93]
	v_mfma_f32_16x16x32_bf16 v[82:85], v[146:149], v[178:181], v[82:85]
	v_mfma_f32_16x16x32_bf16 v[74:77], v[154:157], v[178:181], v[74:77]
	v_mfma_f32_16x16x32_bf16 v[70:73], v[146:149], v[208:211], v[70:73]
	v_mfma_f32_16x16x32_bf16 v[66:69], v[154:157], v[208:211], v[66:69]
	v_mfma_f32_16x16x32_bf16 v[114:117], v[150:153], v[166:169], v[114:117]
	v_mfma_f32_16x16x32_bf16 v[106:109], v[158:161], v[166:169], v[106:109]
	v_mfma_f32_16x16x32_bf16 v[98:101], v[150:153], v[174:177], v[98:101]
	v_mfma_f32_16x16x32_bf16 v[90:93], v[158:161], v[174:177], v[90:93]
	v_mfma_f32_16x16x32_bf16 v[82:85], v[150:153], v[204:207], v[82:85]
	v_mfma_f32_16x16x32_bf16 v[74:77], v[158:161], v[204:207], v[74:77]
	v_mfma_f32_16x16x32_bf16 v[70:73], v[150:153], v[212:215], v[70:73]
	v_mfma_f32_16x16x32_bf16 v[66:69], v[158:161], v[212:215], v[66:69]
	s_setprio 0
	s_barrier
	s_add_i32 s28, s54, s31
	v_lshl_add_u64 v[216:217], v[216:217], 0, s[12:13]
	s_mov_b32 m0, s28
	s_nop 0
	global_load_lds_dwordx4 v[216:217], off
	s_add_i32 m0, s28, 0x2000
	s_add_u32 s26, s26, 0x80080
	v_lshl_add_u64 v[216:217], v[218:219], 0, s[12:13]
	s_addc_u32 s27, s27, 0
	s_add_i32 s28, s55, s31
	global_load_lds_dwordx4 v[216:217], off
	v_lshl_add_u64 v[216:217], s[26:27], 0, v[186:187]
	s_mov_b32 m0, s28
	s_nop 0
	global_load_lds_dwordx4 v[216:217], off
	v_lshl_add_u64 v[216:217], s[26:27], 0, v[182:183]
	s_add_i32 m0, s28, 0x2000
	s_nop 0
	global_load_lds_dwordx4 v[216:217], off
	v_lshl_add_u64 v[216:217], v[220:221], 0, s[12:13]
	s_mov_b32 m0, s42
	s_nop 0
	global_load_lds_dwordx4 v[216:217], off
	v_lshl_add_u64 v[216:217], v[222:223], 0, s[12:13]
	s_mov_b32 m0, s43
	s_nop 0
	global_load_lds_dwordx4 v[216:217], off
	ds_read_b128 v[162:165], v202 offset:49152
	ds_read_b128 v[166:169], v202 offset:50176
	ds_read_b128 v[170:173], v202 offset:51200
	ds_read_b128 v[174:177], v202 offset:52224
	ds_read_b128 v[178:181], v202 offset:53248
	ds_read_b128 v[204:207], v202 offset:54272
	ds_read_b128 v[208:211], v202 offset:55296
	ds_read_b128 v[212:215], v202 offset:56320
	s_waitcnt vmcnt(8)
	s_waitcnt lgkmcnt(0)
	s_barrier
	s_setprio 1
	s_waitcnt lgkmcnt(0)
	v_mfma_f32_16x16x32_bf16 v[62:65], v[130:133], v[162:165], v[62:65]
	v_mfma_f32_16x16x32_bf16 v[58:61], v[138:141], v[162:165], v[58:61]
	v_mfma_f32_16x16x32_bf16 v[54:57], v[130:133], v[170:173], v[54:57]
	v_mfma_f32_16x16x32_bf16 v[46:49], v[138:141], v[170:173], v[46:49]
	v_mfma_f32_16x16x32_bf16 v[38:41], v[130:133], v[178:181], v[38:41]
	v_mfma_f32_16x16x32_bf16 v[30:33], v[138:141], v[178:181], v[30:33]
	v_mfma_f32_16x16x32_bf16 v[22:25], v[130:133], v[208:211], v[22:25]
	v_mfma_f32_16x16x32_bf16 v[14:17], v[138:141], v[208:211], v[14:17]
	v_mfma_f32_16x16x32_bf16 v[62:65], v[134:137], v[166:169], v[62:65]
	v_mfma_f32_16x16x32_bf16 v[58:61], v[142:145], v[166:169], v[58:61]
	v_mfma_f32_16x16x32_bf16 v[54:57], v[134:137], v[174:177], v[54:57]
	v_mfma_f32_16x16x32_bf16 v[46:49], v[142:145], v[174:177], v[46:49]
	v_mfma_f32_16x16x32_bf16 v[38:41], v[134:137], v[204:207], v[38:41]
	v_mfma_f32_16x16x32_bf16 v[30:33], v[142:145], v[204:207], v[30:33]
	v_mfma_f32_16x16x32_bf16 v[22:25], v[134:137], v[212:215], v[22:25]
	v_mfma_f32_16x16x32_bf16 v[14:17], v[142:145], v[212:215], v[14:17]
	s_setprio 0
	s_setprio 1
	v_mfma_f32_16x16x32_bf16 v[50:53], v[146:149], v[162:165], v[50:53]
	v_mfma_f32_16x16x32_bf16 v[42:45], v[154:157], v[162:165], v[42:45]
	v_mfma_f32_16x16x32_bf16 v[34:37], v[146:149], v[170:173], v[34:37]
	v_mfma_f32_16x16x32_bf16 v[26:29], v[154:157], v[170:173], v[26:29]
	v_mfma_f32_16x16x32_bf16 v[18:21], v[146:149], v[178:181], v[18:21]
	v_mfma_f32_16x16x32_bf16 v[10:13], v[154:157], v[178:181], v[10:13]
	v_mfma_f32_16x16x32_bf16 v[6:9], v[146:149], v[208:211], v[6:9]
	v_mfma_f32_16x16x32_bf16 v[2:5], v[154:157], v[208:211], v[2:5]
	v_mfma_f32_16x16x32_bf16 v[50:53], v[150:153], v[166:169], v[50:53]
	v_mfma_f32_16x16x32_bf16 v[42:45], v[158:161], v[166:169], v[42:45]
	v_mfma_f32_16x16x32_bf16 v[34:37], v[150:153], v[174:177], v[34:37]
	v_mfma_f32_16x16x32_bf16 v[26:29], v[158:161], v[174:177], v[26:29]
	v_mfma_f32_16x16x32_bf16 v[18:21], v[150:153], v[204:207], v[18:21]
	v_mfma_f32_16x16x32_bf16 v[10:13], v[158:161], v[204:207], v[10:13]
	v_mfma_f32_16x16x32_bf16 v[6:9], v[150:153], v[212:215], v[6:9]
	v_mfma_f32_16x16x32_bf16 v[2:5], v[158:161], v[212:215], v[2:5]
	s_setprio 0
	s_add_i32 s53, s53, 2
	s_add_u32 s8, s8, 0x100
	s_addc_u32 s9, s9, 0
	s_add_u32 s51, s51, 0x100
	s_addc_u32 s52, s52, 0
	s_cmp_gt_u32 s53, 29
	s_barrier
	s_cbranch_scc0 .LBB0_1942
	s_and_b64 vcc, exec, s[14:15]
	s_cbranch_vccz .LBB0_1945
	s_barrier

.LBB0_2118:
	ds_read_b128 v[142:145], v148
	ds_read_b128 v[152:155], v148 offset:1024
	ds_read_b128 v[156:159], v148 offset:2048
	ds_read_b128 v[160:163], v148 offset:3072
	ds_read_b128 v[164:167], v149
	ds_read_b128 v[168:171], v149 offset:1024
	ds_read_b128 v[172:175], v149 offset:2048
	ds_read_b128 v[176:179], v149 offset:3072
	s_add_u32 s20, s18, 0x100
	s_addc_u32 s21, s19, 0
	s_cmpk_eq_i32 s49, 0x54
	s_cselect_b32 s25, s7, s21
	s_cselect_b32 s24, s6, s20
	s_cselect_b32 s23, s17, s48
	s_cselect_b32 s22, s16, s47
	v_lshl_add_u64 v[212:213], s[18:19], 0, v[134:135]
	s_add_i32 m0, s30, 0xc000
	ds_read_b128 v[180:183], v150
	ds_read_b128 v[184:187], v150 offset:1024
	ds_read_b128 v[188:191], v150 offset:2048
	ds_read_b128 v[192:195], v150 offset:3072
	ds_read_b128 v[196:199], v150 offset:4096
	ds_read_b128 v[200:203], v150 offset:5120
	ds_read_b128 v[204:207], v150 offset:6144
	ds_read_b128 v[208:211], v150 offset:7168
	global_load_lds_dwordx4 v[212:213], off
	v_lshl_add_u64 v[212:213], s[18:19], 0, v[136:137]
	s_add_i32 m0, s30, 0xe000
	s_nop 0
	global_load_lds_dwordx4 v[212:213], off
	s_waitcnt vmcnt(8)
	s_waitcnt lgkmcnt(0)
	s_barrier
	s_setprio 1
	s_waitcnt lgkmcnt(0)
	v_mfma_f32_16x16x32_bf16 v[126:129], v[142:145], v[180:183], v[126:129]
	v_mfma_f32_16x16x32_bf16 v[122:125], v[156:159], v[180:183], v[122:125]
	v_mfma_f32_16x16x32_bf16 v[110:113], v[142:145], v[188:191], v[110:113]
	v_mfma_f32_16x16x32_bf16 v[106:109], v[156:159], v[188:191], v[106:109]
	v_mfma_f32_16x16x32_bf16 v[94:97], v[142:145], v[196:199], v[94:97]
	v_mfma_f32_16x16x32_bf16 v[90:93], v[156:159], v[196:199], v[90:93]
	v_mfma_f32_16x16x32_bf16 v[78:81], v[142:145], v[204:207], v[78:81]
	v_mfma_f32_16x16x32_bf16 v[74:77], v[156:159], v[204:207], v[74:77]
	v_mfma_f32_16x16x32_bf16 v[126:129], v[152:155], v[184:187], v[126:129]
	v_mfma_f32_16x16x32_bf16 v[122:125], v[160:163], v[184:187], v[122:125]
	v_mfma_f32_16x16x32_bf16 v[110:113], v[152:155], v[192:195], v[110:113]
	v_mfma_f32_16x16x32_bf16 v[106:109], v[160:163], v[192:195], v[106:109]
	v_mfma_f32_16x16x32_bf16 v[94:97], v[152:155], v[200:203], v[94:97]
	v_mfma_f32_16x16x32_bf16 v[90:93], v[160:163], v[200:203], v[90:93]
	v_mfma_f32_16x16x32_bf16 v[78:81], v[152:155], v[208:211], v[78:81]
	v_mfma_f32_16x16x32_bf16 v[74:77], v[160:163], v[208:211], v[74:77]
	s_setprio 0
	s_setprio 1
	v_mfma_f32_16x16x32_bf16 v[118:121], v[164:167], v[180:183], v[118:121]
	v_mfma_f32_16x16x32_bf16 v[114:117], v[172:175], v[180:183], v[114:117]
	v_mfma_f32_16x16x32_bf16 v[102:105], v[164:167], v[188:191], v[102:105]
	v_mfma_f32_16x16x32_bf16 v[98:101], v[172:175], v[188:191], v[98:101]
	v_mfma_f32_16x16x32_bf16 v[86:89], v[164:167], v[196:199], v[86:89]
	v_mfma_f32_16x16x32_bf16 v[82:85], v[172:175], v[196:199], v[82:85]
	v_mfma_f32_16x16x32_bf16 v[70:73], v[164:167], v[204:207], v[70:73]
	v_mfma_f32_16x16x32_bf16 v[66:69], v[172:175], v[204:207], v[66:69]
	v_mfma_f32_16x16x32_bf16 v[118:121], v[168:171], v[184:187], v[118:121]
	v_mfma_f32_16x16x32_bf16 v[114:117], v[176:179], v[184:187], v[114:117]
	v_mfma_f32_16x16x32_bf16 v[102:105], v[168:171], v[192:195], v[102:105]
	v_mfma_f32_16x16x32_bf16 v[98:101], v[176:179], v[192:195], v[98:101]
	v_mfma_f32_16x16x32_bf16 v[86:89], v[168:171], v[200:203], v[86:89]
	v_mfma_f32_16x16x32_bf16 v[82:85], v[176:179], v[200:203], v[82:85]
	v_mfma_f32_16x16x32_bf16 v[70:73], v[168:171], v[208:211], v[70:73]
	v_mfma_f32_16x16x32_bf16 v[66:69], v[176:179], v[208:211], v[66:69]
	s_setprio 0
	s_barrier
	s_add_i32 s18, s42, s29
	v_lshl_add_u64 v[212:213], s[22:23], 0, v[130:131]
	s_mov_b32 m0, s18
	ds_read_b128 v[180:183], v150 offset:16384
	ds_read_b128 v[184:187], v150 offset:17408
	ds_read_b128 v[188:191], v150 offset:18432
	ds_read_b128 v[192:195], v150 offset:19456
	ds_read_b128 v[196:199], v150 offset:20480
	ds_read_b128 v[200:203], v150 offset:21504
	ds_read_b128 v[204:207], v150 offset:22528
	ds_read_b128 v[208:211], v150 offset:23552
	global_load_lds_dwordx4 v[212:213], off
	s_add_i32 m0, s18, 0x2000
	s_add_u32 s18, s22, 0x160000
	v_lshl_add_u64 v[214:215], s[22:23], 0, v[132:133]
	s_addc_u32 s19, s23, 0
	s_add_i32 s50, s43, s29
	global_load_lds_dwordx4 v[214:215], off
	v_lshl_add_u64 v[216:217], s[18:19], 0, v[130:131]
	s_mov_b32 m0, s50
	v_lshl_add_u64 v[218:219], s[24:25], 0, v[132:133]
	global_load_lds_dwordx4 v[216:217], off
	v_lshl_add_u64 v[216:217], s[18:19], 0, v[132:133]
	s_add_i32 m0, s50, 0x2000
	s_nop 0
	global_load_lds_dwordx4 v[216:217], off
	v_lshl_add_u64 v[216:217], s[24:25], 0, v[130:131]
	s_mov_b32 m0, s30
	s_nop 0
	global_load_lds_dwordx4 v[216:217], off
	s_mov_b32 m0, s31
	s_nop 0
	global_load_lds_dwordx4 v[218:219], off
	s_waitcnt vmcnt(8)
	s_waitcnt lgkmcnt(0)
	s_barrier
	s_setprio 1
	s_waitcnt lgkmcnt(0)
	v_mfma_f32_16x16x32_bf16 v[62:65], v[142:145], v[180:183], v[62:65]
	v_mfma_f32_16x16x32_bf16 v[58:61], v[156:159], v[180:183], v[58:61]
	v_mfma_f32_16x16x32_bf16 v[46:49], v[142:145], v[188:191], v[46:49]
	v_mfma_f32_16x16x32_bf16 v[42:45], v[156:159], v[188:191], v[42:45]
	v_mfma_f32_16x16x32_bf16 v[30:33], v[142:145], v[196:199], v[30:33]
	v_mfma_f32_16x16x32_bf16 v[26:29], v[156:159], v[196:199], v[26:29]
	v_mfma_f32_16x16x32_bf16 v[14:17], v[142:145], v[204:207], v[14:17]
	v_mfma_f32_16x16x32_bf16 v[10:13], v[156:159], v[204:207], v[10:13]
	v_mfma_f32_16x16x32_bf16 v[62:65], v[152:155], v[184:187], v[62:65]
	v_mfma_f32_16x16x32_bf16 v[58:61], v[160:163], v[184:187], v[58:61]
	v_mfma_f32_16x16x32_bf16 v[46:49], v[152:155], v[192:195], v[46:49]
	v_mfma_f32_16x16x32_bf16 v[42:45], v[160:163], v[192:195], v[42:45]
	v_mfma_f32_16x16x32_bf16 v[30:33], v[152:155], v[200:203], v[30:33]
	v_mfma_f32_16x16x32_bf16 v[26:29], v[160:163], v[200:203], v[26:29]
	v_mfma_f32_16x16x32_bf16 v[14:17], v[152:155], v[208:211], v[14:17]
	v_mfma_f32_16x16x32_bf16 v[10:13], v[160:163], v[208:211], v[10:13]
	s_setprio 0
	s_setprio 1
	v_mfma_f32_16x16x32_bf16 v[54:57], v[164:167], v[180:183], v[54:57]
	v_mfma_f32_16x16x32_bf16 v[50:53], v[172:175], v[180:183], v[50:53]
	v_mfma_f32_16x16x32_bf16 v[38:41], v[164:167], v[188:191], v[38:41]
	v_mfma_f32_16x16x32_bf16 v[34:37], v[172:175], v[188:191], v[34:37]
	v_mfma_f32_16x16x32_bf16 v[22:25], v[164:167], v[196:199], v[22:25]
	v_mfma_f32_16x16x32_bf16 v[18:21], v[172:175], v[196:199], v[18:21]
	v_mfma_f32_16x16x32_bf16 v[6:9], v[164:167], v[204:207], v[6:9]
	v_mfma_f32_16x16x32_bf16 v[2:5], v[172:175], v[204:207], v[2:5]
	v_mfma_f32_16x16x32_bf16 v[54:57], v[168:171], v[184:187], v[54:57]
	v_mfma_f32_16x16x32_bf16 v[50:53], v[176:179], v[184:187], v[50:53]
	v_mfma_f32_16x16x32_bf16 v[38:41], v[168:171], v[192:195], v[38:41]
	v_mfma_f32_16x16x32_bf16 v[34:37], v[176:179], v[192:195], v[34:37]
	v_mfma_f32_16x16x32_bf16 v[22:25], v[168:171], v[200:203], v[22:25]
	v_mfma_f32_16x16x32_bf16 v[18:21], v[176:179], v[200:203], v[18:21]
	v_mfma_f32_16x16x32_bf16 v[6:9], v[168:171], v[208:211], v[6:9]
	v_mfma_f32_16x16x32_bf16 v[2:5], v[176:179], v[208:211], v[2:5]
	s_setprio 0
	s_barrier
	s_add_i32 s50, 0, 0x18000
	s_add_i32 s51, 0, 0x1c000
	v_add_u32_e32 v160, s50, v147
	v_add_u32_e32 v176, s51, v147
	ds_read_b128 v[142:145], v160
	ds_read_b128 v[152:155], v160 offset:1024
	ds_read_b128 v[156:159], v160 offset:2048
	ds_read_b128 v[160:163], v160 offset:3072
	ds_read_b128 v[164:167], v176
	ds_read_b128 v[168:171], v176 offset:1024
	ds_read_b128 v[172:175], v176 offset:2048
	ds_read_b128 v[176:179], v176 offset:3072
	s_add_u32 s18, s24, 0x160000
	s_addc_u32 s19, s25, 0
	s_mov_b32 m0, s33
	v_lshl_add_u64 v[220:221], s[18:19], 0, v[130:131]
	ds_read_b128 v[180:183], v150 offset:32768
	ds_read_b128 v[184:187], v150 offset:33792
	ds_read_b128 v[188:191], v150 offset:34816
	ds_read_b128 v[192:195], v150 offset:35840
	ds_read_b128 v[196:199], v150 offset:36864
	ds_read_b128 v[200:203], v150 offset:37888
	ds_read_b128 v[204:207], v150 offset:38912
	ds_read_b128 v[208:211], v150 offset:39936
	global_load_lds_dwordx4 v[220:221], off
	v_lshl_add_u64 v[220:221], s[18:19], 0, v[132:133]
	s_mov_b32 m0, s34
	s_nop 0
	global_load_lds_dwordx4 v[220:221], off
	s_waitcnt vmcnt(8)
	s_waitcnt lgkmcnt(0)
	s_barrier
	s_setprio 1
	s_waitcnt lgkmcnt(0)
	v_mfma_f32_16x16x32_bf16 v[126:129], v[142:145], v[180:183], v[126:129]
	v_mfma_f32_16x16x32_bf16 v[122:125], v[156:159], v[180:183], v[122:125]
	v_mfma_f32_16x16x32_bf16 v[110:113], v[142:145], v[188:191], v[110:113]
	v_mfma_f32_16x16x32_bf16 v[106:109], v[156:159], v[188:191], v[106:109]
	v_mfma_f32_16x16x32_bf16 v[94:97], v[142:145], v[196:199], v[94:97]
	v_mfma_f32_16x16x32_bf16 v[90:93], v[156:159], v[196:199], v[90:93]
	v_mfma_f32_16x16x32_bf16 v[78:81], v[142:145], v[204:207], v[78:81]
	v_mfma_f32_16x16x32_bf16 v[74:77], v[156:159], v[204:207], v[74:77]
	v_mfma_f32_16x16x32_bf16 v[126:129], v[152:155], v[184:187], v[126:129]
	v_mfma_f32_16x16x32_bf16 v[122:125], v[160:163], v[184:187], v[122:125]
	v_mfma_f32_16x16x32_bf16 v[110:113], v[152:155], v[192:195], v[110:113]
	v_mfma_f32_16x16x32_bf16 v[106:109], v[160:163], v[192:195], v[106:109]
	v_mfma_f32_16x16x32_bf16 v[94:97], v[152:155], v[200:203], v[94:97]
	v_mfma_f32_16x16x32_bf16 v[90:93], v[160:163], v[200:203], v[90:93]
	v_mfma_f32_16x16x32_bf16 v[78:81], v[152:155], v[208:211], v[78:81]
	v_mfma_f32_16x16x32_bf16 v[74:77], v[160:163], v[208:211], v[74:77]
	s_setprio 0
	s_setprio 1
	v_mfma_f32_16x16x32_bf16 v[118:121], v[164:167], v[180:183], v[118:121]
	v_mfma_f32_16x16x32_bf16 v[114:117], v[172:175], v[180:183], v[114:117]
	v_mfma_f32_16x16x32_bf16 v[102:105], v[164:167], v[188:191], v[102:105]
	v_mfma_f32_16x16x32_bf16 v[98:101], v[172:175], v[188:191], v[98:101]
	v_mfma_f32_16x16x32_bf16 v[86:89], v[164:167], v[196:199], v[86:89]
	v_mfma_f32_16x16x32_bf16 v[82:85], v[172:175], v[196:199], v[82:85]
	v_mfma_f32_16x16x32_bf16 v[70:73], v[164:167], v[204:207], v[70:73]
	v_mfma_f32_16x16x32_bf16 v[66:69], v[172:175], v[204:207], v[66:69]
	v_mfma_f32_16x16x32_bf16 v[118:121], v[168:171], v[184:187], v[118:121]
	v_mfma_f32_16x16x32_bf16 v[114:117], v[176:179], v[184:187], v[114:117]
	v_mfma_f32_16x16x32_bf16 v[102:105], v[168:171], v[192:195], v[102:105]
	v_mfma_f32_16x16x32_bf16 v[98:101], v[176:179], v[192:195], v[98:101]
	v_mfma_f32_16x16x32_bf16 v[86:89], v[168:171], v[200:203], v[86:89]
	v_mfma_f32_16x16x32_bf16 v[82:85], v[176:179], v[200:203], v[82:85]
	v_mfma_f32_16x16x32_bf16 v[70:73], v[168:171], v[208:211], v[70:73]
	v_mfma_f32_16x16x32_bf16 v[66:69], v[176:179], v[208:211], v[66:69]
	s_setprio 0
	s_barrier
	s_add_i32 s18, s50, s29
	v_lshl_add_u64 v[212:213], v[212:213], 0, s[12:13]
	s_mov_b32 m0, s18
	ds_read_b128 v[180:183], v150 offset:49152
	ds_read_b128 v[184:187], v150 offset:50176
	ds_read_b128 v[188:191], v150 offset:51200
	ds_read_b128 v[192:195], v150 offset:52224
	ds_read_b128 v[196:199], v150 offset:53248
	ds_read_b128 v[200:203], v150 offset:54272
	ds_read_b128 v[204:207], v150 offset:55296
	ds_read_b128 v[208:211], v150 offset:56320
	global_load_lds_dwordx4 v[212:213], off
	s_add_i32 m0, s18, 0x2000
	s_add_u32 s18, s22, 0x160080
	v_lshl_add_u64 v[212:213], v[214:215], 0, s[12:13]
	s_addc_u32 s19, s23, 0
	s_add_i32 s22, s51, s29
	global_load_lds_dwordx4 v[212:213], off
	v_lshl_add_u64 v[212:213], s[18:19], 0, v[130:131]
	s_mov_b32 m0, s22
	s_nop 0
	global_load_lds_dwordx4 v[212:213], off
	v_lshl_add_u64 v[212:213], s[18:19], 0, v[132:133]
	s_add_i32 m0, s22, 0x2000
	s_nop 0
	global_load_lds_dwordx4 v[212:213], off
	v_lshl_add_u64 v[212:213], v[216:217], 0, s[12:13]
	s_mov_b32 m0, s38
	s_nop 0
	global_load_lds_dwordx4 v[212:213], off
	v_lshl_add_u64 v[212:213], v[218:219], 0, s[12:13]
	s_mov_b32 m0, s39
	s_nop 0
	global_load_lds_dwordx4 v[212:213], off
	s_waitcnt vmcnt(8)
	s_waitcnt lgkmcnt(0)
	s_barrier
	s_setprio 1
	s_waitcnt lgkmcnt(0)
	v_mfma_f32_16x16x32_bf16 v[62:65], v[142:145], v[180:183], v[62:65]
	v_mfma_f32_16x16x32_bf16 v[58:61], v[156:159], v[180:183], v[58:61]
	v_mfma_f32_16x16x32_bf16 v[46:49], v[142:145], v[188:191], v[46:49]
	v_mfma_f32_16x16x32_bf16 v[42:45], v[156:159], v[188:191], v[42:45]
	v_mfma_f32_16x16x32_bf16 v[30:33], v[142:145], v[196:199], v[30:33]
	v_mfma_f32_16x16x32_bf16 v[26:29], v[156:159], v[196:199], v[26:29]
	v_mfma_f32_16x16x32_bf16 v[14:17], v[142:145], v[204:207], v[14:17]
	v_mfma_f32_16x16x32_bf16 v[10:13], v[156:159], v[204:207], v[10:13]
	v_mfma_f32_16x16x32_bf16 v[62:65], v[152:155], v[184:187], v[62:65]
	v_mfma_f32_16x16x32_bf16 v[58:61], v[160:163], v[184:187], v[58:61]
	v_mfma_f32_16x16x32_bf16 v[46:49], v[152:155], v[192:195], v[46:49]
	v_mfma_f32_16x16x32_bf16 v[42:45], v[160:163], v[192:195], v[42:45]
	v_mfma_f32_16x16x32_bf16 v[30:33], v[152:155], v[200:203], v[30:33]
	v_mfma_f32_16x16x32_bf16 v[26:29], v[160:163], v[200:203], v[26:29]
	v_mfma_f32_16x16x32_bf16 v[14:17], v[152:155], v[208:211], v[14:17]
	v_mfma_f32_16x16x32_bf16 v[10:13], v[160:163], v[208:211], v[10:13]
	s_setprio 0
	s_setprio 1
	v_mfma_f32_16x16x32_bf16 v[54:57], v[164:167], v[180:183], v[54:57]
	v_mfma_f32_16x16x32_bf16 v[50:53], v[172:175], v[180:183], v[50:53]
	v_mfma_f32_16x16x32_bf16 v[38:41], v[164:167], v[188:191], v[38:41]
	v_mfma_f32_16x16x32_bf16 v[34:37], v[172:175], v[188:191], v[34:37]
	v_mfma_f32_16x16x32_bf16 v[22:25], v[164:167], v[196:199], v[22:25]
	v_mfma_f32_16x16x32_bf16 v[18:21], v[172:175], v[196:199], v[18:21]
	v_mfma_f32_16x16x32_bf16 v[6:9], v[164:167], v[204:207], v[6:9]
	v_mfma_f32_16x16x32_bf16 v[2:5], v[172:175], v[204:207], v[2:5]
	v_mfma_f32_16x16x32_bf16 v[54:57], v[168:171], v[184:187], v[54:57]
	v_mfma_f32_16x16x32_bf16 v[50:53], v[176:179], v[184:187], v[50:53]
	v_mfma_f32_16x16x32_bf16 v[38:41], v[168:171], v[192:195], v[38:41]
	v_mfma_f32_16x16x32_bf16 v[34:37], v[176:179], v[192:195], v[34:37]
	v_mfma_f32_16x16x32_bf16 v[22:25], v[168:171], v[200:203], v[22:25]
	v_mfma_f32_16x16x32_bf16 v[18:21], v[176:179], v[200:203], v[18:21]
	v_mfma_f32_16x16x32_bf16 v[6:9], v[168:171], v[208:211], v[6:9]
	v_mfma_f32_16x16x32_bf16 v[2:5], v[176:179], v[208:211], v[2:5]
	s_setprio 0
	s_add_i32 s49, s49, 2
	s_add_u32 s47, s47, 0x100
	s_addc_u32 s48, s48, 0
	s_cmpk_gt_u32 s49, 0x55
	s_mov_b64 s[18:19], s[20:21]
	s_barrier
	s_cbranch_scc0 .LBB0_2118
	s_and_b64 vcc, exec, s[14:15]
	s_cbranch_vccz .LBB0_2121
	s_barrier

.LBB0_2207:
	ds_read_b128 v[130:133], v197
	ds_read_b128 v[134:137], v197 offset:1024
	ds_read_b128 v[138:141], v197 offset:2048
	ds_read_b128 v[142:145], v197 offset:3072
	ds_read_b128 v[146:149], v198
	ds_read_b128 v[150:153], v198 offset:1024
	ds_read_b128 v[154:157], v198 offset:2048
	ds_read_b128 v[158:161], v198 offset:3072
	s_add_u32 s28, s10, 0xfff80080
	s_addc_u32 s29, s11, -1
	s_cmp_eq_u32 s36, 28
	s_cselect_b32 s31, s7, s29
	s_cselect_b32 s30, s9, s28
	s_cselect_b32 s29, s21, s35
	s_cselect_b32 s28, s23, s34
	v_lshl_add_u64 v[194:195], s[10:11], 0, v[184:185]
	s_add_i32 m0, s39, 0xc000
	ds_read_b128 v[162:165], v199
	ds_read_b128 v[166:169], v199 offset:1024
	ds_read_b128 v[170:173], v199 offset:2048
	ds_read_b128 v[174:177], v199 offset:3072
	ds_read_b128 v[202:205], v199 offset:4096
	ds_read_b128 v[206:209], v199 offset:5120
	ds_read_b128 v[210:213], v199 offset:6144
	ds_read_b128 v[214:217], v199 offset:7168
	global_load_lds_dwordx4 v[194:195], off
	v_lshl_add_u64 v[194:195], s[10:11], 0, v[186:187]
	s_add_i32 m0, s39, 0xe000
	s_nop 0
	global_load_lds_dwordx4 v[194:195], off
	s_waitcnt vmcnt(8)
	s_waitcnt lgkmcnt(0)
	s_barrier
	s_setprio 1
	s_waitcnt lgkmcnt(0)
	v_mfma_f32_16x16x32_bf16 v[126:129], v[130:133], v[162:165], v[126:129]
	v_mfma_f32_16x16x32_bf16 v[122:125], v[138:141], v[162:165], v[122:125]
	v_mfma_f32_16x16x32_bf16 v[110:113], v[130:133], v[170:173], v[110:113]
	v_mfma_f32_16x16x32_bf16 v[106:109], v[138:141], v[170:173], v[106:109]
	v_mfma_f32_16x16x32_bf16 v[94:97], v[130:133], v[202:205], v[94:97]
	v_mfma_f32_16x16x32_bf16 v[90:93], v[138:141], v[202:205], v[90:93]
	v_mfma_f32_16x16x32_bf16 v[78:81], v[130:133], v[210:213], v[78:81]
	v_mfma_f32_16x16x32_bf16 v[74:77], v[138:141], v[210:213], v[74:77]
	v_mfma_f32_16x16x32_bf16 v[126:129], v[134:137], v[166:169], v[126:129]
	v_mfma_f32_16x16x32_bf16 v[122:125], v[142:145], v[166:169], v[122:125]
	v_mfma_f32_16x16x32_bf16 v[110:113], v[134:137], v[174:177], v[110:113]
	v_mfma_f32_16x16x32_bf16 v[106:109], v[142:145], v[174:177], v[106:109]
	v_mfma_f32_16x16x32_bf16 v[94:97], v[134:137], v[206:209], v[94:97]
	v_mfma_f32_16x16x32_bf16 v[90:93], v[142:145], v[206:209], v[90:93]
	v_mfma_f32_16x16x32_bf16 v[78:81], v[134:137], v[214:217], v[78:81]
	v_mfma_f32_16x16x32_bf16 v[74:77], v[142:145], v[214:217], v[74:77]
	s_setprio 0
	s_setprio 1
	v_mfma_f32_16x16x32_bf16 v[118:121], v[146:149], v[162:165], v[118:121]
	v_mfma_f32_16x16x32_bf16 v[114:117], v[154:157], v[162:165], v[114:117]
	v_mfma_f32_16x16x32_bf16 v[102:105], v[146:149], v[170:173], v[102:105]
	v_mfma_f32_16x16x32_bf16 v[98:101], v[154:157], v[170:173], v[98:101]
	v_mfma_f32_16x16x32_bf16 v[86:89], v[146:149], v[202:205], v[86:89]
	v_mfma_f32_16x16x32_bf16 v[82:85], v[154:157], v[202:205], v[82:85]
	v_mfma_f32_16x16x32_bf16 v[70:73], v[146:149], v[210:213], v[70:73]
	v_mfma_f32_16x16x32_bf16 v[66:69], v[154:157], v[210:213], v[66:69]
	v_mfma_f32_16x16x32_bf16 v[118:121], v[150:153], v[166:169], v[118:121]
	v_mfma_f32_16x16x32_bf16 v[114:117], v[158:161], v[166:169], v[114:117]
	v_mfma_f32_16x16x32_bf16 v[102:105], v[150:153], v[174:177], v[102:105]
	v_mfma_f32_16x16x32_bf16 v[98:101], v[158:161], v[174:177], v[98:101]
	v_mfma_f32_16x16x32_bf16 v[86:89], v[150:153], v[206:209], v[86:89]
	v_mfma_f32_16x16x32_bf16 v[82:85], v[158:161], v[206:209], v[82:85]
	v_mfma_f32_16x16x32_bf16 v[70:73], v[150:153], v[214:217], v[70:73]
	v_mfma_f32_16x16x32_bf16 v[66:69], v[158:161], v[214:217], v[66:69]
	s_setprio 0
	s_barrier
	s_add_i32 s37, s52, s38
	v_lshl_add_u64 v[194:195], s[28:29], 0, v[178:179]
	s_mov_b32 m0, s37
	ds_read_b128 v[162:165], v199 offset:16384
	ds_read_b128 v[166:169], v199 offset:17408
	ds_read_b128 v[170:173], v199 offset:18432
	ds_read_b128 v[174:177], v199 offset:19456
	ds_read_b128 v[202:205], v199 offset:20480
	ds_read_b128 v[206:209], v199 offset:21504
	ds_read_b128 v[210:213], v199 offset:22528
	ds_read_b128 v[214:217], v199 offset:23552
	global_load_lds_dwordx4 v[194:195], off
	s_add_i32 m0, s37, 0x2000
	s_add_u32 s56, s28, 0x80000
	v_lshl_add_u64 v[218:219], s[28:29], 0, v[180:181]
	s_addc_u32 s57, s29, 0
	s_add_i32 s37, s53, s38
	global_load_lds_dwordx4 v[218:219], off
	v_lshl_add_u64 v[220:221], s[56:57], 0, v[178:179]
	s_mov_b32 m0, s37
	v_lshl_add_u64 v[222:223], s[30:31], 0, v[180:181]
	global_load_lds_dwordx4 v[220:221], off
	v_lshl_add_u64 v[220:221], s[56:57], 0, v[180:181]
	s_add_i32 m0, s37, 0x2000
	s_nop 0
	global_load_lds_dwordx4 v[220:221], off
	v_lshl_add_u64 v[220:221], s[30:31], 0, v[178:179]
	s_mov_b32 m0, s39
	s_nop 0
	global_load_lds_dwordx4 v[220:221], off
	s_mov_b32 m0, s40
	s_nop 0
	global_load_lds_dwordx4 v[222:223], off
	s_waitcnt vmcnt(8)
	s_waitcnt lgkmcnt(0)
	s_barrier
	s_setprio 1
	s_waitcnt lgkmcnt(0)
	v_mfma_f32_16x16x32_bf16 v[62:65], v[130:133], v[162:165], v[62:65]
	v_mfma_f32_16x16x32_bf16 v[58:61], v[138:141], v[162:165], v[58:61]
	v_mfma_f32_16x16x32_bf16 v[46:49], v[130:133], v[170:173], v[46:49]
	v_mfma_f32_16x16x32_bf16 v[42:45], v[138:141], v[170:173], v[42:45]
	v_mfma_f32_16x16x32_bf16 v[30:33], v[130:133], v[202:205], v[30:33]
	v_mfma_f32_16x16x32_bf16 v[26:29], v[138:141], v[202:205], v[26:29]
	v_mfma_f32_16x16x32_bf16 v[14:17], v[130:133], v[210:213], v[14:17]
	v_mfma_f32_16x16x32_bf16 v[10:13], v[138:141], v[210:213], v[10:13]
	v_mfma_f32_16x16x32_bf16 v[62:65], v[134:137], v[166:169], v[62:65]
	v_mfma_f32_16x16x32_bf16 v[58:61], v[142:145], v[166:169], v[58:61]
	v_mfma_f32_16x16x32_bf16 v[46:49], v[134:137], v[174:177], v[46:49]
	v_mfma_f32_16x16x32_bf16 v[42:45], v[142:145], v[174:177], v[42:45]
	v_mfma_f32_16x16x32_bf16 v[30:33], v[134:137], v[206:209], v[30:33]
	v_mfma_f32_16x16x32_bf16 v[26:29], v[142:145], v[206:209], v[26:29]
	v_mfma_f32_16x16x32_bf16 v[14:17], v[134:137], v[214:217], v[14:17]
	v_mfma_f32_16x16x32_bf16 v[10:13], v[142:145], v[214:217], v[10:13]
	s_setprio 0
	s_setprio 1
	v_mfma_f32_16x16x32_bf16 v[54:57], v[146:149], v[162:165], v[54:57]
	v_mfma_f32_16x16x32_bf16 v[50:53], v[154:157], v[162:165], v[50:53]
	v_mfma_f32_16x16x32_bf16 v[38:41], v[146:149], v[170:173], v[38:41]
	v_mfma_f32_16x16x32_bf16 v[34:37], v[154:157], v[170:173], v[34:37]
	v_mfma_f32_16x16x32_bf16 v[22:25], v[146:149], v[202:205], v[22:25]
	v_mfma_f32_16x16x32_bf16 v[18:21], v[154:157], v[202:205], v[18:21]
	v_mfma_f32_16x16x32_bf16 v[6:9], v[146:149], v[210:213], v[6:9]
	v_mfma_f32_16x16x32_bf16 v[2:5], v[154:157], v[210:213], v[2:5]
	v_mfma_f32_16x16x32_bf16 v[54:57], v[150:153], v[166:169], v[54:57]
	v_mfma_f32_16x16x32_bf16 v[50:53], v[158:161], v[166:169], v[50:53]
	v_mfma_f32_16x16x32_bf16 v[38:41], v[150:153], v[174:177], v[38:41]
	v_mfma_f32_16x16x32_bf16 v[34:37], v[158:161], v[174:177], v[34:37]
	v_mfma_f32_16x16x32_bf16 v[22:25], v[150:153], v[206:209], v[22:25]
	v_mfma_f32_16x16x32_bf16 v[18:21], v[158:161], v[206:209], v[18:21]
	v_mfma_f32_16x16x32_bf16 v[6:9], v[150:153], v[214:217], v[6:9]
	v_mfma_f32_16x16x32_bf16 v[2:5], v[158:161], v[214:217], v[2:5]
	s_setprio 0
	s_barrier
	s_add_i32 s37, 0, 0x18000
	s_add_i32 s56, 0, 0x1c000
	v_add_u32_e32 v142, s37, v196
	v_add_u32_e32 v158, s56, v196
	ds_read_b128 v[130:133], v142
	ds_read_b128 v[134:137], v142 offset:1024
	ds_read_b128 v[138:141], v142 offset:2048
	ds_read_b128 v[142:145], v142 offset:3072
	ds_read_b128 v[146:149], v158
	ds_read_b128 v[150:153], v158 offset:1024
	ds_read_b128 v[154:157], v158 offset:2048
	ds_read_b128 v[158:161], v158 offset:3072
	s_add_u32 s30, s30, 0x80000
	s_addc_u32 s31, s31, 0
	s_mov_b32 m0, s41
	v_lshl_add_u64 v[224:225], s[30:31], 0, v[178:179]
	ds_read_b128 v[162:165], v199 offset:32768
	ds_read_b128 v[166:169], v199 offset:33792
	ds_read_b128 v[170:173], v199 offset:34816
	ds_read_b128 v[174:177], v199 offset:35840
	ds_read_b128 v[202:205], v199 offset:36864
	ds_read_b128 v[206:209], v199 offset:37888
	ds_read_b128 v[210:213], v199 offset:38912
	ds_read_b128 v[214:217], v199 offset:39936
	global_load_lds_dwordx4 v[224:225], off
	v_lshl_add_u64 v[224:225], s[30:31], 0, v[180:181]
	s_mov_b32 m0, s42
	s_nop 0
	global_load_lds_dwordx4 v[224:225], off
	s_waitcnt vmcnt(8)
	s_waitcnt lgkmcnt(0)
	s_barrier
	s_setprio 1
	s_waitcnt lgkmcnt(0)
	v_mfma_f32_16x16x32_bf16 v[126:129], v[130:133], v[162:165], v[126:129]
	v_mfma_f32_16x16x32_bf16 v[122:125], v[138:141], v[162:165], v[122:125]
	v_mfma_f32_16x16x32_bf16 v[110:113], v[130:133], v[170:173], v[110:113]
	v_mfma_f32_16x16x32_bf16 v[106:109], v[138:141], v[170:173], v[106:109]
	v_mfma_f32_16x16x32_bf16 v[94:97], v[130:133], v[202:205], v[94:97]
	v_mfma_f32_16x16x32_bf16 v[90:93], v[138:141], v[202:205], v[90:93]
	v_mfma_f32_16x16x32_bf16 v[78:81], v[130:133], v[210:213], v[78:81]
	v_mfma_f32_16x16x32_bf16 v[74:77], v[138:141], v[210:213], v[74:77]
	v_mfma_f32_16x16x32_bf16 v[126:129], v[134:137], v[166:169], v[126:129]
	v_mfma_f32_16x16x32_bf16 v[122:125], v[142:145], v[166:169], v[122:125]
	v_mfma_f32_16x16x32_bf16 v[110:113], v[134:137], v[174:177], v[110:113]
	v_mfma_f32_16x16x32_bf16 v[106:109], v[142:145], v[174:177], v[106:109]
	v_mfma_f32_16x16x32_bf16 v[94:97], v[134:137], v[206:209], v[94:97]
	v_mfma_f32_16x16x32_bf16 v[90:93], v[142:145], v[206:209], v[90:93]
	v_mfma_f32_16x16x32_bf16 v[78:81], v[134:137], v[214:217], v[78:81]
	v_mfma_f32_16x16x32_bf16 v[74:77], v[142:145], v[214:217], v[74:77]
	s_setprio 0
	s_setprio 1
	v_mfma_f32_16x16x32_bf16 v[118:121], v[146:149], v[162:165], v[118:121]
	v_mfma_f32_16x16x32_bf16 v[114:117], v[154:157], v[162:165], v[114:117]
	v_mfma_f32_16x16x32_bf16 v[102:105], v[146:149], v[170:173], v[102:105]
	v_mfma_f32_16x16x32_bf16 v[98:101], v[154:157], v[170:173], v[98:101]
	v_mfma_f32_16x16x32_bf16 v[86:89], v[146:149], v[202:205], v[86:89]
	v_mfma_f32_16x16x32_bf16 v[82:85], v[154:157], v[202:205], v[82:85]
	v_mfma_f32_16x16x32_bf16 v[70:73], v[146:149], v[210:213], v[70:73]
	v_mfma_f32_16x16x32_bf16 v[66:69], v[154:157], v[210:213], v[66:69]
	v_mfma_f32_16x16x32_bf16 v[118:121], v[150:153], v[166:169], v[118:121]
	v_mfma_f32_16x16x32_bf16 v[114:117], v[158:161], v[166:169], v[114:117]
	v_mfma_f32_16x16x32_bf16 v[102:105], v[150:153], v[174:177], v[102:105]
	v_mfma_f32_16x16x32_bf16 v[98:101], v[158:161], v[174:177], v[98:101]
	v_mfma_f32_16x16x32_bf16 v[86:89], v[150:153], v[206:209], v[86:89]
	v_mfma_f32_16x16x32_bf16 v[82:85], v[158:161], v[206:209], v[82:85]
	v_mfma_f32_16x16x32_bf16 v[70:73], v[150:153], v[214:217], v[70:73]
	v_mfma_f32_16x16x32_bf16 v[66:69], v[158:161], v[214:217], v[66:69]
	s_setprio 0
	s_barrier
	s_add_i32 s30, s37, s38
	v_lshl_add_u64 v[194:195], v[194:195], 0, s[14:15]
	s_mov_b32 m0, s30
	ds_read_b128 v[162:165], v199 offset:49152
	ds_read_b128 v[166:169], v199 offset:50176
	ds_read_b128 v[170:173], v199 offset:51200
	ds_read_b128 v[174:177], v199 offset:52224
	ds_read_b128 v[202:205], v199 offset:53248
	ds_read_b128 v[206:209], v199 offset:54272
	ds_read_b128 v[210:213], v199 offset:55296
	ds_read_b128 v[214:217], v199 offset:56320
	global_load_lds_dwordx4 v[194:195], off
	s_add_i32 m0, s30, 0x2000
	s_add_u32 s28, s28, 0x80080
	v_lshl_add_u64 v[194:195], v[218:219], 0, s[14:15]
	s_addc_u32 s29, s29, 0
	s_add_i32 s30, s56, s38
	global_load_lds_dwordx4 v[194:195], off
	v_lshl_add_u64 v[194:195], s[28:29], 0, v[178:179]
	s_mov_b32 m0, s30
	s_nop 0
	global_load_lds_dwordx4 v[194:195], off
	v_lshl_add_u64 v[194:195], s[28:29], 0, v[180:181]
	s_add_i32 m0, s30, 0x2000
	s_nop 0
	global_load_lds_dwordx4 v[194:195], off
	v_lshl_add_u64 v[194:195], v[220:221], 0, s[14:15]
	s_mov_b32 m0, s46
	s_nop 0
	global_load_lds_dwordx4 v[194:195], off
	v_lshl_add_u64 v[194:195], v[222:223], 0, s[14:15]
	s_mov_b32 m0, s47
	s_nop 0
	global_load_lds_dwordx4 v[194:195], off
	s_waitcnt vmcnt(8)
	s_waitcnt lgkmcnt(0)
	s_barrier
	s_setprio 1
	s_waitcnt lgkmcnt(0)
	v_mfma_f32_16x16x32_bf16 v[62:65], v[130:133], v[162:165], v[62:65]
	v_mfma_f32_16x16x32_bf16 v[58:61], v[138:141], v[162:165], v[58:61]
	v_mfma_f32_16x16x32_bf16 v[46:49], v[130:133], v[170:173], v[46:49]
	v_mfma_f32_16x16x32_bf16 v[42:45], v[138:141], v[170:173], v[42:45]
	v_mfma_f32_16x16x32_bf16 v[30:33], v[130:133], v[202:205], v[30:33]
	v_mfma_f32_16x16x32_bf16 v[26:29], v[138:141], v[202:205], v[26:29]
	v_mfma_f32_16x16x32_bf16 v[14:17], v[130:133], v[210:213], v[14:17]
	v_mfma_f32_16x16x32_bf16 v[10:13], v[138:141], v[210:213], v[10:13]
	v_mfma_f32_16x16x32_bf16 v[62:65], v[134:137], v[166:169], v[62:65]
	v_mfma_f32_16x16x32_bf16 v[58:61], v[142:145], v[166:169], v[58:61]
	v_mfma_f32_16x16x32_bf16 v[46:49], v[134:137], v[174:177], v[46:49]
	v_mfma_f32_16x16x32_bf16 v[42:45], v[142:145], v[174:177], v[42:45]
	v_mfma_f32_16x16x32_bf16 v[30:33], v[134:137], v[206:209], v[30:33]
	v_mfma_f32_16x16x32_bf16 v[26:29], v[142:145], v[206:209], v[26:29]
	v_mfma_f32_16x16x32_bf16 v[14:17], v[134:137], v[214:217], v[14:17]
	v_mfma_f32_16x16x32_bf16 v[10:13], v[142:145], v[214:217], v[10:13]
	s_setprio 0
	s_setprio 1
	v_mfma_f32_16x16x32_bf16 v[54:57], v[146:149], v[162:165], v[54:57]
	v_mfma_f32_16x16x32_bf16 v[50:53], v[154:157], v[162:165], v[50:53]
	v_mfma_f32_16x16x32_bf16 v[38:41], v[146:149], v[170:173], v[38:41]
	v_mfma_f32_16x16x32_bf16 v[34:37], v[154:157], v[170:173], v[34:37]
	v_mfma_f32_16x16x32_bf16 v[22:25], v[146:149], v[202:205], v[22:25]
	v_mfma_f32_16x16x32_bf16 v[18:21], v[154:157], v[202:205], v[18:21]
	v_mfma_f32_16x16x32_bf16 v[6:9], v[146:149], v[210:213], v[6:9]
	v_mfma_f32_16x16x32_bf16 v[2:5], v[154:157], v[210:213], v[2:5]
	v_mfma_f32_16x16x32_bf16 v[54:57], v[150:153], v[166:169], v[54:57]
	v_mfma_f32_16x16x32_bf16 v[50:53], v[158:161], v[166:169], v[50:53]
	v_mfma_f32_16x16x32_bf16 v[38:41], v[150:153], v[174:177], v[38:41]
	v_mfma_f32_16x16x32_bf16 v[34:37], v[158:161], v[174:177], v[34:37]
	v_mfma_f32_16x16x32_bf16 v[22:25], v[150:153], v[206:209], v[22:25]
	v_mfma_f32_16x16x32_bf16 v[18:21], v[158:161], v[206:209], v[18:21]
	v_mfma_f32_16x16x32_bf16 v[6:9], v[150:153], v[214:217], v[6:9]
	v_mfma_f32_16x16x32_bf16 v[2:5], v[158:161], v[214:217], v[2:5]
	s_setprio 0
	s_add_i32 s36, s36, 2
	s_add_u32 s10, s10, 0x100
	s_addc_u32 s11, s11, 0
	s_add_u32 s34, s34, 0x100
	s_addc_u32 s35, s35, 0
	s_cmp_gt_u32 s36, 29
	s_barrier
	s_cbranch_scc0 .LBB0_2207
	s_and_b64 vcc, exec, s[16:17]
	s_cbranch_vccz .LBB0_2210
	s_barrier

.LBB0_2412:
	ds_read_b128 v[138:141], v144
	ds_read_b128 v[150:153], v144 offset:1024
	ds_read_b128 v[154:157], v144 offset:2048
	ds_read_b128 v[158:161], v144 offset:3072
	ds_read_b128 v[162:165], v145
	ds_read_b128 v[166:169], v145 offset:1024
	ds_read_b128 v[170:173], v145 offset:2048
	ds_read_b128 v[174:177], v145 offset:3072
	s_add_u32 s24, s22, 0x100
	s_addc_u32 s25, s23, 0
	s_add_u32 s26, s54, s22
	s_addc_u32 s27, s55, s23
	s_cmp_eq_u32 s56, 28
	s_cselect_b32 s28, 0, s24
	s_cselect_b32 s29, 0, s25
	s_cselect_b32 s26, s19, s26
	s_cselect_b32 s27, s10, s27
	s_add_u32 s28, s8, s28
	s_addc_u32 s29, s9, s29
	s_mov_b32 m0, s42
	v_lshl_add_u64 v[210:211], v[134:135], 0, s[22:23]
	ds_read_b128 v[178:181], v146
	ds_read_b128 v[182:185], v146 offset:1024
	ds_read_b128 v[186:189], v146 offset:2048
	ds_read_b128 v[190:193], v146 offset:3072
	ds_read_b128 v[194:197], v146 offset:4096
	ds_read_b128 v[198:201], v146 offset:5120
	ds_read_b128 v[202:205], v146 offset:6144
	ds_read_b128 v[206:209], v146 offset:7168
	global_load_lds_dwordx4 v[210:211], off
	v_lshl_add_u64 v[210:211], v[136:137], 0, s[22:23]
	s_mov_b32 m0, s43
	s_nop 0
	global_load_lds_dwordx4 v[210:211], off
	s_waitcnt vmcnt(8)
	s_waitcnt lgkmcnt(0)
	s_barrier
	s_setprio 1
	s_waitcnt lgkmcnt(0)
	v_mfma_f32_16x16x32_bf16 v[126:129], v[138:141], v[178:181], v[126:129]
	v_mfma_f32_16x16x32_bf16 v[122:125], v[154:157], v[178:181], v[122:125]
	v_mfma_f32_16x16x32_bf16 v[110:113], v[138:141], v[186:189], v[110:113]
	v_mfma_f32_16x16x32_bf16 v[106:109], v[154:157], v[186:189], v[106:109]
	v_mfma_f32_16x16x32_bf16 v[94:97], v[138:141], v[194:197], v[94:97]
	v_mfma_f32_16x16x32_bf16 v[90:93], v[154:157], v[194:197], v[90:93]
	v_mfma_f32_16x16x32_bf16 v[78:81], v[138:141], v[202:205], v[78:81]
	v_mfma_f32_16x16x32_bf16 v[74:77], v[154:157], v[202:205], v[74:77]
	v_mfma_f32_16x16x32_bf16 v[126:129], v[150:153], v[182:185], v[126:129]
	v_mfma_f32_16x16x32_bf16 v[122:125], v[158:161], v[182:185], v[122:125]
	v_mfma_f32_16x16x32_bf16 v[110:113], v[150:153], v[190:193], v[110:113]
	v_mfma_f32_16x16x32_bf16 v[106:109], v[158:161], v[190:193], v[106:109]
	v_mfma_f32_16x16x32_bf16 v[94:97], v[150:153], v[198:201], v[94:97]
	v_mfma_f32_16x16x32_bf16 v[90:93], v[158:161], v[198:201], v[90:93]
	v_mfma_f32_16x16x32_bf16 v[78:81], v[150:153], v[206:209], v[78:81]
	v_mfma_f32_16x16x32_bf16 v[74:77], v[158:161], v[206:209], v[74:77]
	s_setprio 0
	s_setprio 1
	v_mfma_f32_16x16x32_bf16 v[118:121], v[162:165], v[178:181], v[118:121]
	v_mfma_f32_16x16x32_bf16 v[114:117], v[170:173], v[178:181], v[114:117]
	v_mfma_f32_16x16x32_bf16 v[102:105], v[162:165], v[186:189], v[102:105]
	v_mfma_f32_16x16x32_bf16 v[98:101], v[170:173], v[186:189], v[98:101]
	v_mfma_f32_16x16x32_bf16 v[86:89], v[162:165], v[194:197], v[86:89]
	v_mfma_f32_16x16x32_bf16 v[82:85], v[170:173], v[194:197], v[82:85]
	v_mfma_f32_16x16x32_bf16 v[70:73], v[162:165], v[202:205], v[70:73]
	v_mfma_f32_16x16x32_bf16 v[66:69], v[170:173], v[202:205], v[66:69]
	v_mfma_f32_16x16x32_bf16 v[118:121], v[166:169], v[182:185], v[118:121]
	v_mfma_f32_16x16x32_bf16 v[114:117], v[174:177], v[182:185], v[114:117]
	v_mfma_f32_16x16x32_bf16 v[102:105], v[166:169], v[190:193], v[102:105]
	v_mfma_f32_16x16x32_bf16 v[98:101], v[174:177], v[190:193], v[98:101]
	v_mfma_f32_16x16x32_bf16 v[86:89], v[166:169], v[198:201], v[86:89]
	v_mfma_f32_16x16x32_bf16 v[82:85], v[174:177], v[198:201], v[82:85]
	v_mfma_f32_16x16x32_bf16 v[70:73], v[166:169], v[206:209], v[70:73]
	v_mfma_f32_16x16x32_bf16 v[66:69], v[174:177], v[206:209], v[66:69]
	s_setprio 0
	s_barrier
	s_mov_b32 m0, s44
	v_lshl_add_u64 v[210:211], s[26:27], 0, v[132:133]
	s_add_u32 s22, s26, 0x80000
	ds_read_b128 v[178:181], v146 offset:16384
	ds_read_b128 v[182:185], v146 offset:17408
	ds_read_b128 v[186:189], v146 offset:18432
	ds_read_b128 v[190:193], v146 offset:19456
	ds_read_b128 v[194:197], v146 offset:20480
	ds_read_b128 v[198:201], v146 offset:21504
	ds_read_b128 v[202:205], v146 offset:22528
	ds_read_b128 v[206:209], v146 offset:23552
	global_load_lds_dwordx4 v[210:211], off
	v_lshl_add_u64 v[212:213], s[26:27], 0, v[130:131]
	s_mov_b32 m0, s45
	s_addc_u32 s23, s27, 0
	global_load_lds_dwordx4 v[212:213], off
	v_lshl_add_u64 v[214:215], s[22:23], 0, v[132:133]
	s_mov_b32 m0, s46
	v_lshl_add_u64 v[216:217], s[28:29], 0, v[130:131]
	global_load_lds_dwordx4 v[214:215], off
	v_lshl_add_u64 v[214:215], s[22:23], 0, v[130:131]
	s_mov_b32 m0, s47
	s_nop 0
	global_load_lds_dwordx4 v[214:215], off
	v_lshl_add_u64 v[214:215], s[28:29], 0, v[132:133]
	s_mov_b32 m0, s33
	s_nop 0
	global_load_lds_dwordx4 v[214:215], off
	s_mov_b32 m0, s34
	s_nop 0
	global_load_lds_dwordx4 v[216:217], off
	s_waitcnt vmcnt(8)
	s_waitcnt lgkmcnt(0)
	s_barrier
	s_setprio 1
	s_waitcnt lgkmcnt(0)
	v_mfma_f32_16x16x32_bf16 v[62:65], v[138:141], v[178:181], v[62:65]
	v_mfma_f32_16x16x32_bf16 v[58:61], v[154:157], v[178:181], v[58:61]
	v_mfma_f32_16x16x32_bf16 v[46:49], v[138:141], v[186:189], v[46:49]
	v_mfma_f32_16x16x32_bf16 v[42:45], v[154:157], v[186:189], v[42:45]
	v_mfma_f32_16x16x32_bf16 v[30:33], v[138:141], v[194:197], v[30:33]
	v_mfma_f32_16x16x32_bf16 v[26:29], v[154:157], v[194:197], v[26:29]
	v_mfma_f32_16x16x32_bf16 v[14:17], v[138:141], v[202:205], v[14:17]
	v_mfma_f32_16x16x32_bf16 v[10:13], v[154:157], v[202:205], v[10:13]
	v_mfma_f32_16x16x32_bf16 v[62:65], v[150:153], v[182:185], v[62:65]
	v_mfma_f32_16x16x32_bf16 v[58:61], v[158:161], v[182:185], v[58:61]
	v_mfma_f32_16x16x32_bf16 v[46:49], v[150:153], v[190:193], v[46:49]
	v_mfma_f32_16x16x32_bf16 v[42:45], v[158:161], v[190:193], v[42:45]
	v_mfma_f32_16x16x32_bf16 v[30:33], v[150:153], v[198:201], v[30:33]
	v_mfma_f32_16x16x32_bf16 v[26:29], v[158:161], v[198:201], v[26:29]
	v_mfma_f32_16x16x32_bf16 v[14:17], v[150:153], v[206:209], v[14:17]
	v_mfma_f32_16x16x32_bf16 v[10:13], v[158:161], v[206:209], v[10:13]
	s_setprio 0
	s_setprio 1
	v_mfma_f32_16x16x32_bf16 v[54:57], v[162:165], v[178:181], v[54:57]
	v_mfma_f32_16x16x32_bf16 v[50:53], v[170:173], v[178:181], v[50:53]
	v_mfma_f32_16x16x32_bf16 v[38:41], v[162:165], v[186:189], v[38:41]
	v_mfma_f32_16x16x32_bf16 v[34:37], v[170:173], v[186:189], v[34:37]
	v_mfma_f32_16x16x32_bf16 v[22:25], v[162:165], v[194:197], v[22:25]
	v_mfma_f32_16x16x32_bf16 v[18:21], v[170:173], v[194:197], v[18:21]
	v_mfma_f32_16x16x32_bf16 v[6:9], v[162:165], v[202:205], v[6:9]
	v_mfma_f32_16x16x32_bf16 v[2:5], v[170:173], v[202:205], v[2:5]
	v_mfma_f32_16x16x32_bf16 v[54:57], v[166:169], v[182:185], v[54:57]
	v_mfma_f32_16x16x32_bf16 v[50:53], v[174:177], v[182:185], v[50:53]
	v_mfma_f32_16x16x32_bf16 v[38:41], v[166:169], v[190:193], v[38:41]
	v_mfma_f32_16x16x32_bf16 v[34:37], v[174:177], v[190:193], v[34:37]
	v_mfma_f32_16x16x32_bf16 v[22:25], v[166:169], v[198:201], v[22:25]
	v_mfma_f32_16x16x32_bf16 v[18:21], v[174:177], v[198:201], v[18:21]
	v_mfma_f32_16x16x32_bf16 v[6:9], v[166:169], v[206:209], v[6:9]
	v_mfma_f32_16x16x32_bf16 v[2:5], v[174:177], v[206:209], v[2:5]
	s_setprio 0
	s_barrier
	ds_read_b128 v[138:141], v147
	ds_read_b128 v[150:153], v147 offset:1024
	ds_read_b128 v[154:157], v147 offset:2048
	ds_read_b128 v[158:161], v147 offset:3072
	ds_read_b128 v[162:165], v148
	ds_read_b128 v[166:169], v148 offset:1024
	ds_read_b128 v[170:173], v148 offset:2048
	ds_read_b128 v[174:177], v148 offset:3072
	s_add_u32 s22, s28, 0x80000
	s_addc_u32 s23, s29, 0
	s_mov_b32 m0, s35
	v_lshl_add_u64 v[218:219], s[22:23], 0, v[132:133]
	ds_read_b128 v[178:181], v146 offset:32768
	ds_read_b128 v[182:185], v146 offset:33792
	ds_read_b128 v[186:189], v146 offset:34816
	ds_read_b128 v[190:193], v146 offset:35840
	ds_read_b128 v[194:197], v146 offset:36864
	ds_read_b128 v[198:201], v146 offset:37888
	ds_read_b128 v[202:205], v146 offset:38912
	ds_read_b128 v[206:209], v146 offset:39936
	global_load_lds_dwordx4 v[218:219], off
	v_lshl_add_u64 v[218:219], s[22:23], 0, v[130:131]
	s_mov_b32 m0, s36
	s_nop 0
	global_load_lds_dwordx4 v[218:219], off
	s_waitcnt vmcnt(8)
	s_waitcnt lgkmcnt(0)
	s_barrier
	s_setprio 1
	s_waitcnt lgkmcnt(0)
	v_mfma_f32_16x16x32_bf16 v[126:129], v[138:141], v[178:181], v[126:129]
	v_mfma_f32_16x16x32_bf16 v[122:125], v[154:157], v[178:181], v[122:125]
	v_mfma_f32_16x16x32_bf16 v[110:113], v[138:141], v[186:189], v[110:113]
	v_mfma_f32_16x16x32_bf16 v[106:109], v[154:157], v[186:189], v[106:109]
	v_mfma_f32_16x16x32_bf16 v[94:97], v[138:141], v[194:197], v[94:97]
	v_mfma_f32_16x16x32_bf16 v[90:93], v[154:157], v[194:197], v[90:93]
	v_mfma_f32_16x16x32_bf16 v[78:81], v[138:141], v[202:205], v[78:81]
	v_mfma_f32_16x16x32_bf16 v[74:77], v[154:157], v[202:205], v[74:77]
	v_mfma_f32_16x16x32_bf16 v[126:129], v[150:153], v[182:185], v[126:129]
	v_mfma_f32_16x16x32_bf16 v[122:125], v[158:161], v[182:185], v[122:125]
	v_mfma_f32_16x16x32_bf16 v[110:113], v[150:153], v[190:193], v[110:113]
	v_mfma_f32_16x16x32_bf16 v[106:109], v[158:161], v[190:193], v[106:109]
	v_mfma_f32_16x16x32_bf16 v[94:97], v[150:153], v[198:201], v[94:97]
	v_mfma_f32_16x16x32_bf16 v[90:93], v[158:161], v[198:201], v[90:93]
	v_mfma_f32_16x16x32_bf16 v[78:81], v[150:153], v[206:209], v[78:81]
	v_mfma_f32_16x16x32_bf16 v[74:77], v[158:161], v[206:209], v[74:77]
	s_setprio 0
	s_setprio 1
	v_mfma_f32_16x16x32_bf16 v[118:121], v[162:165], v[178:181], v[118:121]
	v_mfma_f32_16x16x32_bf16 v[114:117], v[170:173], v[178:181], v[114:117]
	v_mfma_f32_16x16x32_bf16 v[102:105], v[162:165], v[186:189], v[102:105]
	v_mfma_f32_16x16x32_bf16 v[98:101], v[170:173], v[186:189], v[98:101]
	v_mfma_f32_16x16x32_bf16 v[86:89], v[162:165], v[194:197], v[86:89]
	v_mfma_f32_16x16x32_bf16 v[82:85], v[170:173], v[194:197], v[82:85]
	v_mfma_f32_16x16x32_bf16 v[70:73], v[162:165], v[202:205], v[70:73]
	v_mfma_f32_16x16x32_bf16 v[66:69], v[170:173], v[202:205], v[66:69]
	v_mfma_f32_16x16x32_bf16 v[118:121], v[166:169], v[182:185], v[118:121]
	v_mfma_f32_16x16x32_bf16 v[114:117], v[174:177], v[182:185], v[114:117]
	v_mfma_f32_16x16x32_bf16 v[102:105], v[166:169], v[190:193], v[102:105]
	v_mfma_f32_16x16x32_bf16 v[98:101], v[174:177], v[190:193], v[98:101]
	v_mfma_f32_16x16x32_bf16 v[86:89], v[166:169], v[198:201], v[86:89]
	v_mfma_f32_16x16x32_bf16 v[82:85], v[174:177], v[198:201], v[82:85]
	v_mfma_f32_16x16x32_bf16 v[70:73], v[166:169], v[206:209], v[70:73]
	v_mfma_f32_16x16x32_bf16 v[66:69], v[174:177], v[206:209], v[66:69]
	s_setprio 0
	s_barrier
	s_mov_b32 m0, s48
	v_lshl_add_u64 v[210:211], v[210:211], 0, s[14:15]
	s_add_u32 s22, s26, 0x80080
	ds_read_b128 v[178:181], v146 offset:49152
	ds_read_b128 v[182:185], v146 offset:50176
	ds_read_b128 v[186:189], v146 offset:51200
	ds_read_b128 v[190:193], v146 offset:52224
	ds_read_b128 v[194:197], v146 offset:53248
	ds_read_b128 v[198:201], v146 offset:54272
	ds_read_b128 v[202:205], v146 offset:55296
	ds_read_b128 v[206:209], v146 offset:56320
	global_load_lds_dwordx4 v[210:211], off
	v_lshl_add_u64 v[210:211], v[212:213], 0, s[14:15]
	s_mov_b32 m0, s49
	s_addc_u32 s23, s27, 0
	global_load_lds_dwordx4 v[210:211], off
	v_lshl_add_u64 v[210:211], s[22:23], 0, v[132:133]
	s_mov_b32 m0, s50
	s_nop 0
	global_load_lds_dwordx4 v[210:211], off
	v_lshl_add_u64 v[210:211], s[22:23], 0, v[130:131]
	s_mov_b32 m0, s51
	s_nop 0
	global_load_lds_dwordx4 v[210:211], off
	v_lshl_add_u64 v[210:211], v[214:215], 0, s[14:15]
	s_mov_b32 m0, s39
	s_nop 0
	global_load_lds_dwordx4 v[210:211], off
	v_lshl_add_u64 v[210:211], v[216:217], 0, s[14:15]
	s_mov_b32 m0, s40
	s_nop 0
	global_load_lds_dwordx4 v[210:211], off
	s_waitcnt vmcnt(8)
	s_waitcnt lgkmcnt(0)
	s_barrier
	s_setprio 1
	s_waitcnt lgkmcnt(0)
	v_mfma_f32_16x16x32_bf16 v[62:65], v[138:141], v[178:181], v[62:65]
	v_mfma_f32_16x16x32_bf16 v[58:61], v[154:157], v[178:181], v[58:61]
	v_mfma_f32_16x16x32_bf16 v[46:49], v[138:141], v[186:189], v[46:49]
	v_mfma_f32_16x16x32_bf16 v[42:45], v[154:157], v[186:189], v[42:45]
	v_mfma_f32_16x16x32_bf16 v[30:33], v[138:141], v[194:197], v[30:33]
	v_mfma_f32_16x16x32_bf16 v[26:29], v[154:157], v[194:197], v[26:29]
	v_mfma_f32_16x16x32_bf16 v[14:17], v[138:141], v[202:205], v[14:17]
	v_mfma_f32_16x16x32_bf16 v[10:13], v[154:157], v[202:205], v[10:13]
	v_mfma_f32_16x16x32_bf16 v[62:65], v[150:153], v[182:185], v[62:65]
	v_mfma_f32_16x16x32_bf16 v[58:61], v[158:161], v[182:185], v[58:61]
	v_mfma_f32_16x16x32_bf16 v[46:49], v[150:153], v[190:193], v[46:49]
	v_mfma_f32_16x16x32_bf16 v[42:45], v[158:161], v[190:193], v[42:45]
	v_mfma_f32_16x16x32_bf16 v[30:33], v[150:153], v[198:201], v[30:33]
	v_mfma_f32_16x16x32_bf16 v[26:29], v[158:161], v[198:201], v[26:29]
	v_mfma_f32_16x16x32_bf16 v[14:17], v[150:153], v[206:209], v[14:17]
	v_mfma_f32_16x16x32_bf16 v[10:13], v[158:161], v[206:209], v[10:13]
	s_setprio 0
	s_setprio 1
	v_mfma_f32_16x16x32_bf16 v[54:57], v[162:165], v[178:181], v[54:57]
	v_mfma_f32_16x16x32_bf16 v[50:53], v[170:173], v[178:181], v[50:53]
	v_mfma_f32_16x16x32_bf16 v[38:41], v[162:165], v[186:189], v[38:41]
	v_mfma_f32_16x16x32_bf16 v[34:37], v[170:173], v[186:189], v[34:37]
	v_mfma_f32_16x16x32_bf16 v[22:25], v[162:165], v[194:197], v[22:25]
	v_mfma_f32_16x16x32_bf16 v[18:21], v[170:173], v[194:197], v[18:21]
	v_mfma_f32_16x16x32_bf16 v[6:9], v[162:165], v[202:205], v[6:9]
	v_mfma_f32_16x16x32_bf16 v[2:5], v[170:173], v[202:205], v[2:5]
	v_mfma_f32_16x16x32_bf16 v[54:57], v[166:169], v[182:185], v[54:57]
	v_mfma_f32_16x16x32_bf16 v[50:53], v[174:177], v[182:185], v[50:53]
	v_mfma_f32_16x16x32_bf16 v[38:41], v[166:169], v[190:193], v[38:41]
	v_mfma_f32_16x16x32_bf16 v[34:37], v[174:177], v[190:193], v[34:37]
	v_mfma_f32_16x16x32_bf16 v[22:25], v[166:169], v[198:201], v[22:25]
	v_mfma_f32_16x16x32_bf16 v[18:21], v[174:177], v[198:201], v[18:21]
	v_mfma_f32_16x16x32_bf16 v[6:9], v[166:169], v[206:209], v[6:9]
	v_mfma_f32_16x16x32_bf16 v[2:5], v[174:177], v[206:209], v[2:5]
	s_setprio 0
	s_add_i32 s56, s56, 2
	s_cmp_gt_u32 s56, 29
	s_mov_b64 s[22:23], s[24:25]
	s_barrier
	s_cbranch_scc0 .LBB0_2412
	s_and_b64 vcc, exec, s[16:17]
	s_cbranch_vccz .LBB0_2415
	s_barrier

.LBB0_2492:
	ds_read_b128 v[130:133], v159
	ds_read_b128 v[134:137], v159 offset:1024
	ds_read_b128 v[164:167], v159 offset:2048
	ds_read_b128 v[168:171], v159 offset:3072
	ds_read_b128 v[172:175], v161
	ds_read_b128 v[182:185], v161 offset:1024
	ds_read_b128 v[186:189], v161 offset:2048
	ds_read_b128 v[190:193], v161 offset:3072
	s_add_u32 s22, s0, 0xfff80080
	s_addc_u32 s23, s1, -1
	s_cmp_eq_u32 s48, 28
	s_cselect_b32 s25, s9, s23
	s_cselect_b32 s24, s8, s22
	s_cselect_b32 s23, s44, s47
	s_cselect_b32 s22, s45, s46
	v_lshl_add_u64 v[154:155], s[0:1], 0, v[146:147]
	s_add_i32 m0, s28, 0xc000
	ds_read_b128 v[194:197], v163
	ds_read_b128 v[198:201], v163 offset:1024
	ds_read_b128 v[202:205], v163 offset:2048
	ds_read_b128 v[206:209], v163 offset:3072
	ds_read_b128 v[210:213], v163 offset:4096
	ds_read_b128 v[214:217], v163 offset:5120
	ds_read_b128 v[218:221], v163 offset:6144
	ds_read_b128 v[222:225], v163 offset:7168
	global_load_lds_dwordx4 v[154:155], off
	v_lshl_add_u64 v[154:155], s[0:1], 0, v[148:149]
	s_add_i32 m0, s28, 0xe000
	s_nop 0
	global_load_lds_dwordx4 v[154:155], off
	s_waitcnt vmcnt(8)
	s_waitcnt lgkmcnt(0)
	s_barrier
	s_setprio 1
	s_waitcnt lgkmcnt(0)
	v_mfma_f32_16x16x32_bf16 v[126:129], v[130:133], v[194:197], v[126:129]
	v_mfma_f32_16x16x32_bf16 v[122:125], v[164:167], v[194:197], v[122:125]
	v_mfma_f32_16x16x32_bf16 v[118:121], v[130:133], v[202:205], v[118:121]
	v_mfma_f32_16x16x32_bf16 v[110:113], v[164:167], v[202:205], v[110:113]
	v_mfma_f32_16x16x32_bf16 v[102:105], v[130:133], v[210:213], v[102:105]
	v_mfma_f32_16x16x32_bf16 v[94:97], v[164:167], v[210:213], v[94:97]
	v_mfma_f32_16x16x32_bf16 v[86:89], v[130:133], v[218:221], v[86:89]
	v_mfma_f32_16x16x32_bf16 v[78:81], v[164:167], v[218:221], v[78:81]
	v_mfma_f32_16x16x32_bf16 v[126:129], v[134:137], v[198:201], v[126:129]
	v_mfma_f32_16x16x32_bf16 v[122:125], v[168:171], v[198:201], v[122:125]
	v_mfma_f32_16x16x32_bf16 v[118:121], v[134:137], v[206:209], v[118:121]
	v_mfma_f32_16x16x32_bf16 v[110:113], v[168:171], v[206:209], v[110:113]
	v_mfma_f32_16x16x32_bf16 v[102:105], v[134:137], v[214:217], v[102:105]
	v_mfma_f32_16x16x32_bf16 v[94:97], v[168:171], v[214:217], v[94:97]
	v_mfma_f32_16x16x32_bf16 v[86:89], v[134:137], v[222:225], v[86:89]
	v_mfma_f32_16x16x32_bf16 v[78:81], v[168:171], v[222:225], v[78:81]
	s_setprio 0
	s_setprio 1
	v_mfma_f32_16x16x32_bf16 v[114:117], v[172:175], v[194:197], v[114:117]
	v_mfma_f32_16x16x32_bf16 v[106:109], v[186:189], v[194:197], v[106:109]
	v_mfma_f32_16x16x32_bf16 v[98:101], v[172:175], v[202:205], v[98:101]
	v_mfma_f32_16x16x32_bf16 v[90:93], v[186:189], v[202:205], v[90:93]
	v_mfma_f32_16x16x32_bf16 v[82:85], v[172:175], v[210:213], v[82:85]
	v_mfma_f32_16x16x32_bf16 v[74:77], v[186:189], v[210:213], v[74:77]
	v_mfma_f32_16x16x32_bf16 v[70:73], v[172:175], v[218:221], v[70:73]
	v_mfma_f32_16x16x32_bf16 v[66:69], v[186:189], v[218:221], v[66:69]
	v_mfma_f32_16x16x32_bf16 v[114:117], v[182:185], v[198:201], v[114:117]
	v_mfma_f32_16x16x32_bf16 v[106:109], v[190:193], v[198:201], v[106:109]
	v_mfma_f32_16x16x32_bf16 v[98:101], v[182:185], v[206:209], v[98:101]
	v_mfma_f32_16x16x32_bf16 v[90:93], v[190:193], v[206:209], v[90:93]
	v_mfma_f32_16x16x32_bf16 v[82:85], v[182:185], v[214:217], v[82:85]
	v_mfma_f32_16x16x32_bf16 v[74:77], v[190:193], v[214:217], v[74:77]
	v_mfma_f32_16x16x32_bf16 v[70:73], v[182:185], v[222:225], v[70:73]
	v_mfma_f32_16x16x32_bf16 v[66:69], v[190:193], v[222:225], v[66:69]
	s_setprio 0
	s_barrier
	s_add_i32 s49, s64, s27
	v_lshl_add_u64 v[154:155], s[22:23], 0, v[142:143]
	s_mov_b32 m0, s49
	ds_read_b128 v[194:197], v163 offset:16384
	ds_read_b128 v[198:201], v163 offset:17408
	ds_read_b128 v[202:205], v163 offset:18432
	ds_read_b128 v[206:209], v163 offset:19456
	ds_read_b128 v[210:213], v163 offset:20480
	ds_read_b128 v[214:217], v163 offset:21504
	ds_read_b128 v[218:221], v163 offset:22528
	ds_read_b128 v[222:225], v163 offset:23552
	global_load_lds_dwordx4 v[154:155], off
	s_add_i32 m0, s49, 0x2000
	s_add_u32 s50, s22, 0x80000
	v_lshl_add_u64 v[176:177], s[22:23], 0, v[138:139]
	s_addc_u32 s51, s23, 0
	s_add_i32 s49, s65, s27
	global_load_lds_dwordx4 v[176:177], off
	v_lshl_add_u64 v[226:227], s[50:51], 0, v[142:143]
	s_mov_b32 m0, s49
	v_lshl_add_u64 v[228:229], s[24:25], 0, v[140:141]
	global_load_lds_dwordx4 v[226:227], off
	v_lshl_add_u64 v[226:227], s[50:51], 0, v[138:139]
	s_add_i32 m0, s49, 0x2000
	s_nop 0
	global_load_lds_dwordx4 v[226:227], off
	v_lshl_add_u64 v[226:227], s[24:25], 0, v[144:145]
	s_mov_b32 m0, s28
	s_nop 0
	global_load_lds_dwordx4 v[226:227], off
	s_mov_b32 m0, s29
	s_nop 0
	global_load_lds_dwordx4 v[228:229], off
	s_waitcnt vmcnt(8)
	s_waitcnt lgkmcnt(0)
	s_barrier
	s_setprio 1
	s_waitcnt lgkmcnt(0)
	v_mfma_f32_16x16x32_bf16 v[62:65], v[130:133], v[194:197], v[62:65]
	v_mfma_f32_16x16x32_bf16 v[58:61], v[164:167], v[194:197], v[58:61]
	v_mfma_f32_16x16x32_bf16 v[54:57], v[130:133], v[202:205], v[54:57]
	v_mfma_f32_16x16x32_bf16 v[46:49], v[164:167], v[202:205], v[46:49]
	v_mfma_f32_16x16x32_bf16 v[38:41], v[130:133], v[210:213], v[38:41]
	v_mfma_f32_16x16x32_bf16 v[30:33], v[164:167], v[210:213], v[30:33]
	v_mfma_f32_16x16x32_bf16 v[22:25], v[130:133], v[218:221], v[22:25]
	v_mfma_f32_16x16x32_bf16 v[14:17], v[164:167], v[218:221], v[14:17]
	v_mfma_f32_16x16x32_bf16 v[62:65], v[134:137], v[198:201], v[62:65]
	v_mfma_f32_16x16x32_bf16 v[58:61], v[168:171], v[198:201], v[58:61]
	v_mfma_f32_16x16x32_bf16 v[54:57], v[134:137], v[206:209], v[54:57]
	v_mfma_f32_16x16x32_bf16 v[46:49], v[168:171], v[206:209], v[46:49]
	v_mfma_f32_16x16x32_bf16 v[38:41], v[134:137], v[214:217], v[38:41]
	v_mfma_f32_16x16x32_bf16 v[30:33], v[168:171], v[214:217], v[30:33]
	v_mfma_f32_16x16x32_bf16 v[22:25], v[134:137], v[222:225], v[22:25]
	v_mfma_f32_16x16x32_bf16 v[14:17], v[168:171], v[222:225], v[14:17]
	s_setprio 0
	s_setprio 1
	v_mfma_f32_16x16x32_bf16 v[50:53], v[172:175], v[194:197], v[50:53]
	v_mfma_f32_16x16x32_bf16 v[42:45], v[186:189], v[194:197], v[42:45]
	v_mfma_f32_16x16x32_bf16 v[34:37], v[172:175], v[202:205], v[34:37]
	v_mfma_f32_16x16x32_bf16 v[26:29], v[186:189], v[202:205], v[26:29]
	v_mfma_f32_16x16x32_bf16 v[18:21], v[172:175], v[210:213], v[18:21]
	v_mfma_f32_16x16x32_bf16 v[10:13], v[186:189], v[210:213], v[10:13]
	v_mfma_f32_16x16x32_bf16 v[6:9], v[172:175], v[218:221], v[6:9]
	v_mfma_f32_16x16x32_bf16 v[2:5], v[186:189], v[218:221], v[2:5]
	v_mfma_f32_16x16x32_bf16 v[50:53], v[182:185], v[198:201], v[50:53]
	v_mfma_f32_16x16x32_bf16 v[42:45], v[190:193], v[198:201], v[42:45]
	v_mfma_f32_16x16x32_bf16 v[34:37], v[182:185], v[206:209], v[34:37]
	v_mfma_f32_16x16x32_bf16 v[26:29], v[190:193], v[206:209], v[26:29]
	v_mfma_f32_16x16x32_bf16 v[18:21], v[182:185], v[214:217], v[18:21]
	v_mfma_f32_16x16x32_bf16 v[10:13], v[190:193], v[214:217], v[10:13]
	v_mfma_f32_16x16x32_bf16 v[6:9], v[182:185], v[222:225], v[6:9]
	v_mfma_f32_16x16x32_bf16 v[2:5], v[190:193], v[222:225], v[2:5]
	s_setprio 0
	s_barrier
	v_add_u32_e32 v150, s66, v157
	ds_read_b128 v[130:133], v150
	ds_read_b128 v[134:137], v150 offset:1024
	ds_read_b128 v[164:167], v150 offset:2048
	ds_read_b128 v[168:171], v150 offset:3072
	v_add_u32_e32 v150, s67, v157
	ds_read_b128 v[172:175], v150
	ds_read_b128 v[182:185], v150 offset:1024
	ds_read_b128 v[186:189], v150 offset:2048
	ds_read_b128 v[190:193], v150 offset:3072
	s_add_u32 s24, s24, 0x80000
	s_addc_u32 s25, s25, 0
	s_mov_b32 m0, s30
	v_lshl_add_u64 v[230:231], s[24:25], 0, v[144:145]
	ds_read_b128 v[194:197], v163 offset:32768
	ds_read_b128 v[198:201], v163 offset:33792
	ds_read_b128 v[202:205], v163 offset:34816
	ds_read_b128 v[206:209], v163 offset:35840
	ds_read_b128 v[210:213], v163 offset:36864
	ds_read_b128 v[214:217], v163 offset:37888
	ds_read_b128 v[218:221], v163 offset:38912
	ds_read_b128 v[222:225], v163 offset:39936
	global_load_lds_dwordx4 v[230:231], off
	v_lshl_add_u64 v[230:231], s[24:25], 0, v[140:141]
	s_mov_b32 m0, s31
	s_nop 0
	global_load_lds_dwordx4 v[230:231], off
	s_waitcnt vmcnt(8)
	s_waitcnt lgkmcnt(0)
	s_barrier
	s_setprio 1
	s_waitcnt lgkmcnt(0)
	v_mfma_f32_16x16x32_bf16 v[126:129], v[130:133], v[194:197], v[126:129]
	v_mfma_f32_16x16x32_bf16 v[122:125], v[164:167], v[194:197], v[122:125]
	v_mfma_f32_16x16x32_bf16 v[118:121], v[130:133], v[202:205], v[118:121]
	v_mfma_f32_16x16x32_bf16 v[110:113], v[164:167], v[202:205], v[110:113]
	v_mfma_f32_16x16x32_bf16 v[102:105], v[130:133], v[210:213], v[102:105]
	v_mfma_f32_16x16x32_bf16 v[94:97], v[164:167], v[210:213], v[94:97]
	v_mfma_f32_16x16x32_bf16 v[86:89], v[130:133], v[218:221], v[86:89]
	v_mfma_f32_16x16x32_bf16 v[78:81], v[164:167], v[218:221], v[78:81]
	v_mfma_f32_16x16x32_bf16 v[126:129], v[134:137], v[198:201], v[126:129]
	v_mfma_f32_16x16x32_bf16 v[122:125], v[168:171], v[198:201], v[122:125]
	v_mfma_f32_16x16x32_bf16 v[118:121], v[134:137], v[206:209], v[118:121]
	v_mfma_f32_16x16x32_bf16 v[110:113], v[168:171], v[206:209], v[110:113]
	v_mfma_f32_16x16x32_bf16 v[102:105], v[134:137], v[214:217], v[102:105]
	v_mfma_f32_16x16x32_bf16 v[94:97], v[168:171], v[214:217], v[94:97]
	v_mfma_f32_16x16x32_bf16 v[86:89], v[134:137], v[222:225], v[86:89]
	v_mfma_f32_16x16x32_bf16 v[78:81], v[168:171], v[222:225], v[78:81]
	s_setprio 0
	s_setprio 1
	v_mfma_f32_16x16x32_bf16 v[114:117], v[172:175], v[194:197], v[114:117]
	v_mfma_f32_16x16x32_bf16 v[106:109], v[186:189], v[194:197], v[106:109]
	v_mfma_f32_16x16x32_bf16 v[98:101], v[172:175], v[202:205], v[98:101]
	v_mfma_f32_16x16x32_bf16 v[90:93], v[186:189], v[202:205], v[90:93]
	v_mfma_f32_16x16x32_bf16 v[82:85], v[172:175], v[210:213], v[82:85]
	v_mfma_f32_16x16x32_bf16 v[74:77], v[186:189], v[210:213], v[74:77]
	v_mfma_f32_16x16x32_bf16 v[70:73], v[172:175], v[218:221], v[70:73]
	v_mfma_f32_16x16x32_bf16 v[66:69], v[186:189], v[218:221], v[66:69]
	v_mfma_f32_16x16x32_bf16 v[114:117], v[182:185], v[198:201], v[114:117]
	v_mfma_f32_16x16x32_bf16 v[106:109], v[190:193], v[198:201], v[106:109]
	v_mfma_f32_16x16x32_bf16 v[98:101], v[182:185], v[206:209], v[98:101]
	v_mfma_f32_16x16x32_bf16 v[90:93], v[190:193], v[206:209], v[90:93]
	v_mfma_f32_16x16x32_bf16 v[82:85], v[182:185], v[214:217], v[82:85]
	v_mfma_f32_16x16x32_bf16 v[74:77], v[190:193], v[214:217], v[74:77]
	v_mfma_f32_16x16x32_bf16 v[70:73], v[182:185], v[222:225], v[70:73]
	v_mfma_f32_16x16x32_bf16 v[66:69], v[190:193], v[222:225], v[66:69]
	s_setprio 0
	s_barrier
	s_add_i32 s24, s66, s27
	v_lshl_add_u64 v[154:155], v[154:155], 0, s[12:13]
	s_mov_b32 m0, s24
	ds_read_b128 v[194:197], v163 offset:49152
	ds_read_b128 v[198:201], v163 offset:50176
	ds_read_b128 v[202:205], v163 offset:51200
	ds_read_b128 v[206:209], v163 offset:52224
	ds_read_b128 v[210:213], v163 offset:53248
	ds_read_b128 v[214:217], v163 offset:54272
	ds_read_b128 v[218:221], v163 offset:55296
	ds_read_b128 v[222:225], v163 offset:56320
	global_load_lds_dwordx4 v[154:155], off
	s_add_i32 m0, s24, 0x2000
	s_add_u32 s22, s22, 0x80080
	v_lshl_add_u64 v[154:155], v[176:177], 0, s[12:13]
	s_addc_u32 s23, s23, 0
	s_add_i32 s24, s67, s27
	global_load_lds_dwordx4 v[154:155], off
	v_lshl_add_u64 v[154:155], s[22:23], 0, v[142:143]
	s_mov_b32 m0, s24
	s_nop 0
	global_load_lds_dwordx4 v[154:155], off
	v_lshl_add_u64 v[154:155], s[22:23], 0, v[138:139]
	s_add_i32 m0, s24, 0x2000
	s_nop 0
	global_load_lds_dwordx4 v[154:155], off
	v_lshl_add_u64 v[154:155], v[226:227], 0, s[12:13]
	s_mov_b32 m0, s35
	s_nop 0
	global_load_lds_dwordx4 v[154:155], off
	v_lshl_add_u64 v[154:155], v[228:229], 0, s[12:13]
	s_mov_b32 m0, s36
	s_nop 0
	global_load_lds_dwordx4 v[154:155], off
	s_waitcnt vmcnt(8)
	s_waitcnt lgkmcnt(0)
	s_barrier
	s_setprio 1
	s_waitcnt lgkmcnt(0)
	v_mfma_f32_16x16x32_bf16 v[62:65], v[130:133], v[194:197], v[62:65]
	v_mfma_f32_16x16x32_bf16 v[58:61], v[164:167], v[194:197], v[58:61]
	v_mfma_f32_16x16x32_bf16 v[54:57], v[130:133], v[202:205], v[54:57]
	v_mfma_f32_16x16x32_bf16 v[46:49], v[164:167], v[202:205], v[46:49]
	v_mfma_f32_16x16x32_bf16 v[38:41], v[130:133], v[210:213], v[38:41]
	v_mfma_f32_16x16x32_bf16 v[30:33], v[164:167], v[210:213], v[30:33]
	v_mfma_f32_16x16x32_bf16 v[22:25], v[130:133], v[218:221], v[22:25]
	v_mfma_f32_16x16x32_bf16 v[14:17], v[164:167], v[218:221], v[14:17]
	v_mfma_f32_16x16x32_bf16 v[62:65], v[134:137], v[198:201], v[62:65]
	v_mfma_f32_16x16x32_bf16 v[58:61], v[168:171], v[198:201], v[58:61]
	v_mfma_f32_16x16x32_bf16 v[54:57], v[134:137], v[206:209], v[54:57]
	v_mfma_f32_16x16x32_bf16 v[46:49], v[168:171], v[206:209], v[46:49]
	v_mfma_f32_16x16x32_bf16 v[38:41], v[134:137], v[214:217], v[38:41]
	v_mfma_f32_16x16x32_bf16 v[30:33], v[168:171], v[214:217], v[30:33]
	v_mfma_f32_16x16x32_bf16 v[22:25], v[134:137], v[222:225], v[22:25]
	v_mfma_f32_16x16x32_bf16 v[14:17], v[168:171], v[222:225], v[14:17]
	s_setprio 0
	s_setprio 1
	v_mfma_f32_16x16x32_bf16 v[50:53], v[172:175], v[194:197], v[50:53]
	v_mfma_f32_16x16x32_bf16 v[42:45], v[186:189], v[194:197], v[42:45]
	v_mfma_f32_16x16x32_bf16 v[34:37], v[172:175], v[202:205], v[34:37]
	v_mfma_f32_16x16x32_bf16 v[26:29], v[186:189], v[202:205], v[26:29]
	v_mfma_f32_16x16x32_bf16 v[18:21], v[172:175], v[210:213], v[18:21]
	v_mfma_f32_16x16x32_bf16 v[10:13], v[186:189], v[210:213], v[10:13]
	v_mfma_f32_16x16x32_bf16 v[6:9], v[172:175], v[218:221], v[6:9]
	v_mfma_f32_16x16x32_bf16 v[2:5], v[186:189], v[218:221], v[2:5]
	v_mfma_f32_16x16x32_bf16 v[50:53], v[182:185], v[198:201], v[50:53]
	v_mfma_f32_16x16x32_bf16 v[42:45], v[190:193], v[198:201], v[42:45]
	v_mfma_f32_16x16x32_bf16 v[34:37], v[182:185], v[206:209], v[34:37]
	v_mfma_f32_16x16x32_bf16 v[26:29], v[190:193], v[206:209], v[26:29]
	v_mfma_f32_16x16x32_bf16 v[18:21], v[182:185], v[214:217], v[18:21]
	v_mfma_f32_16x16x32_bf16 v[10:13], v[190:193], v[214:217], v[10:13]
	v_mfma_f32_16x16x32_bf16 v[6:9], v[182:185], v[222:225], v[6:9]
	v_mfma_f32_16x16x32_bf16 v[2:5], v[190:193], v[222:225], v[2:5]
	s_setprio 0
	s_add_i32 s48, s48, 2
	s_add_u32 s0, s0, 0x100
	s_addc_u32 s1, s1, 0
	s_add_u32 s46, s46, 0x100
	s_addc_u32 s47, s47, 0
	s_cmp_gt_u32 s48, 29
	s_barrier
	s_cbranch_scc0 .LBB0_2492
	s_and_b64 vcc, exec, s[14:15]
	s_cbranch_vccz .LBB0_2495
	s_barrier

.LBB0_2644:
	ds_read_b128 v[138:141], v144
	ds_read_b128 v[150:153], v144 offset:1024
	ds_read_b128 v[154:157], v144 offset:2048
	ds_read_b128 v[158:161], v144 offset:3072
	ds_read_b128 v[162:165], v145
	ds_read_b128 v[166:169], v145 offset:1024
	ds_read_b128 v[170:173], v145 offset:2048
	ds_read_b128 v[174:177], v145 offset:3072
	s_add_u32 s20, s18, 0x100
	s_addc_u32 s21, s19, 0
	s_add_u32 s22, s4, s18
	s_addc_u32 s23, s52, s19
	s_cmpk_eq_i32 s53, 0x54
	s_cselect_b32 s24, 0, s20
	s_cselect_b32 s25, 0, s21
	s_cselect_b32 s22, s14, s22
	s_cselect_b32 s23, s15, s23
	s_add_u32 s24, s0, s24
	s_addc_u32 s25, s1, s25
	s_mov_b32 m0, s39
	v_lshl_add_u64 v[214:215], v[134:135], 0, s[18:19]
	ds_read_b128 v[182:185], v146
	ds_read_b128 v[186:189], v146 offset:1024
	ds_read_b128 v[190:193], v146 offset:2048
	ds_read_b128 v[194:197], v146 offset:3072
	ds_read_b128 v[198:201], v146 offset:4096
	ds_read_b128 v[202:205], v146 offset:5120
	ds_read_b128 v[206:209], v146 offset:6144
	ds_read_b128 v[210:213], v146 offset:7168
	global_load_lds_dwordx4 v[214:215], off
	v_lshl_add_u64 v[214:215], v[136:137], 0, s[18:19]
	s_mov_b32 m0, s41
	s_nop 0
	global_load_lds_dwordx4 v[214:215], off
	s_waitcnt vmcnt(8)
	s_waitcnt lgkmcnt(0)
	s_barrier
	s_setprio 1
	s_waitcnt lgkmcnt(0)
	v_mfma_f32_16x16x32_bf16 v[126:129], v[138:141], v[182:185], v[126:129]
	v_mfma_f32_16x16x32_bf16 v[122:125], v[154:157], v[182:185], v[122:125]
	v_mfma_f32_16x16x32_bf16 v[110:113], v[138:141], v[190:193], v[110:113]
	v_mfma_f32_16x16x32_bf16 v[106:109], v[154:157], v[190:193], v[106:109]
	v_mfma_f32_16x16x32_bf16 v[94:97], v[138:141], v[198:201], v[94:97]
	v_mfma_f32_16x16x32_bf16 v[90:93], v[154:157], v[198:201], v[90:93]
	v_mfma_f32_16x16x32_bf16 v[78:81], v[138:141], v[206:209], v[78:81]
	v_mfma_f32_16x16x32_bf16 v[74:77], v[154:157], v[206:209], v[74:77]
	v_mfma_f32_16x16x32_bf16 v[126:129], v[150:153], v[186:189], v[126:129]
	v_mfma_f32_16x16x32_bf16 v[122:125], v[158:161], v[186:189], v[122:125]
	v_mfma_f32_16x16x32_bf16 v[110:113], v[150:153], v[194:197], v[110:113]
	v_mfma_f32_16x16x32_bf16 v[106:109], v[158:161], v[194:197], v[106:109]
	v_mfma_f32_16x16x32_bf16 v[94:97], v[150:153], v[202:205], v[94:97]
	v_mfma_f32_16x16x32_bf16 v[90:93], v[158:161], v[202:205], v[90:93]
	v_mfma_f32_16x16x32_bf16 v[78:81], v[150:153], v[210:213], v[78:81]
	v_mfma_f32_16x16x32_bf16 v[74:77], v[158:161], v[210:213], v[74:77]
	s_setprio 0
	s_setprio 1
	v_mfma_f32_16x16x32_bf16 v[118:121], v[162:165], v[182:185], v[118:121]
	v_mfma_f32_16x16x32_bf16 v[114:117], v[170:173], v[182:185], v[114:117]
	v_mfma_f32_16x16x32_bf16 v[102:105], v[162:165], v[190:193], v[102:105]
	v_mfma_f32_16x16x32_bf16 v[98:101], v[170:173], v[190:193], v[98:101]
	v_mfma_f32_16x16x32_bf16 v[86:89], v[162:165], v[198:201], v[86:89]
	v_mfma_f32_16x16x32_bf16 v[82:85], v[170:173], v[198:201], v[82:85]
	v_mfma_f32_16x16x32_bf16 v[70:73], v[162:165], v[206:209], v[70:73]
	v_mfma_f32_16x16x32_bf16 v[66:69], v[170:173], v[206:209], v[66:69]
	v_mfma_f32_16x16x32_bf16 v[118:121], v[166:169], v[186:189], v[118:121]
	v_mfma_f32_16x16x32_bf16 v[114:117], v[174:177], v[186:189], v[114:117]
	v_mfma_f32_16x16x32_bf16 v[102:105], v[166:169], v[194:197], v[102:105]
	v_mfma_f32_16x16x32_bf16 v[98:101], v[174:177], v[194:197], v[98:101]
	v_mfma_f32_16x16x32_bf16 v[86:89], v[166:169], v[202:205], v[86:89]
	v_mfma_f32_16x16x32_bf16 v[82:85], v[174:177], v[202:205], v[82:85]
	v_mfma_f32_16x16x32_bf16 v[70:73], v[166:169], v[210:213], v[70:73]
	v_mfma_f32_16x16x32_bf16 v[66:69], v[174:177], v[210:213], v[66:69]
	s_setprio 0
	s_barrier
	s_mov_b32 m0, s42
	v_lshl_add_u64 v[214:215], s[22:23], 0, v[132:133]
	s_add_u32 s18, s22, 0x160000
	ds_read_b128 v[182:185], v146 offset:16384
	ds_read_b128 v[186:189], v146 offset:17408
	ds_read_b128 v[190:193], v146 offset:18432
	ds_read_b128 v[194:197], v146 offset:19456
	ds_read_b128 v[198:201], v146 offset:20480
	ds_read_b128 v[202:205], v146 offset:21504
	ds_read_b128 v[206:209], v146 offset:22528
	ds_read_b128 v[210:213], v146 offset:23552
	global_load_lds_dwordx4 v[214:215], off
	v_lshl_add_u64 v[216:217], s[22:23], 0, v[130:131]
	s_mov_b32 m0, s43
	s_addc_u32 s19, s23, 0
	global_load_lds_dwordx4 v[216:217], off
	v_lshl_add_u64 v[218:219], s[18:19], 0, v[132:133]
	s_mov_b32 m0, s44
	v_lshl_add_u64 v[220:221], s[24:25], 0, v[130:131]
	global_load_lds_dwordx4 v[218:219], off
	v_lshl_add_u64 v[218:219], s[18:19], 0, v[130:131]
	s_mov_b32 m0, s45
	s_nop 0
	global_load_lds_dwordx4 v[218:219], off
	v_lshl_add_u64 v[218:219], s[24:25], 0, v[132:133]
	s_mov_b32 m0, s28
	s_nop 0
	global_load_lds_dwordx4 v[218:219], off
	s_mov_b32 m0, s29
	s_nop 0
	global_load_lds_dwordx4 v[220:221], off
	s_waitcnt vmcnt(8)
	s_waitcnt lgkmcnt(0)
	s_barrier
	s_setprio 1
	s_waitcnt lgkmcnt(0)
	v_mfma_f32_16x16x32_bf16 v[62:65], v[138:141], v[182:185], v[62:65]
	v_mfma_f32_16x16x32_bf16 v[58:61], v[154:157], v[182:185], v[58:61]
	v_mfma_f32_16x16x32_bf16 v[46:49], v[138:141], v[190:193], v[46:49]
	v_mfma_f32_16x16x32_bf16 v[42:45], v[154:157], v[190:193], v[42:45]
	v_mfma_f32_16x16x32_bf16 v[30:33], v[138:141], v[198:201], v[30:33]
	v_mfma_f32_16x16x32_bf16 v[26:29], v[154:157], v[198:201], v[26:29]
	v_mfma_f32_16x16x32_bf16 v[14:17], v[138:141], v[206:209], v[14:17]
	v_mfma_f32_16x16x32_bf16 v[10:13], v[154:157], v[206:209], v[10:13]
	v_mfma_f32_16x16x32_bf16 v[62:65], v[150:153], v[186:189], v[62:65]
	v_mfma_f32_16x16x32_bf16 v[58:61], v[158:161], v[186:189], v[58:61]
	v_mfma_f32_16x16x32_bf16 v[46:49], v[150:153], v[194:197], v[46:49]
	v_mfma_f32_16x16x32_bf16 v[42:45], v[158:161], v[194:197], v[42:45]
	v_mfma_f32_16x16x32_bf16 v[30:33], v[150:153], v[202:205], v[30:33]
	v_mfma_f32_16x16x32_bf16 v[26:29], v[158:161], v[202:205], v[26:29]
	v_mfma_f32_16x16x32_bf16 v[14:17], v[150:153], v[210:213], v[14:17]
	v_mfma_f32_16x16x32_bf16 v[10:13], v[158:161], v[210:213], v[10:13]
	s_setprio 0
	s_setprio 1
	v_mfma_f32_16x16x32_bf16 v[54:57], v[162:165], v[182:185], v[54:57]
	v_mfma_f32_16x16x32_bf16 v[50:53], v[170:173], v[182:185], v[50:53]
	v_mfma_f32_16x16x32_bf16 v[38:41], v[162:165], v[190:193], v[38:41]
	v_mfma_f32_16x16x32_bf16 v[34:37], v[170:173], v[190:193], v[34:37]
	v_mfma_f32_16x16x32_bf16 v[22:25], v[162:165], v[198:201], v[22:25]
	v_mfma_f32_16x16x32_bf16 v[18:21], v[170:173], v[198:201], v[18:21]
	v_mfma_f32_16x16x32_bf16 v[6:9], v[162:165], v[206:209], v[6:9]
	v_mfma_f32_16x16x32_bf16 v[2:5], v[170:173], v[206:209], v[2:5]
	v_mfma_f32_16x16x32_bf16 v[54:57], v[166:169], v[186:189], v[54:57]
	v_mfma_f32_16x16x32_bf16 v[50:53], v[174:177], v[186:189], v[50:53]
	v_mfma_f32_16x16x32_bf16 v[38:41], v[166:169], v[194:197], v[38:41]
	v_mfma_f32_16x16x32_bf16 v[34:37], v[174:177], v[194:197], v[34:37]
	v_mfma_f32_16x16x32_bf16 v[22:25], v[166:169], v[202:205], v[22:25]
	v_mfma_f32_16x16x32_bf16 v[18:21], v[174:177], v[202:205], v[18:21]
	v_mfma_f32_16x16x32_bf16 v[6:9], v[166:169], v[210:213], v[6:9]
	v_mfma_f32_16x16x32_bf16 v[2:5], v[174:177], v[210:213], v[2:5]
	s_setprio 0
	s_barrier
	ds_read_b128 v[138:141], v147
	ds_read_b128 v[150:153], v147 offset:1024
	ds_read_b128 v[154:157], v147 offset:2048
	ds_read_b128 v[158:161], v147 offset:3072
	ds_read_b128 v[162:165], v148
	ds_read_b128 v[166:169], v148 offset:1024
	ds_read_b128 v[170:173], v148 offset:2048
	ds_read_b128 v[174:177], v148 offset:3072
	s_add_u32 s18, s24, 0x160000
	s_addc_u32 s19, s25, 0
	s_mov_b32 m0, s30
	v_lshl_add_u64 v[222:223], s[18:19], 0, v[132:133]
	ds_read_b128 v[182:185], v146 offset:32768
	ds_read_b128 v[186:189], v146 offset:33792
	ds_read_b128 v[190:193], v146 offset:34816
	ds_read_b128 v[194:197], v146 offset:35840
	ds_read_b128 v[198:201], v146 offset:36864
	ds_read_b128 v[202:205], v146 offset:37888
	ds_read_b128 v[206:209], v146 offset:38912
	ds_read_b128 v[210:213], v146 offset:39936
	global_load_lds_dwordx4 v[222:223], off
	v_lshl_add_u64 v[222:223], s[18:19], 0, v[130:131]
	s_mov_b32 m0, s31
	s_nop 0
	global_load_lds_dwordx4 v[222:223], off
	s_waitcnt vmcnt(8)
	s_waitcnt lgkmcnt(0)
	s_barrier
	s_setprio 1
	s_waitcnt lgkmcnt(0)
	v_mfma_f32_16x16x32_bf16 v[126:129], v[138:141], v[182:185], v[126:129]
	v_mfma_f32_16x16x32_bf16 v[122:125], v[154:157], v[182:185], v[122:125]
	v_mfma_f32_16x16x32_bf16 v[110:113], v[138:141], v[190:193], v[110:113]
	v_mfma_f32_16x16x32_bf16 v[106:109], v[154:157], v[190:193], v[106:109]
	v_mfma_f32_16x16x32_bf16 v[94:97], v[138:141], v[198:201], v[94:97]
	v_mfma_f32_16x16x32_bf16 v[90:93], v[154:157], v[198:201], v[90:93]
	v_mfma_f32_16x16x32_bf16 v[78:81], v[138:141], v[206:209], v[78:81]
	v_mfma_f32_16x16x32_bf16 v[74:77], v[154:157], v[206:209], v[74:77]
	v_mfma_f32_16x16x32_bf16 v[126:129], v[150:153], v[186:189], v[126:129]
	v_mfma_f32_16x16x32_bf16 v[122:125], v[158:161], v[186:189], v[122:125]
	v_mfma_f32_16x16x32_bf16 v[110:113], v[150:153], v[194:197], v[110:113]
	v_mfma_f32_16x16x32_bf16 v[106:109], v[158:161], v[194:197], v[106:109]
	v_mfma_f32_16x16x32_bf16 v[94:97], v[150:153], v[202:205], v[94:97]
	v_mfma_f32_16x16x32_bf16 v[90:93], v[158:161], v[202:205], v[90:93]
	v_mfma_f32_16x16x32_bf16 v[78:81], v[150:153], v[210:213], v[78:81]
	v_mfma_f32_16x16x32_bf16 v[74:77], v[158:161], v[210:213], v[74:77]
	s_setprio 0
	s_setprio 1
	v_mfma_f32_16x16x32_bf16 v[118:121], v[162:165], v[182:185], v[118:121]
	v_mfma_f32_16x16x32_bf16 v[114:117], v[170:173], v[182:185], v[114:117]
	v_mfma_f32_16x16x32_bf16 v[102:105], v[162:165], v[190:193], v[102:105]
	v_mfma_f32_16x16x32_bf16 v[98:101], v[170:173], v[190:193], v[98:101]
	v_mfma_f32_16x16x32_bf16 v[86:89], v[162:165], v[198:201], v[86:89]
	v_mfma_f32_16x16x32_bf16 v[82:85], v[170:173], v[198:201], v[82:85]
	v_mfma_f32_16x16x32_bf16 v[70:73], v[162:165], v[206:209], v[70:73]
	v_mfma_f32_16x16x32_bf16 v[66:69], v[170:173], v[206:209], v[66:69]
	v_mfma_f32_16x16x32_bf16 v[118:121], v[166:169], v[186:189], v[118:121]
	v_mfma_f32_16x16x32_bf16 v[114:117], v[174:177], v[186:189], v[114:117]
	v_mfma_f32_16x16x32_bf16 v[102:105], v[166:169], v[194:197], v[102:105]
	v_mfma_f32_16x16x32_bf16 v[98:101], v[174:177], v[194:197], v[98:101]
	v_mfma_f32_16x16x32_bf16 v[86:89], v[166:169], v[202:205], v[86:89]
	v_mfma_f32_16x16x32_bf16 v[82:85], v[174:177], v[202:205], v[82:85]
	v_mfma_f32_16x16x32_bf16 v[70:73], v[166:169], v[210:213], v[70:73]
	v_mfma_f32_16x16x32_bf16 v[66:69], v[174:177], v[210:213], v[66:69]
	s_setprio 0
	s_barrier
	s_mov_b32 m0, s46
	v_lshl_add_u64 v[214:215], v[214:215], 0, s[10:11]
	s_add_u32 s18, s22, 0x160080
	ds_read_b128 v[182:185], v146 offset:49152
	ds_read_b128 v[186:189], v146 offset:50176
	ds_read_b128 v[190:193], v146 offset:51200
	ds_read_b128 v[194:197], v146 offset:52224
	ds_read_b128 v[198:201], v146 offset:53248
	ds_read_b128 v[202:205], v146 offset:54272
	ds_read_b128 v[206:209], v146 offset:55296
	ds_read_b128 v[210:213], v146 offset:56320
	global_load_lds_dwordx4 v[214:215], off
	v_lshl_add_u64 v[214:215], v[216:217], 0, s[10:11]
	s_mov_b32 m0, s47
	s_addc_u32 s19, s23, 0
	global_load_lds_dwordx4 v[214:215], off
	v_lshl_add_u64 v[214:215], s[18:19], 0, v[132:133]
	s_mov_b32 m0, s48
	s_nop 0
	global_load_lds_dwordx4 v[214:215], off
	v_lshl_add_u64 v[214:215], s[18:19], 0, v[130:131]
	s_mov_b32 m0, s49
	s_nop 0
	global_load_lds_dwordx4 v[214:215], off
	v_lshl_add_u64 v[214:215], v[218:219], 0, s[10:11]
	s_mov_b32 m0, s36
	s_nop 0
	global_load_lds_dwordx4 v[214:215], off
	v_lshl_add_u64 v[214:215], v[220:221], 0, s[10:11]
	s_mov_b32 m0, s37
	s_nop 0
	global_load_lds_dwordx4 v[214:215], off
	s_waitcnt vmcnt(8)
	s_waitcnt lgkmcnt(0)
	s_barrier
	s_setprio 1
	s_waitcnt lgkmcnt(0)
	v_mfma_f32_16x16x32_bf16 v[62:65], v[138:141], v[182:185], v[62:65]
	v_mfma_f32_16x16x32_bf16 v[58:61], v[154:157], v[182:185], v[58:61]
	v_mfma_f32_16x16x32_bf16 v[46:49], v[138:141], v[190:193], v[46:49]
	v_mfma_f32_16x16x32_bf16 v[42:45], v[154:157], v[190:193], v[42:45]
	v_mfma_f32_16x16x32_bf16 v[30:33], v[138:141], v[198:201], v[30:33]
	v_mfma_f32_16x16x32_bf16 v[26:29], v[154:157], v[198:201], v[26:29]
	v_mfma_f32_16x16x32_bf16 v[14:17], v[138:141], v[206:209], v[14:17]
	v_mfma_f32_16x16x32_bf16 v[10:13], v[154:157], v[206:209], v[10:13]
	v_mfma_f32_16x16x32_bf16 v[62:65], v[150:153], v[186:189], v[62:65]
	v_mfma_f32_16x16x32_bf16 v[58:61], v[158:161], v[186:189], v[58:61]
	v_mfma_f32_16x16x32_bf16 v[46:49], v[150:153], v[194:197], v[46:49]
	v_mfma_f32_16x16x32_bf16 v[42:45], v[158:161], v[194:197], v[42:45]
	v_mfma_f32_16x16x32_bf16 v[30:33], v[150:153], v[202:205], v[30:33]
	v_mfma_f32_16x16x32_bf16 v[26:29], v[158:161], v[202:205], v[26:29]
	v_mfma_f32_16x16x32_bf16 v[14:17], v[150:153], v[210:213], v[14:17]
	v_mfma_f32_16x16x32_bf16 v[10:13], v[158:161], v[210:213], v[10:13]
	s_setprio 0
	s_setprio 1
	v_mfma_f32_16x16x32_bf16 v[54:57], v[162:165], v[182:185], v[54:57]
	v_mfma_f32_16x16x32_bf16 v[50:53], v[170:173], v[182:185], v[50:53]
	v_mfma_f32_16x16x32_bf16 v[38:41], v[162:165], v[190:193], v[38:41]
	v_mfma_f32_16x16x32_bf16 v[34:37], v[170:173], v[190:193], v[34:37]
	v_mfma_f32_16x16x32_bf16 v[22:25], v[162:165], v[198:201], v[22:25]
	v_mfma_f32_16x16x32_bf16 v[18:21], v[170:173], v[198:201], v[18:21]
	v_mfma_f32_16x16x32_bf16 v[6:9], v[162:165], v[206:209], v[6:9]
	v_mfma_f32_16x16x32_bf16 v[2:5], v[170:173], v[206:209], v[2:5]
	v_mfma_f32_16x16x32_bf16 v[54:57], v[166:169], v[186:189], v[54:57]
	v_mfma_f32_16x16x32_bf16 v[50:53], v[174:177], v[186:189], v[50:53]
	v_mfma_f32_16x16x32_bf16 v[38:41], v[166:169], v[194:197], v[38:41]
	v_mfma_f32_16x16x32_bf16 v[34:37], v[174:177], v[194:197], v[34:37]
	v_mfma_f32_16x16x32_bf16 v[22:25], v[166:169], v[202:205], v[22:25]
	v_mfma_f32_16x16x32_bf16 v[18:21], v[174:177], v[202:205], v[18:21]
	v_mfma_f32_16x16x32_bf16 v[6:9], v[166:169], v[210:213], v[6:9]
	v_mfma_f32_16x16x32_bf16 v[2:5], v[174:177], v[210:213], v[2:5]
	s_setprio 0
	s_add_i32 s53, s53, 2
	s_cmpk_gt_u32 s53, 0x55
	s_mov_b64 s[18:19], s[20:21]
	s_barrier
	s_cbranch_scc0 .LBB0_2644
	s_and_b64 vcc, exec, s[12:13]
	s_cbranch_vccz .LBB0_2647
	s_barrier

.Lat_active:
	s_and_b32 s22, s21, 0x8000
	s_add_i32 s8, s43, s22
	v_add_u32_e32 v192, s8, v246
	ds_read_b128 v[4:7], v192
	ds_read_b128 v[8:11], v192 offset:8192
	v_xor_b32_e32 v193, 32, v192
	ds_read_b128 v[12:15], v193
	ds_read_b128 v[178:181], v193 offset:8192
	v_xor_b32_e32 v194, 64, v192
	ds_read_b128 v[182:185], v194
	ds_read_b128 v[186:189], v194 offset:8192
	v_xor_b32_e32 v195, 0x60, v192
	s_add_i32 s10, s19, 1
	s_cmp_ge_i32 s10, s16
	s_cbranch_scc1 .Lat_nodma
	s_add_i32 s10, s80, s20
	s_add_i32 s10, s10, 64
	s_lshl_b32 s10, s10, 12
	s_add_u32 s98, s2, s10
	s_addc_u32 s99, s3, 0
	s_add_i32 s8, s21, 0x8000
	s_and_b32 s8, s8, 0x8000
	s_add_i32 s9, s8, 0
	s_add_i32 m0, s9, s81
	s_add_i32 s10, s54, s20
	global_load_lds_dwordx4 v200, s[98:99]
	s_add_i32 m0, s9, s83
	s_lshl_b32 s10, s10, 12
	global_load_lds_dwordx4 v201, s[98:99]
	s_add_i32 m0, s9, s87
	s_add_i32 s8, s42, s8
	global_load_lds_dwordx4 v202, s[98:99]
	s_add_i32 m0, s9, s91
	s_nop 0
	global_load_lds_dwordx4 v203, s[98:99]
	s_add_u32 s98, s4, s10
	s_addc_u32 s99, s5, 0
	s_mov_b32 m0, s8
	s_nop 0
	global_load_lds_dwordx4 v204, s[98:99]
	s_add_i32 m0, s8, 0x400
	s_nop 0
	global_load_lds_dwordx4 v205, s[98:99]
	s_add_i32 m0, s8, 0x800
	s_nop 0
	global_load_lds_dwordx4 v206, s[98:99]
	s_add_i32 m0, s8, 0xc00
	s_nop 0
	global_load_lds_dwordx4 v207, s[98:99]
.Lat_nodma:
	s_waitcnt lgkmcnt(0)
	v_mfma_f32_32x32x16_bf16 v[162:177], v[4:7], v[210:213], 0
	v_mfma_f32_32x32x16_bf16 v[146:161], v[8:11], v[210:213], 0
	ds_read_b128 v[4:7], v195
	ds_read_b128 v[8:11], v195 offset:8192
	v_mfma_f32_32x32x16_bf16 v[162:177], v[12:15], v[214:217], v[162:177]
	v_mfma_f32_32x32x16_bf16 v[146:161], v[178:181], v[214:217], v[146:161]
	ds_read_b128 v[12:15], v192 offset:128
	ds_read_b128 v[178:181], v192 offset:8320
	v_mfma_f32_32x32x16_bf16 v[162:177], v[182:185], v[218:221], v[162:177]
	v_mfma_f32_32x32x16_bf16 v[146:161], v[186:189], v[218:221], v[146:161]
	ds_read_b128 v[182:185], v193 offset:128
	ds_read_b128 v[186:189], v193 offset:8320
	s_waitcnt lgkmcnt(0)
	v_mfma_f32_32x32x16_bf16 v[162:177], v[4:7], v[222:225], v[162:177]
	v_mfma_f32_32x32x16_bf16 v[146:161], v[8:11], v[222:225], v[146:161]
	ds_read_b128 v[4:7], v194 offset:128
	ds_read_b128 v[8:11], v194 offset:8320
	v_mfma_f32_32x32x16_bf16 v[162:177], v[12:15], v[226:229], v[162:177]
	v_mfma_f32_32x32x16_bf16 v[146:161], v[178:181], v[226:229], v[146:161]
	ds_read_b128 v[12:15], v195 offset:128
	ds_read_b128 v[178:181], v195 offset:8320
	v_mfma_f32_32x32x16_bf16 v[162:177], v[182:185], v[230:233], v[162:177]
	v_mfma_f32_32x32x16_bf16 v[146:161], v[186:189], v[230:233], v[146:161]
	s_waitcnt lgkmcnt(0)
	v_mfma_f32_32x32x16_bf16 v[162:177], v[4:7], v[234:237], v[162:177]
	v_mfma_f32_32x32x16_bf16 v[146:161], v[8:11], v[234:237], v[146:161]
	v_mfma_f32_32x32x16_bf16 v[162:177], v[12:15], v[238:241], v[162:177]
	v_mfma_f32_32x32x16_bf16 v[146:161], v[178:181], v[238:241], v[146:161]
	s_add_i32 s23, s18, s20
	s_add_i32 s10, s20, 63
	s_add_i32 s8, s23, 0xffffe0bf
	s_cmpk_lt_i32 s8, 0xffa6
	s_cselect_b64 s[8:9], -1, 0
	s_cmp_lt_i32 s10, s15
	s_cselect_b64 s[12:13], -1, 0
	s_and_b64 s[10:11], s[12:13], s[8:9]
	s_and_b64 vcc, exec, s[10:11]
	s_cbranch_vccnz .Lat_farmax
	v_lshrrev_b32_e32 v11, 3, v242
	v_and_b32_e32 v11, 4, v11
	v_and_b32_e32 v2, 31, v242
	v_sub_u32_e32 v2, v11, v2
	v_add_u32_e32 v2, s23, v2
	s_add_i32 s23, 0, 0x18600
	v_lshl_add_u32 v2, v2, 2, s23
	ds_read2_b32 v[178:179], v2 offset0:0 offset1:1
	ds_read2_b32 v[180:181], v2 offset0:2 offset1:3
	ds_read2_b32 v[182:183], v2 offset0:8 offset1:9
	ds_read2_b32 v[184:185], v2 offset0:10 offset1:11
	ds_read2_b32 v[186:187], v2 offset0:16 offset1:17
	ds_read2_b32 v[188:189], v2 offset0:18 offset1:19
	ds_read2_b32 v[190:191], v2 offset0:24 offset1:25
	ds_read2_b32 v[192:193], v2 offset0:26 offset1:27
	ds_read2_b32 v[194:195], v2 offset0:32 offset1:33
	ds_read2_b32 v[196:197], v2 offset0:34 offset1:35
	ds_read2_b32 v[198:199], v2 offset0:40 offset1:41
	ds_read2_b32 v[200:201], v2 offset0:42 offset1:43
	ds_read2_b32 v[202:203], v2 offset0:48 offset1:49
	ds_read2_b32 v[204:205], v2 offset0:50 offset1:51
	ds_read2_b32 v[206:207], v2 offset0:56 offset1:57
	ds_read2_b32 v[208:209], v2 offset0:58 offset1:59
	s_waitcnt lgkmcnt(0)
	v_fmamk_f32 v162, v162, 0x3e0293ee, v178
	v_fmamk_f32 v146, v146, 0x3e0293ee, v194
	v_fmamk_f32 v163, v163, 0x3e0293ee, v179
	v_fmamk_f32 v147, v147, 0x3e0293ee, v195
	v_max_f32_e32 v2, v162, v146
	v_fmamk_f32 v164, v164, 0x3e0293ee, v180
	v_fmamk_f32 v148, v148, 0x3e0293ee, v196
	v_max3_f32 v2, v2, v163, v147
	v_fmamk_f32 v165, v165, 0x3e0293ee, v181
	v_fmamk_f32 v149, v149, 0x3e0293ee, v197
	v_max3_f32 v2, v2, v164, v148
	v_fmamk_f32 v166, v166, 0x3e0293ee, v182
	v_fmamk_f32 v150, v150, 0x3e0293ee, v198
	v_max3_f32 v2, v2, v165, v149
	v_fmamk_f32 v167, v167, 0x3e0293ee, v183
	v_fmamk_f32 v151, v151, 0x3e0293ee, v199
	v_max3_f32 v2, v2, v166, v150
	v_fmamk_f32 v168, v168, 0x3e0293ee, v184
	v_fmamk_f32 v152, v152, 0x3e0293ee, v200
	v_max3_f32 v2, v2, v167, v151
	v_fmamk_f32 v169, v169, 0x3e0293ee, v185
	v_fmamk_f32 v153, v153, 0x3e0293ee, v201
	v_max3_f32 v2, v2, v168, v152
	v_fmamk_f32 v170, v170, 0x3e0293ee, v186
	v_fmamk_f32 v154, v154, 0x3e0293ee, v202
	v_max3_f32 v2, v2, v169, v153
	v_fmamk_f32 v171, v171, 0x3e0293ee, v187
	v_fmamk_f32 v155, v155, 0x3e0293ee, v203
	v_max3_f32 v2, v2, v170, v154
	v_fmamk_f32 v172, v172, 0x3e0293ee, v188
	v_fmamk_f32 v156, v156, 0x3e0293ee, v204
	v_max3_f32 v2, v2, v171, v155
	v_fmamk_f32 v173, v173, 0x3e0293ee, v189
	v_fmamk_f32 v157, v157, 0x3e0293ee, v205
	v_max3_f32 v2, v2, v172, v156
	v_fmamk_f32 v174, v174, 0x3e0293ee, v190
	v_fmamk_f32 v158, v158, 0x3e0293ee, v206
	v_max3_f32 v2, v2, v173, v157
	v_fmamk_f32 v175, v175, 0x3e0293ee, v191
	v_fmamk_f32 v159, v159, 0x3e0293ee, v207
	v_max3_f32 v2, v2, v174, v158
	v_fmamk_f32 v176, v176, 0x3e0293ee, v192
	v_fmamk_f32 v160, v160, 0x3e0293ee, v208
	v_max3_f32 v2, v2, v175, v159
	v_fmamk_f32 v177, v177, 0x3e0293ee, v193
	v_fmamk_f32 v161, v161, 0x3e0293ee, v209
	v_max3_f32 v2, v2, v176, v160
	v_max3_f32 v4, v2, v177, v161
	s_branch .LBB0_2770

.LBB0_3114:
	ds_read_b128 v[142:145], v148
	ds_read_b128 v[152:155], v148 offset:1024
	ds_read_b128 v[156:159], v148 offset:2048
	ds_read_b128 v[160:163], v148 offset:3072
	ds_read_b128 v[164:167], v149
	ds_read_b128 v[168:171], v149 offset:1024
	ds_read_b128 v[172:175], v149 offset:2048
	ds_read_b128 v[176:179], v149 offset:3072
	s_add_u32 s26, s24, 0x100
	s_addc_u32 s27, s25, 0
	s_cmp_eq_u32 s55, 28
	s_cselect_b32 s31, s19, s27
	s_cselect_b32 s30, s51, s26
	s_cselect_b32 s29, s17, s54
	s_cselect_b32 s28, s52, s53
	v_lshl_add_u64 v[212:213], s[24:25], 0, v[134:135]
	s_add_i32 m0, s5, 0xc000
	ds_read_b128 v[180:183], v150
	ds_read_b128 v[184:187], v150 offset:1024
	ds_read_b128 v[188:191], v150 offset:2048
	ds_read_b128 v[192:195], v150 offset:3072
	ds_read_b128 v[196:199], v150 offset:4096
	ds_read_b128 v[200:203], v150 offset:5120
	ds_read_b128 v[204:207], v150 offset:6144
	ds_read_b128 v[208:211], v150 offset:7168
	global_load_lds_dwordx4 v[212:213], off
	v_lshl_add_u64 v[212:213], s[24:25], 0, v[136:137]
	s_add_i32 m0, s5, 0xe000
	s_nop 0
	global_load_lds_dwordx4 v[212:213], off
	s_waitcnt vmcnt(8)
	s_waitcnt lgkmcnt(0)
	s_barrier
	s_setprio 1
	s_waitcnt lgkmcnt(0)
	v_mfma_f32_16x16x32_bf16 v[126:129], v[142:145], v[180:183], v[126:129]
	v_mfma_f32_16x16x32_bf16 v[122:125], v[156:159], v[180:183], v[122:125]
	v_mfma_f32_16x16x32_bf16 v[110:113], v[142:145], v[188:191], v[110:113]
	v_mfma_f32_16x16x32_bf16 v[106:109], v[156:159], v[188:191], v[106:109]
	v_mfma_f32_16x16x32_bf16 v[94:97], v[142:145], v[196:199], v[94:97]
	v_mfma_f32_16x16x32_bf16 v[90:93], v[156:159], v[196:199], v[90:93]
	v_mfma_f32_16x16x32_bf16 v[78:81], v[142:145], v[204:207], v[78:81]
	v_mfma_f32_16x16x32_bf16 v[74:77], v[156:159], v[204:207], v[74:77]
	v_mfma_f32_16x16x32_bf16 v[126:129], v[152:155], v[184:187], v[126:129]
	v_mfma_f32_16x16x32_bf16 v[122:125], v[160:163], v[184:187], v[122:125]
	v_mfma_f32_16x16x32_bf16 v[110:113], v[152:155], v[192:195], v[110:113]
	v_mfma_f32_16x16x32_bf16 v[106:109], v[160:163], v[192:195], v[106:109]
	v_mfma_f32_16x16x32_bf16 v[94:97], v[152:155], v[200:203], v[94:97]
	v_mfma_f32_16x16x32_bf16 v[90:93], v[160:163], v[200:203], v[90:93]
	v_mfma_f32_16x16x32_bf16 v[78:81], v[152:155], v[208:211], v[78:81]
	v_mfma_f32_16x16x32_bf16 v[74:77], v[160:163], v[208:211], v[74:77]
	s_setprio 0
	s_setprio 1
	v_mfma_f32_16x16x32_bf16 v[118:121], v[164:167], v[180:183], v[118:121]
	v_mfma_f32_16x16x32_bf16 v[114:117], v[172:175], v[180:183], v[114:117]
	v_mfma_f32_16x16x32_bf16 v[102:105], v[164:167], v[188:191], v[102:105]
	v_mfma_f32_16x16x32_bf16 v[98:101], v[172:175], v[188:191], v[98:101]
	v_mfma_f32_16x16x32_bf16 v[86:89], v[164:167], v[196:199], v[86:89]
	v_mfma_f32_16x16x32_bf16 v[82:85], v[172:175], v[196:199], v[82:85]
	v_mfma_f32_16x16x32_bf16 v[70:73], v[164:167], v[204:207], v[70:73]
	v_mfma_f32_16x16x32_bf16 v[66:69], v[172:175], v[204:207], v[66:69]
	v_mfma_f32_16x16x32_bf16 v[118:121], v[168:171], v[184:187], v[118:121]
	v_mfma_f32_16x16x32_bf16 v[114:117], v[176:179], v[184:187], v[114:117]
	v_mfma_f32_16x16x32_bf16 v[102:105], v[168:171], v[192:195], v[102:105]
	v_mfma_f32_16x16x32_bf16 v[98:101], v[176:179], v[192:195], v[98:101]
	v_mfma_f32_16x16x32_bf16 v[86:89], v[168:171], v[200:203], v[86:89]
	v_mfma_f32_16x16x32_bf16 v[82:85], v[176:179], v[200:203], v[82:85]
	v_mfma_f32_16x16x32_bf16 v[70:73], v[168:171], v[208:211], v[70:73]
	v_mfma_f32_16x16x32_bf16 v[66:69], v[176:179], v[208:211], v[66:69]
	s_setprio 0
	s_barrier
	s_add_i32 s24, s48, s37
	v_lshl_add_u64 v[212:213], s[28:29], 0, v[130:131]
	s_mov_b32 m0, s24
	ds_read_b128 v[180:183], v150 offset:16384
	ds_read_b128 v[184:187], v150 offset:17408
	ds_read_b128 v[188:191], v150 offset:18432
	ds_read_b128 v[192:195], v150 offset:19456
	ds_read_b128 v[196:199], v150 offset:20480
	ds_read_b128 v[200:203], v150 offset:21504
	ds_read_b128 v[204:207], v150 offset:22528
	ds_read_b128 v[208:211], v150 offset:23552
	global_load_lds_dwordx4 v[212:213], off
	s_add_i32 m0, s24, 0x2000
	s_add_u32 s24, s28, 0x80000
	v_lshl_add_u64 v[214:215], s[28:29], 0, v[132:133]
	s_addc_u32 s25, s29, 0
	s_add_i32 s56, s49, s37
	global_load_lds_dwordx4 v[214:215], off
	v_lshl_add_u64 v[216:217], s[24:25], 0, v[130:131]
	s_mov_b32 m0, s56
	v_lshl_add_u64 v[218:219], s[30:31], 0, v[132:133]
	global_load_lds_dwordx4 v[216:217], off
	v_lshl_add_u64 v[216:217], s[24:25], 0, v[132:133]
	s_add_i32 m0, s56, 0x2000
	s_nop 0
	global_load_lds_dwordx4 v[216:217], off
	v_lshl_add_u64 v[216:217], s[30:31], 0, v[130:131]
	s_mov_b32 m0, s5
	s_nop 0
	global_load_lds_dwordx4 v[216:217], off
	s_mov_b32 m0, s38
	s_nop 0
	global_load_lds_dwordx4 v[218:219], off
	s_waitcnt vmcnt(8)
	s_waitcnt lgkmcnt(0)
	s_barrier
	s_setprio 1
	s_waitcnt lgkmcnt(0)
	v_mfma_f32_16x16x32_bf16 v[62:65], v[142:145], v[180:183], v[62:65]
	v_mfma_f32_16x16x32_bf16 v[58:61], v[156:159], v[180:183], v[58:61]
	v_mfma_f32_16x16x32_bf16 v[46:49], v[142:145], v[188:191], v[46:49]
	v_mfma_f32_16x16x32_bf16 v[42:45], v[156:159], v[188:191], v[42:45]
	v_mfma_f32_16x16x32_bf16 v[30:33], v[142:145], v[196:199], v[30:33]
	v_mfma_f32_16x16x32_bf16 v[26:29], v[156:159], v[196:199], v[26:29]
	v_mfma_f32_16x16x32_bf16 v[14:17], v[142:145], v[204:207], v[14:17]
	v_mfma_f32_16x16x32_bf16 v[10:13], v[156:159], v[204:207], v[10:13]
	v_mfma_f32_16x16x32_bf16 v[62:65], v[152:155], v[184:187], v[62:65]
	v_mfma_f32_16x16x32_bf16 v[58:61], v[160:163], v[184:187], v[58:61]
	v_mfma_f32_16x16x32_bf16 v[46:49], v[152:155], v[192:195], v[46:49]
	v_mfma_f32_16x16x32_bf16 v[42:45], v[160:163], v[192:195], v[42:45]
	v_mfma_f32_16x16x32_bf16 v[30:33], v[152:155], v[200:203], v[30:33]
	v_mfma_f32_16x16x32_bf16 v[26:29], v[160:163], v[200:203], v[26:29]
	v_mfma_f32_16x16x32_bf16 v[14:17], v[152:155], v[208:211], v[14:17]
	v_mfma_f32_16x16x32_bf16 v[10:13], v[160:163], v[208:211], v[10:13]
	s_setprio 0
	s_setprio 1
	v_mfma_f32_16x16x32_bf16 v[54:57], v[164:167], v[180:183], v[54:57]
	v_mfma_f32_16x16x32_bf16 v[50:53], v[172:175], v[180:183], v[50:53]
	v_mfma_f32_16x16x32_bf16 v[38:41], v[164:167], v[188:191], v[38:41]
	v_mfma_f32_16x16x32_bf16 v[34:37], v[172:175], v[188:191], v[34:37]
	v_mfma_f32_16x16x32_bf16 v[22:25], v[164:167], v[196:199], v[22:25]
	v_mfma_f32_16x16x32_bf16 v[18:21], v[172:175], v[196:199], v[18:21]
	v_mfma_f32_16x16x32_bf16 v[6:9], v[164:167], v[204:207], v[6:9]
	v_mfma_f32_16x16x32_bf16 v[2:5], v[172:175], v[204:207], v[2:5]
	v_mfma_f32_16x16x32_bf16 v[54:57], v[168:171], v[184:187], v[54:57]
	v_mfma_f32_16x16x32_bf16 v[50:53], v[176:179], v[184:187], v[50:53]
	v_mfma_f32_16x16x32_bf16 v[38:41], v[168:171], v[192:195], v[38:41]
	v_mfma_f32_16x16x32_bf16 v[34:37], v[176:179], v[192:195], v[34:37]
	v_mfma_f32_16x16x32_bf16 v[22:25], v[168:171], v[200:203], v[22:25]
	v_mfma_f32_16x16x32_bf16 v[18:21], v[176:179], v[200:203], v[18:21]
	v_mfma_f32_16x16x32_bf16 v[6:9], v[168:171], v[208:211], v[6:9]
	v_mfma_f32_16x16x32_bf16 v[2:5], v[176:179], v[208:211], v[2:5]
	s_setprio 0
	s_barrier
	s_add_i32 s56, 0, 0x18000
	s_add_i32 s57, 0, 0x1c000
	v_add_u32_e32 v160, s56, v147
	v_add_u32_e32 v176, s57, v147
	ds_read_b128 v[142:145], v160
	ds_read_b128 v[152:155], v160 offset:1024
	ds_read_b128 v[156:159], v160 offset:2048
	ds_read_b128 v[160:163], v160 offset:3072
	ds_read_b128 v[164:167], v176
	ds_read_b128 v[168:171], v176 offset:1024
	ds_read_b128 v[172:175], v176 offset:2048
	ds_read_b128 v[176:179], v176 offset:3072
	s_add_u32 s24, s30, 0x80000
	s_addc_u32 s25, s31, 0
	s_mov_b32 m0, s39
	v_lshl_add_u64 v[220:221], s[24:25], 0, v[130:131]
	ds_read_b128 v[180:183], v150 offset:32768
	ds_read_b128 v[184:187], v150 offset:33792
	ds_read_b128 v[188:191], v150 offset:34816
	ds_read_b128 v[192:195], v150 offset:35840
	ds_read_b128 v[196:199], v150 offset:36864
	ds_read_b128 v[200:203], v150 offset:37888
	ds_read_b128 v[204:207], v150 offset:38912
	ds_read_b128 v[208:211], v150 offset:39936
	global_load_lds_dwordx4 v[220:221], off
	v_lshl_add_u64 v[220:221], s[24:25], 0, v[132:133]
	s_mov_b32 m0, s40
	s_nop 0
	global_load_lds_dwordx4 v[220:221], off
	s_waitcnt vmcnt(8)
	s_waitcnt lgkmcnt(0)
	s_barrier
	s_setprio 1
	s_waitcnt lgkmcnt(0)
	v_mfma_f32_16x16x32_bf16 v[126:129], v[142:145], v[180:183], v[126:129]
	v_mfma_f32_16x16x32_bf16 v[122:125], v[156:159], v[180:183], v[122:125]
	v_mfma_f32_16x16x32_bf16 v[110:113], v[142:145], v[188:191], v[110:113]
	v_mfma_f32_16x16x32_bf16 v[106:109], v[156:159], v[188:191], v[106:109]
	v_mfma_f32_16x16x32_bf16 v[94:97], v[142:145], v[196:199], v[94:97]
	v_mfma_f32_16x16x32_bf16 v[90:93], v[156:159], v[196:199], v[90:93]
	v_mfma_f32_16x16x32_bf16 v[78:81], v[142:145], v[204:207], v[78:81]
	v_mfma_f32_16x16x32_bf16 v[74:77], v[156:159], v[204:207], v[74:77]
	v_mfma_f32_16x16x32_bf16 v[126:129], v[152:155], v[184:187], v[126:129]
	v_mfma_f32_16x16x32_bf16 v[122:125], v[160:163], v[184:187], v[122:125]
	v_mfma_f32_16x16x32_bf16 v[110:113], v[152:155], v[192:195], v[110:113]
	v_mfma_f32_16x16x32_bf16 v[106:109], v[160:163], v[192:195], v[106:109]
	v_mfma_f32_16x16x32_bf16 v[94:97], v[152:155], v[200:203], v[94:97]
	v_mfma_f32_16x16x32_bf16 v[90:93], v[160:163], v[200:203], v[90:93]
	v_mfma_f32_16x16x32_bf16 v[78:81], v[152:155], v[208:211], v[78:81]
	v_mfma_f32_16x16x32_bf16 v[74:77], v[160:163], v[208:211], v[74:77]
	s_setprio 0
	s_setprio 1
	v_mfma_f32_16x16x32_bf16 v[118:121], v[164:167], v[180:183], v[118:121]
	v_mfma_f32_16x16x32_bf16 v[114:117], v[172:175], v[180:183], v[114:117]
	v_mfma_f32_16x16x32_bf16 v[102:105], v[164:167], v[188:191], v[102:105]
	v_mfma_f32_16x16x32_bf16 v[98:101], v[172:175], v[188:191], v[98:101]
	v_mfma_f32_16x16x32_bf16 v[86:89], v[164:167], v[196:199], v[86:89]
	v_mfma_f32_16x16x32_bf16 v[82:85], v[172:175], v[196:199], v[82:85]
	v_mfma_f32_16x16x32_bf16 v[70:73], v[164:167], v[204:207], v[70:73]
	v_mfma_f32_16x16x32_bf16 v[66:69], v[172:175], v[204:207], v[66:69]
	v_mfma_f32_16x16x32_bf16 v[118:121], v[168:171], v[184:187], v[118:121]
	v_mfma_f32_16x16x32_bf16 v[114:117], v[176:179], v[184:187], v[114:117]
	v_mfma_f32_16x16x32_bf16 v[102:105], v[168:171], v[192:195], v[102:105]
	v_mfma_f32_16x16x32_bf16 v[98:101], v[176:179], v[192:195], v[98:101]
	v_mfma_f32_16x16x32_bf16 v[86:89], v[168:171], v[200:203], v[86:89]
	v_mfma_f32_16x16x32_bf16 v[82:85], v[176:179], v[200:203], v[82:85]
	v_mfma_f32_16x16x32_bf16 v[70:73], v[168:171], v[208:211], v[70:73]
	v_mfma_f32_16x16x32_bf16 v[66:69], v[176:179], v[208:211], v[66:69]
	s_setprio 0
	s_barrier
	s_add_i32 s24, s56, s37
	v_lshl_add_u64 v[212:213], v[212:213], 0, s[12:13]
	s_mov_b32 m0, s24
	ds_read_b128 v[180:183], v150 offset:49152
	ds_read_b128 v[184:187], v150 offset:50176
	ds_read_b128 v[188:191], v150 offset:51200
	ds_read_b128 v[192:195], v150 offset:52224
	ds_read_b128 v[196:199], v150 offset:53248
	ds_read_b128 v[200:203], v150 offset:54272
	ds_read_b128 v[204:207], v150 offset:55296
	ds_read_b128 v[208:211], v150 offset:56320
	global_load_lds_dwordx4 v[212:213], off
	s_add_i32 m0, s24, 0x2000
	s_add_u32 s24, s28, 0x80080
	v_lshl_add_u64 v[212:213], v[214:215], 0, s[12:13]
	s_addc_u32 s25, s29, 0
	s_add_i32 s28, s57, s37
	global_load_lds_dwordx4 v[212:213], off
	v_lshl_add_u64 v[212:213], s[24:25], 0, v[130:131]
	s_mov_b32 m0, s28
	s_nop 0
	global_load_lds_dwordx4 v[212:213], off
	v_lshl_add_u64 v[212:213], s[24:25], 0, v[132:133]
	s_add_i32 m0, s28, 0x2000
	s_nop 0
	global_load_lds_dwordx4 v[212:213], off
	v_lshl_add_u64 v[212:213], v[216:217], 0, s[12:13]
	s_mov_b32 m0, s44
	s_nop 0
	global_load_lds_dwordx4 v[212:213], off
	v_lshl_add_u64 v[212:213], v[218:219], 0, s[12:13]
	s_mov_b32 m0, s45
	s_nop 0
	global_load_lds_dwordx4 v[212:213], off
	s_waitcnt vmcnt(8)
	s_waitcnt lgkmcnt(0)
	s_barrier
	s_setprio 1
	s_waitcnt lgkmcnt(0)
	v_mfma_f32_16x16x32_bf16 v[62:65], v[142:145], v[180:183], v[62:65]
	v_mfma_f32_16x16x32_bf16 v[58:61], v[156:159], v[180:183], v[58:61]
	v_mfma_f32_16x16x32_bf16 v[46:49], v[142:145], v[188:191], v[46:49]
	v_mfma_f32_16x16x32_bf16 v[42:45], v[156:159], v[188:191], v[42:45]
	v_mfma_f32_16x16x32_bf16 v[30:33], v[142:145], v[196:199], v[30:33]
	v_mfma_f32_16x16x32_bf16 v[26:29], v[156:159], v[196:199], v[26:29]
	v_mfma_f32_16x16x32_bf16 v[14:17], v[142:145], v[204:207], v[14:17]
	v_mfma_f32_16x16x32_bf16 v[10:13], v[156:159], v[204:207], v[10:13]
	v_mfma_f32_16x16x32_bf16 v[62:65], v[152:155], v[184:187], v[62:65]
	v_mfma_f32_16x16x32_bf16 v[58:61], v[160:163], v[184:187], v[58:61]
	v_mfma_f32_16x16x32_bf16 v[46:49], v[152:155], v[192:195], v[46:49]
	v_mfma_f32_16x16x32_bf16 v[42:45], v[160:163], v[192:195], v[42:45]
	v_mfma_f32_16x16x32_bf16 v[30:33], v[152:155], v[200:203], v[30:33]
	v_mfma_f32_16x16x32_bf16 v[26:29], v[160:163], v[200:203], v[26:29]
	v_mfma_f32_16x16x32_bf16 v[14:17], v[152:155], v[208:211], v[14:17]
	v_mfma_f32_16x16x32_bf16 v[10:13], v[160:163], v[208:211], v[10:13]
	s_setprio 0
	s_setprio 1
	v_mfma_f32_16x16x32_bf16 v[54:57], v[164:167], v[180:183], v[54:57]
	v_mfma_f32_16x16x32_bf16 v[50:53], v[172:175], v[180:183], v[50:53]
	v_mfma_f32_16x16x32_bf16 v[38:41], v[164:167], v[188:191], v[38:41]
	v_mfma_f32_16x16x32_bf16 v[34:37], v[172:175], v[188:191], v[34:37]
	v_mfma_f32_16x16x32_bf16 v[22:25], v[164:167], v[196:199], v[22:25]
	v_mfma_f32_16x16x32_bf16 v[18:21], v[172:175], v[196:199], v[18:21]
	v_mfma_f32_16x16x32_bf16 v[6:9], v[164:167], v[204:207], v[6:9]
	v_mfma_f32_16x16x32_bf16 v[2:5], v[172:175], v[204:207], v[2:5]
	v_mfma_f32_16x16x32_bf16 v[54:57], v[168:171], v[184:187], v[54:57]
	v_mfma_f32_16x16x32_bf16 v[50:53], v[176:179], v[184:187], v[50:53]
	v_mfma_f32_16x16x32_bf16 v[38:41], v[168:171], v[192:195], v[38:41]
	v_mfma_f32_16x16x32_bf16 v[34:37], v[176:179], v[192:195], v[34:37]
	v_mfma_f32_16x16x32_bf16 v[22:25], v[168:171], v[200:203], v[22:25]
	v_mfma_f32_16x16x32_bf16 v[18:21], v[176:179], v[200:203], v[18:21]
	v_mfma_f32_16x16x32_bf16 v[6:9], v[168:171], v[208:211], v[6:9]
	v_mfma_f32_16x16x32_bf16 v[2:5], v[176:179], v[208:211], v[2:5]
	s_setprio 0
	s_add_i32 s55, s55, 2
	s_add_u32 s53, s53, 0x100
	s_addc_u32 s54, s54, 0
	s_cmp_gt_u32 s55, 29
	s_mov_b64 s[24:25], s[26:27]
	s_barrier
	s_cbranch_scc0 .LBB0_3114
	s_and_b64 vcc, exec, s[14:15]
	s_cbranch_vccz .LBB0_3117
	s_barrier

.LBB0_3201:
	s_waitcnt lgkmcnt(0)
	s_add_u32 s40, s8, 0xfff80080
	s_addc_u32 s41, s9, -1
	s_cmp_eq_u32 s66, 28
	s_cselect_b32 s43, s7, s41
	s_cselect_b32 s42, s35, s40
	s_cselect_b32 s41, s31, s65
	s_cselect_b32 s40, s63, s64
	v_lshl_add_u64 v[216:217], s[8:9], 0, v[138:139]
	s_add_i32 m0, s46, 0xc000
	s_nop 0
	global_load_lds_dwordx4 v[216:217], off
	v_lshl_add_u64 v[216:217], s[8:9], 0, v[140:141]
	s_add_i32 m0, s46, 0xe000
	s_nop 0
	global_load_lds_dwordx4 v[216:217], off
	ds_read_b128 v[146:149], v164
	ds_read_b128 v[150:153], v164 offset:1024
	ds_read_b128 v[154:157], v164 offset:2048
	ds_read_b128 v[158:161], v164 offset:3072
	ds_read_b128 v[168:171], v165
	ds_read_b128 v[172:175], v165 offset:1024
	ds_read_b128 v[176:179], v165 offset:2048
	ds_read_b128 v[180:183], v165 offset:3072
	ds_read_b128 v[184:187], v166
	ds_read_b128 v[188:191], v166 offset:1024
	ds_read_b128 v[192:195], v166 offset:2048
	ds_read_b128 v[196:199], v166 offset:3072
	ds_read_b128 v[200:203], v166 offset:4096
	ds_read_b128 v[204:207], v166 offset:5120
	ds_read_b128 v[208:211], v166 offset:6144
	ds_read_b128 v[212:215], v166 offset:7168
	s_waitcnt vmcnt(8)
	s_waitcnt lgkmcnt(0)
	s_barrier
	s_setprio 1
	s_waitcnt lgkmcnt(0)
	v_mfma_f32_16x16x32_bf16 v[126:129], v[146:149], v[184:187], v[126:129]
	v_mfma_f32_16x16x32_bf16 v[122:125], v[154:157], v[184:187], v[122:125]
	v_mfma_f32_16x16x32_bf16 v[118:121], v[146:149], v[192:195], v[118:121]
	v_mfma_f32_16x16x32_bf16 v[110:113], v[154:157], v[192:195], v[110:113]
	v_mfma_f32_16x16x32_bf16 v[102:105], v[146:149], v[200:203], v[102:105]
	v_mfma_f32_16x16x32_bf16 v[94:97], v[154:157], v[200:203], v[94:97]
	v_mfma_f32_16x16x32_bf16 v[86:89], v[146:149], v[208:211], v[86:89]
	v_mfma_f32_16x16x32_bf16 v[78:81], v[154:157], v[208:211], v[78:81]
	v_mfma_f32_16x16x32_bf16 v[126:129], v[150:153], v[188:191], v[126:129]
	v_mfma_f32_16x16x32_bf16 v[122:125], v[158:161], v[188:191], v[122:125]
	v_mfma_f32_16x16x32_bf16 v[118:121], v[150:153], v[196:199], v[118:121]
	v_mfma_f32_16x16x32_bf16 v[110:113], v[158:161], v[196:199], v[110:113]
	v_mfma_f32_16x16x32_bf16 v[102:105], v[150:153], v[204:207], v[102:105]
	v_mfma_f32_16x16x32_bf16 v[94:97], v[158:161], v[204:207], v[94:97]
	v_mfma_f32_16x16x32_bf16 v[86:89], v[150:153], v[212:215], v[86:89]
	v_mfma_f32_16x16x32_bf16 v[78:81], v[158:161], v[212:215], v[78:81]
	s_setprio 0
	s_setprio 1
	v_mfma_f32_16x16x32_bf16 v[114:117], v[168:171], v[184:187], v[114:117]
	v_mfma_f32_16x16x32_bf16 v[106:109], v[176:179], v[184:187], v[106:109]
	v_mfma_f32_16x16x32_bf16 v[98:101], v[168:171], v[192:195], v[98:101]
	v_mfma_f32_16x16x32_bf16 v[90:93], v[176:179], v[192:195], v[90:93]
	v_mfma_f32_16x16x32_bf16 v[82:85], v[168:171], v[200:203], v[82:85]
	v_mfma_f32_16x16x32_bf16 v[74:77], v[176:179], v[200:203], v[74:77]
	v_mfma_f32_16x16x32_bf16 v[70:73], v[168:171], v[208:211], v[70:73]
	v_mfma_f32_16x16x32_bf16 v[66:69], v[176:179], v[208:211], v[66:69]
	v_mfma_f32_16x16x32_bf16 v[114:117], v[172:175], v[188:191], v[114:117]
	v_mfma_f32_16x16x32_bf16 v[106:109], v[180:183], v[188:191], v[106:109]
	v_mfma_f32_16x16x32_bf16 v[98:101], v[172:175], v[196:199], v[98:101]
	v_mfma_f32_16x16x32_bf16 v[90:93], v[180:183], v[196:199], v[90:93]
	v_mfma_f32_16x16x32_bf16 v[82:85], v[172:175], v[204:207], v[82:85]
	v_mfma_f32_16x16x32_bf16 v[74:77], v[180:183], v[204:207], v[74:77]
	v_mfma_f32_16x16x32_bf16 v[70:73], v[172:175], v[212:215], v[70:73]
	v_mfma_f32_16x16x32_bf16 v[66:69], v[180:183], v[212:215], v[66:69]
	s_setprio 0
	s_barrier
	s_add_i32 s67, s56, s33
	v_lshl_add_u64 v[216:217], s[40:41], 0, v[134:135]
	s_mov_b32 m0, s67
	s_nop 0
	global_load_lds_dwordx4 v[216:217], off
	s_add_i32 m0, s67, 0x2000
	s_add_u32 s68, s40, 0x80000
	v_lshl_add_u64 v[218:219], s[40:41], 0, v[130:131]
	s_addc_u32 s69, s41, 0
	s_add_i32 s67, s57, s33
	global_load_lds_dwordx4 v[218:219], off
	v_lshl_add_u64 v[220:221], s[68:69], 0, v[134:135]
	s_mov_b32 m0, s67
	v_lshl_add_u64 v[222:223], s[42:43], 0, v[132:133]
	global_load_lds_dwordx4 v[220:221], off
	v_lshl_add_u64 v[220:221], s[68:69], 0, v[130:131]
	s_add_i32 m0, s67, 0x2000
	s_nop 0
	global_load_lds_dwordx4 v[220:221], off
	v_lshl_add_u64 v[220:221], s[42:43], 0, v[136:137]
	s_mov_b32 m0, s46
	s_nop 0
	global_load_lds_dwordx4 v[220:221], off
	s_mov_b32 m0, s47
	s_nop 0
	global_load_lds_dwordx4 v[222:223], off
	ds_read_b128 v[184:187], v166 offset:16384
	ds_read_b128 v[188:191], v166 offset:17408
	ds_read_b128 v[192:195], v166 offset:18432
	ds_read_b128 v[196:199], v166 offset:19456
	ds_read_b128 v[200:203], v166 offset:20480
	ds_read_b128 v[204:207], v166 offset:21504
	ds_read_b128 v[208:211], v166 offset:22528
	ds_read_b128 v[212:215], v166 offset:23552
	s_waitcnt vmcnt(8)
	s_waitcnt lgkmcnt(0)
	s_barrier
	s_setprio 1
	s_waitcnt lgkmcnt(0)
	v_mfma_f32_16x16x32_bf16 v[62:65], v[146:149], v[184:187], v[62:65]
	v_mfma_f32_16x16x32_bf16 v[58:61], v[154:157], v[184:187], v[58:61]
	v_mfma_f32_16x16x32_bf16 v[54:57], v[146:149], v[192:195], v[54:57]
	v_mfma_f32_16x16x32_bf16 v[46:49], v[154:157], v[192:195], v[46:49]
	v_mfma_f32_16x16x32_bf16 v[38:41], v[146:149], v[200:203], v[38:41]
	v_mfma_f32_16x16x32_bf16 v[30:33], v[154:157], v[200:203], v[30:33]
	v_mfma_f32_16x16x32_bf16 v[22:25], v[146:149], v[208:211], v[22:25]
	v_mfma_f32_16x16x32_bf16 v[14:17], v[154:157], v[208:211], v[14:17]
	v_mfma_f32_16x16x32_bf16 v[62:65], v[150:153], v[188:191], v[62:65]
	v_mfma_f32_16x16x32_bf16 v[58:61], v[158:161], v[188:191], v[58:61]
	v_mfma_f32_16x16x32_bf16 v[54:57], v[150:153], v[196:199], v[54:57]
	v_mfma_f32_16x16x32_bf16 v[46:49], v[158:161], v[196:199], v[46:49]
	v_mfma_f32_16x16x32_bf16 v[38:41], v[150:153], v[204:207], v[38:41]
	v_mfma_f32_16x16x32_bf16 v[30:33], v[158:161], v[204:207], v[30:33]
	v_mfma_f32_16x16x32_bf16 v[22:25], v[150:153], v[212:215], v[22:25]
	v_mfma_f32_16x16x32_bf16 v[14:17], v[158:161], v[212:215], v[14:17]
	s_setprio 0
	s_setprio 1
	v_mfma_f32_16x16x32_bf16 v[50:53], v[168:171], v[184:187], v[50:53]
	v_mfma_f32_16x16x32_bf16 v[42:45], v[176:179], v[184:187], v[42:45]
	v_mfma_f32_16x16x32_bf16 v[34:37], v[168:171], v[192:195], v[34:37]
	v_mfma_f32_16x16x32_bf16 v[26:29], v[176:179], v[192:195], v[26:29]
	v_mfma_f32_16x16x32_bf16 v[18:21], v[168:171], v[200:203], v[18:21]
	v_mfma_f32_16x16x32_bf16 v[10:13], v[176:179], v[200:203], v[10:13]
	v_mfma_f32_16x16x32_bf16 v[6:9], v[168:171], v[208:211], v[6:9]
	v_mfma_f32_16x16x32_bf16 v[2:5], v[176:179], v[208:211], v[2:5]
	v_mfma_f32_16x16x32_bf16 v[50:53], v[172:175], v[188:191], v[50:53]
	v_mfma_f32_16x16x32_bf16 v[42:45], v[180:183], v[188:191], v[42:45]
	v_mfma_f32_16x16x32_bf16 v[34:37], v[172:175], v[196:199], v[34:37]
	v_mfma_f32_16x16x32_bf16 v[26:29], v[180:183], v[196:199], v[26:29]
	v_mfma_f32_16x16x32_bf16 v[18:21], v[172:175], v[204:207], v[18:21]
	v_mfma_f32_16x16x32_bf16 v[10:13], v[180:183], v[204:207], v[10:13]
	v_mfma_f32_16x16x32_bf16 v[6:9], v[172:175], v[212:215], v[6:9]
	v_mfma_f32_16x16x32_bf16 v[2:5], v[180:183], v[212:215], v[2:5]
	s_setprio 0
	s_barrier
	s_add_i32 s67, 0, 0x18000
	s_add_i32 s68, 0, 0x1c000
	v_add_u32_e32 v158, s67, v163
	v_add_u32_e32 v180, s68, v163
	s_add_u32 s42, s42, 0x80000
	s_addc_u32 s43, s43, 0
	s_mov_b32 m0, s48
	v_lshl_add_u64 v[224:225], s[42:43], 0, v[136:137]
	global_load_lds_dwordx4 v[224:225], off
	v_lshl_add_u64 v[224:225], s[42:43], 0, v[132:133]
	s_mov_b32 m0, s49
	s_nop 0
	global_load_lds_dwordx4 v[224:225], off
	ds_read_b128 v[146:149], v158
	ds_read_b128 v[150:153], v158 offset:1024
	ds_read_b128 v[154:157], v158 offset:2048
	ds_read_b128 v[158:161], v158 offset:3072
	ds_read_b128 v[168:171], v180
	ds_read_b128 v[172:175], v180 offset:1024
	ds_read_b128 v[176:179], v180 offset:2048
	ds_read_b128 v[180:183], v180 offset:3072
	ds_read_b128 v[184:187], v166 offset:32768
	ds_read_b128 v[188:191], v166 offset:33792
	ds_read_b128 v[192:195], v166 offset:34816
	ds_read_b128 v[196:199], v166 offset:35840
	ds_read_b128 v[200:203], v166 offset:36864
	ds_read_b128 v[204:207], v166 offset:37888
	ds_read_b128 v[208:211], v166 offset:38912
	ds_read_b128 v[212:215], v166 offset:39936
	s_waitcnt vmcnt(8)
	s_waitcnt lgkmcnt(0)
	s_barrier
	s_setprio 1
	s_waitcnt lgkmcnt(0)
	v_mfma_f32_16x16x32_bf16 v[126:129], v[146:149], v[184:187], v[126:129]
	v_mfma_f32_16x16x32_bf16 v[122:125], v[154:157], v[184:187], v[122:125]
	v_mfma_f32_16x16x32_bf16 v[118:121], v[146:149], v[192:195], v[118:121]
	v_mfma_f32_16x16x32_bf16 v[110:113], v[154:157], v[192:195], v[110:113]
	v_mfma_f32_16x16x32_bf16 v[102:105], v[146:149], v[200:203], v[102:105]
	v_mfma_f32_16x16x32_bf16 v[94:97], v[154:157], v[200:203], v[94:97]
	v_mfma_f32_16x16x32_bf16 v[86:89], v[146:149], v[208:211], v[86:89]
	v_mfma_f32_16x16x32_bf16 v[78:81], v[154:157], v[208:211], v[78:81]
	v_mfma_f32_16x16x32_bf16 v[126:129], v[150:153], v[188:191], v[126:129]
	v_mfma_f32_16x16x32_bf16 v[122:125], v[158:161], v[188:191], v[122:125]
	v_mfma_f32_16x16x32_bf16 v[118:121], v[150:153], v[196:199], v[118:121]
	v_mfma_f32_16x16x32_bf16 v[110:113], v[158:161], v[196:199], v[110:113]
	v_mfma_f32_16x16x32_bf16 v[102:105], v[150:153], v[204:207], v[102:105]
	v_mfma_f32_16x16x32_bf16 v[94:97], v[158:161], v[204:207], v[94:97]
	v_mfma_f32_16x16x32_bf16 v[86:89], v[150:153], v[212:215], v[86:89]
	v_mfma_f32_16x16x32_bf16 v[78:81], v[158:161], v[212:215], v[78:81]
	s_setprio 0
	s_setprio 1
	v_mfma_f32_16x16x32_bf16 v[114:117], v[168:171], v[184:187], v[114:117]
	v_mfma_f32_16x16x32_bf16 v[106:109], v[176:179], v[184:187], v[106:109]
	v_mfma_f32_16x16x32_bf16 v[98:101], v[168:171], v[192:195], v[98:101]
	v_mfma_f32_16x16x32_bf16 v[90:93], v[176:179], v[192:195], v[90:93]
	v_mfma_f32_16x16x32_bf16 v[82:85], v[168:171], v[200:203], v[82:85]
	v_mfma_f32_16x16x32_bf16 v[74:77], v[176:179], v[200:203], v[74:77]
	v_mfma_f32_16x16x32_bf16 v[70:73], v[168:171], v[208:211], v[70:73]
	v_mfma_f32_16x16x32_bf16 v[66:69], v[176:179], v[208:211], v[66:69]
	v_mfma_f32_16x16x32_bf16 v[114:117], v[172:175], v[188:191], v[114:117]
	v_mfma_f32_16x16x32_bf16 v[106:109], v[180:183], v[188:191], v[106:109]
	v_mfma_f32_16x16x32_bf16 v[98:101], v[172:175], v[196:199], v[98:101]
	v_mfma_f32_16x16x32_bf16 v[90:93], v[180:183], v[196:199], v[90:93]
	v_mfma_f32_16x16x32_bf16 v[82:85], v[172:175], v[204:207], v[82:85]
	v_mfma_f32_16x16x32_bf16 v[74:77], v[180:183], v[204:207], v[74:77]
	v_mfma_f32_16x16x32_bf16 v[70:73], v[172:175], v[212:215], v[70:73]
	v_mfma_f32_16x16x32_bf16 v[66:69], v[180:183], v[212:215], v[66:69]
	s_setprio 0
	s_barrier
	s_add_i32 s42, s67, s33
	v_lshl_add_u64 v[216:217], v[216:217], 0, s[12:13]
	s_mov_b32 m0, s42
	s_nop 0
	global_load_lds_dwordx4 v[216:217], off
	s_add_i32 m0, s42, 0x2000
	s_add_u32 s40, s40, 0x80080
	v_lshl_add_u64 v[216:217], v[218:219], 0, s[12:13]
	s_addc_u32 s41, s41, 0
	s_add_i32 s42, s68, s33
	global_load_lds_dwordx4 v[216:217], off
	v_lshl_add_u64 v[216:217], s[40:41], 0, v[134:135]
	s_mov_b32 m0, s42
	s_nop 0
	global_load_lds_dwordx4 v[216:217], off
	v_lshl_add_u64 v[216:217], s[40:41], 0, v[130:131]
	s_add_i32 m0, s42, 0x2000
	s_nop 0
	global_load_lds_dwordx4 v[216:217], off
	v_lshl_add_u64 v[216:217], v[220:221], 0, s[12:13]
	s_mov_b32 m0, s53
	s_nop 0
	global_load_lds_dwordx4 v[216:217], off
	v_lshl_add_u64 v[216:217], v[222:223], 0, s[12:13]
	s_mov_b32 m0, s54
	s_nop 0
	global_load_lds_dwordx4 v[216:217], off
	ds_read_b128 v[184:187], v166 offset:49152
	ds_read_b128 v[188:191], v166 offset:50176
	ds_read_b128 v[192:195], v166 offset:51200
	ds_read_b128 v[196:199], v166 offset:52224
	ds_read_b128 v[200:203], v166 offset:53248
	ds_read_b128 v[204:207], v166 offset:54272
	ds_read_b128 v[208:211], v166 offset:55296
	ds_read_b128 v[212:215], v166 offset:56320
	s_waitcnt vmcnt(8)
	s_waitcnt lgkmcnt(0)
	s_barrier
	s_setprio 1
	s_waitcnt lgkmcnt(0)
	v_mfma_f32_16x16x32_bf16 v[62:65], v[146:149], v[184:187], v[62:65]
	v_mfma_f32_16x16x32_bf16 v[58:61], v[154:157], v[184:187], v[58:61]
	v_mfma_f32_16x16x32_bf16 v[54:57], v[146:149], v[192:195], v[54:57]
	v_mfma_f32_16x16x32_bf16 v[46:49], v[154:157], v[192:195], v[46:49]
	v_mfma_f32_16x16x32_bf16 v[38:41], v[146:149], v[200:203], v[38:41]
	v_mfma_f32_16x16x32_bf16 v[30:33], v[154:157], v[200:203], v[30:33]
	v_mfma_f32_16x16x32_bf16 v[22:25], v[146:149], v[208:211], v[22:25]
	v_mfma_f32_16x16x32_bf16 v[14:17], v[154:157], v[208:211], v[14:17]
	v_mfma_f32_16x16x32_bf16 v[62:65], v[150:153], v[188:191], v[62:65]
	v_mfma_f32_16x16x32_bf16 v[58:61], v[158:161], v[188:191], v[58:61]
	v_mfma_f32_16x16x32_bf16 v[54:57], v[150:153], v[196:199], v[54:57]
	v_mfma_f32_16x16x32_bf16 v[46:49], v[158:161], v[196:199], v[46:49]
	v_mfma_f32_16x16x32_bf16 v[38:41], v[150:153], v[204:207], v[38:41]
	v_mfma_f32_16x16x32_bf16 v[30:33], v[158:161], v[204:207], v[30:33]
	v_mfma_f32_16x16x32_bf16 v[22:25], v[150:153], v[212:215], v[22:25]
	v_mfma_f32_16x16x32_bf16 v[14:17], v[158:161], v[212:215], v[14:17]
	s_setprio 0
	s_setprio 1
	v_mfma_f32_16x16x32_bf16 v[50:53], v[168:171], v[184:187], v[50:53]
	v_mfma_f32_16x16x32_bf16 v[42:45], v[176:179], v[184:187], v[42:45]
	v_mfma_f32_16x16x32_bf16 v[34:37], v[168:171], v[192:195], v[34:37]
	v_mfma_f32_16x16x32_bf16 v[26:29], v[176:179], v[192:195], v[26:29]
	v_mfma_f32_16x16x32_bf16 v[18:21], v[168:171], v[200:203], v[18:21]
	v_mfma_f32_16x16x32_bf16 v[10:13], v[176:179], v[200:203], v[10:13]
	v_mfma_f32_16x16x32_bf16 v[6:9], v[168:171], v[208:211], v[6:9]
	v_mfma_f32_16x16x32_bf16 v[2:5], v[176:179], v[208:211], v[2:5]
	v_mfma_f32_16x16x32_bf16 v[50:53], v[172:175], v[188:191], v[50:53]
	v_mfma_f32_16x16x32_bf16 v[42:45], v[180:183], v[188:191], v[42:45]
	v_mfma_f32_16x16x32_bf16 v[34:37], v[172:175], v[196:199], v[34:37]
	v_mfma_f32_16x16x32_bf16 v[26:29], v[180:183], v[196:199], v[26:29]
	v_mfma_f32_16x16x32_bf16 v[18:21], v[172:175], v[204:207], v[18:21]
	v_mfma_f32_16x16x32_bf16 v[10:13], v[180:183], v[204:207], v[10:13]
	v_mfma_f32_16x16x32_bf16 v[6:9], v[172:175], v[212:215], v[6:9]
	v_mfma_f32_16x16x32_bf16 v[2:5], v[180:183], v[212:215], v[2:5]
	s_setprio 0
	s_add_i32 s66, s66, 2
	s_add_u32 s8, s8, 0x100
	s_addc_u32 s9, s9, 0
	s_add_u32 s64, s64, 0x100
	s_addc_u32 s65, s65, 0
	s_cmp_gt_u32 s66, 29
	s_barrier
	s_cbranch_scc0 .LBB0_3201
	s_and_b64 vcc, exec, s[14:15]
	s_cbranch_vccz .LBB0_3204
	s_barrier

.LBB0_3378:
	ds_read_b128 v[142:145], v148
	ds_read_b128 v[152:155], v148 offset:1024
	ds_read_b128 v[156:159], v148 offset:2048
	ds_read_b128 v[160:163], v148 offset:3072
	ds_read_b128 v[164:167], v149
	ds_read_b128 v[168:171], v149 offset:1024
	ds_read_b128 v[172:175], v149 offset:2048
	ds_read_b128 v[176:179], v149 offset:3072
	s_add_u32 s20, s18, 0x100
	s_addc_u32 s21, s19, 0
	s_cmpk_eq_i32 s49, 0x54
	s_cselect_b32 s25, s7, s21
	s_cselect_b32 s24, s6, s20
	s_cselect_b32 s23, s17, s48
	s_cselect_b32 s22, s16, s47
	v_lshl_add_u64 v[212:213], s[18:19], 0, v[134:135]
	s_add_i32 m0, s28, 0xc000
	ds_read_b128 v[180:183], v150
	ds_read_b128 v[184:187], v150 offset:1024
	ds_read_b128 v[188:191], v150 offset:2048
	ds_read_b128 v[192:195], v150 offset:3072
	ds_read_b128 v[196:199], v150 offset:4096
	ds_read_b128 v[200:203], v150 offset:5120
	ds_read_b128 v[204:207], v150 offset:6144
	ds_read_b128 v[208:211], v150 offset:7168
	global_load_lds_dwordx4 v[212:213], off
	v_lshl_add_u64 v[212:213], s[18:19], 0, v[136:137]
	s_add_i32 m0, s28, 0xe000
	s_nop 0
	global_load_lds_dwordx4 v[212:213], off
	s_waitcnt vmcnt(8)
	s_waitcnt lgkmcnt(0)
	s_barrier
	s_setprio 1
	s_waitcnt lgkmcnt(0)
	v_mfma_f32_16x16x32_bf16 v[126:129], v[142:145], v[180:183], v[126:129]
	v_mfma_f32_16x16x32_bf16 v[122:125], v[156:159], v[180:183], v[122:125]
	v_mfma_f32_16x16x32_bf16 v[110:113], v[142:145], v[188:191], v[110:113]
	v_mfma_f32_16x16x32_bf16 v[106:109], v[156:159], v[188:191], v[106:109]
	v_mfma_f32_16x16x32_bf16 v[94:97], v[142:145], v[196:199], v[94:97]
	v_mfma_f32_16x16x32_bf16 v[90:93], v[156:159], v[196:199], v[90:93]
	v_mfma_f32_16x16x32_bf16 v[78:81], v[142:145], v[204:207], v[78:81]
	v_mfma_f32_16x16x32_bf16 v[74:77], v[156:159], v[204:207], v[74:77]
	v_mfma_f32_16x16x32_bf16 v[126:129], v[152:155], v[184:187], v[126:129]
	v_mfma_f32_16x16x32_bf16 v[122:125], v[160:163], v[184:187], v[122:125]
	v_mfma_f32_16x16x32_bf16 v[110:113], v[152:155], v[192:195], v[110:113]
	v_mfma_f32_16x16x32_bf16 v[106:109], v[160:163], v[192:195], v[106:109]
	v_mfma_f32_16x16x32_bf16 v[94:97], v[152:155], v[200:203], v[94:97]
	v_mfma_f32_16x16x32_bf16 v[90:93], v[160:163], v[200:203], v[90:93]
	v_mfma_f32_16x16x32_bf16 v[78:81], v[152:155], v[208:211], v[78:81]
	v_mfma_f32_16x16x32_bf16 v[74:77], v[160:163], v[208:211], v[74:77]
	s_setprio 0
	s_setprio 1
	v_mfma_f32_16x16x32_bf16 v[118:121], v[164:167], v[180:183], v[118:121]
	v_mfma_f32_16x16x32_bf16 v[114:117], v[172:175], v[180:183], v[114:117]
	v_mfma_f32_16x16x32_bf16 v[102:105], v[164:167], v[188:191], v[102:105]
	v_mfma_f32_16x16x32_bf16 v[98:101], v[172:175], v[188:191], v[98:101]
	v_mfma_f32_16x16x32_bf16 v[86:89], v[164:167], v[196:199], v[86:89]
	v_mfma_f32_16x16x32_bf16 v[82:85], v[172:175], v[196:199], v[82:85]
	v_mfma_f32_16x16x32_bf16 v[70:73], v[164:167], v[204:207], v[70:73]
	v_mfma_f32_16x16x32_bf16 v[66:69], v[172:175], v[204:207], v[66:69]
	v_mfma_f32_16x16x32_bf16 v[118:121], v[168:171], v[184:187], v[118:121]
	v_mfma_f32_16x16x32_bf16 v[114:117], v[176:179], v[184:187], v[114:117]
	v_mfma_f32_16x16x32_bf16 v[102:105], v[168:171], v[192:195], v[102:105]
	v_mfma_f32_16x16x32_bf16 v[98:101], v[176:179], v[192:195], v[98:101]
	v_mfma_f32_16x16x32_bf16 v[86:89], v[168:171], v[200:203], v[86:89]
	v_mfma_f32_16x16x32_bf16 v[82:85], v[176:179], v[200:203], v[82:85]
	v_mfma_f32_16x16x32_bf16 v[70:73], v[168:171], v[208:211], v[70:73]
	v_mfma_f32_16x16x32_bf16 v[66:69], v[176:179], v[208:211], v[66:69]
	s_setprio 0
	s_barrier
	s_add_i32 s18, s41, s27
	v_lshl_add_u64 v[212:213], s[22:23], 0, v[130:131]
	s_mov_b32 m0, s18
	ds_read_b128 v[180:183], v150 offset:16384
	ds_read_b128 v[184:187], v150 offset:17408
	ds_read_b128 v[188:191], v150 offset:18432
	ds_read_b128 v[192:195], v150 offset:19456
	ds_read_b128 v[196:199], v150 offset:20480
	ds_read_b128 v[200:203], v150 offset:21504
	ds_read_b128 v[204:207], v150 offset:22528
	ds_read_b128 v[208:211], v150 offset:23552
	global_load_lds_dwordx4 v[212:213], off
	s_add_i32 m0, s18, 0x2000
	s_add_u32 s18, s22, 0x160000
	v_lshl_add_u64 v[214:215], s[22:23], 0, v[132:133]
	s_addc_u32 s19, s23, 0
	s_add_i32 s50, s42, s27
	global_load_lds_dwordx4 v[214:215], off
	v_lshl_add_u64 v[216:217], s[18:19], 0, v[130:131]
	s_mov_b32 m0, s50
	v_lshl_add_u64 v[218:219], s[24:25], 0, v[132:133]
	global_load_lds_dwordx4 v[216:217], off
	v_lshl_add_u64 v[216:217], s[18:19], 0, v[132:133]
	s_add_i32 m0, s50, 0x2000
	s_nop 0
	global_load_lds_dwordx4 v[216:217], off
	v_lshl_add_u64 v[216:217], s[24:25], 0, v[130:131]
	s_mov_b32 m0, s28
	s_nop 0
	global_load_lds_dwordx4 v[216:217], off
	s_mov_b32 m0, s29
	s_nop 0
	global_load_lds_dwordx4 v[218:219], off
	s_waitcnt vmcnt(8)
	s_waitcnt lgkmcnt(0)
	s_barrier
	s_setprio 1
	s_waitcnt lgkmcnt(0)
	v_mfma_f32_16x16x32_bf16 v[62:65], v[142:145], v[180:183], v[62:65]
	v_mfma_f32_16x16x32_bf16 v[58:61], v[156:159], v[180:183], v[58:61]
	v_mfma_f32_16x16x32_bf16 v[46:49], v[142:145], v[188:191], v[46:49]
	v_mfma_f32_16x16x32_bf16 v[42:45], v[156:159], v[188:191], v[42:45]
	v_mfma_f32_16x16x32_bf16 v[30:33], v[142:145], v[196:199], v[30:33]
	v_mfma_f32_16x16x32_bf16 v[26:29], v[156:159], v[196:199], v[26:29]
	v_mfma_f32_16x16x32_bf16 v[14:17], v[142:145], v[204:207], v[14:17]
	v_mfma_f32_16x16x32_bf16 v[10:13], v[156:159], v[204:207], v[10:13]
	v_mfma_f32_16x16x32_bf16 v[62:65], v[152:155], v[184:187], v[62:65]
	v_mfma_f32_16x16x32_bf16 v[58:61], v[160:163], v[184:187], v[58:61]
	v_mfma_f32_16x16x32_bf16 v[46:49], v[152:155], v[192:195], v[46:49]
	v_mfma_f32_16x16x32_bf16 v[42:45], v[160:163], v[192:195], v[42:45]
	v_mfma_f32_16x16x32_bf16 v[30:33], v[152:155], v[200:203], v[30:33]
	v_mfma_f32_16x16x32_bf16 v[26:29], v[160:163], v[200:203], v[26:29]
	v_mfma_f32_16x16x32_bf16 v[14:17], v[152:155], v[208:211], v[14:17]
	v_mfma_f32_16x16x32_bf16 v[10:13], v[160:163], v[208:211], v[10:13]
	s_setprio 0
	s_setprio 1
	v_mfma_f32_16x16x32_bf16 v[54:57], v[164:167], v[180:183], v[54:57]
	v_mfma_f32_16x16x32_bf16 v[50:53], v[172:175], v[180:183], v[50:53]
	v_mfma_f32_16x16x32_bf16 v[38:41], v[164:167], v[188:191], v[38:41]
	v_mfma_f32_16x16x32_bf16 v[34:37], v[172:175], v[188:191], v[34:37]
	v_mfma_f32_16x16x32_bf16 v[22:25], v[164:167], v[196:199], v[22:25]
	v_mfma_f32_16x16x32_bf16 v[18:21], v[172:175], v[196:199], v[18:21]
	v_mfma_f32_16x16x32_bf16 v[6:9], v[164:167], v[204:207], v[6:9]
	v_mfma_f32_16x16x32_bf16 v[2:5], v[172:175], v[204:207], v[2:5]
	v_mfma_f32_16x16x32_bf16 v[54:57], v[168:171], v[184:187], v[54:57]
	v_mfma_f32_16x16x32_bf16 v[50:53], v[176:179], v[184:187], v[50:53]
	v_mfma_f32_16x16x32_bf16 v[38:41], v[168:171], v[192:195], v[38:41]
	v_mfma_f32_16x16x32_bf16 v[34:37], v[176:179], v[192:195], v[34:37]
	v_mfma_f32_16x16x32_bf16 v[22:25], v[168:171], v[200:203], v[22:25]
	v_mfma_f32_16x16x32_bf16 v[18:21], v[176:179], v[200:203], v[18:21]
	v_mfma_f32_16x16x32_bf16 v[6:9], v[168:171], v[208:211], v[6:9]
	v_mfma_f32_16x16x32_bf16 v[2:5], v[176:179], v[208:211], v[2:5]
	s_setprio 0
	s_barrier
	s_add_i32 s50, 0, 0x18000
	s_add_i32 s51, 0, 0x1c000
	v_add_u32_e32 v160, s50, v147
	v_add_u32_e32 v176, s51, v147
	ds_read_b128 v[142:145], v160
	ds_read_b128 v[152:155], v160 offset:1024
	ds_read_b128 v[156:159], v160 offset:2048
	ds_read_b128 v[160:163], v160 offset:3072
	ds_read_b128 v[164:167], v176
	ds_read_b128 v[168:171], v176 offset:1024
	ds_read_b128 v[172:175], v176 offset:2048
	ds_read_b128 v[176:179], v176 offset:3072
	s_add_u32 s18, s24, 0x160000
	s_addc_u32 s19, s25, 0
	s_mov_b32 m0, s30
	v_lshl_add_u64 v[220:221], s[18:19], 0, v[130:131]
	ds_read_b128 v[180:183], v150 offset:32768
	ds_read_b128 v[184:187], v150 offset:33792
	ds_read_b128 v[188:191], v150 offset:34816
	ds_read_b128 v[192:195], v150 offset:35840
	ds_read_b128 v[196:199], v150 offset:36864
	ds_read_b128 v[200:203], v150 offset:37888
	ds_read_b128 v[204:207], v150 offset:38912
	ds_read_b128 v[208:211], v150 offset:39936
	global_load_lds_dwordx4 v[220:221], off
	v_lshl_add_u64 v[220:221], s[18:19], 0, v[132:133]
	s_mov_b32 m0, s31
	s_nop 0
	global_load_lds_dwordx4 v[220:221], off
	s_waitcnt vmcnt(8)
	s_waitcnt lgkmcnt(0)
	s_barrier
	s_setprio 1
	s_waitcnt lgkmcnt(0)
	v_mfma_f32_16x16x32_bf16 v[126:129], v[142:145], v[180:183], v[126:129]
	v_mfma_f32_16x16x32_bf16 v[122:125], v[156:159], v[180:183], v[122:125]
	v_mfma_f32_16x16x32_bf16 v[110:113], v[142:145], v[188:191], v[110:113]
	v_mfma_f32_16x16x32_bf16 v[106:109], v[156:159], v[188:191], v[106:109]
	v_mfma_f32_16x16x32_bf16 v[94:97], v[142:145], v[196:199], v[94:97]
	v_mfma_f32_16x16x32_bf16 v[90:93], v[156:159], v[196:199], v[90:93]
	v_mfma_f32_16x16x32_bf16 v[78:81], v[142:145], v[204:207], v[78:81]
	v_mfma_f32_16x16x32_bf16 v[74:77], v[156:159], v[204:207], v[74:77]
	v_mfma_f32_16x16x32_bf16 v[126:129], v[152:155], v[184:187], v[126:129]
	v_mfma_f32_16x16x32_bf16 v[122:125], v[160:163], v[184:187], v[122:125]
	v_mfma_f32_16x16x32_bf16 v[110:113], v[152:155], v[192:195], v[110:113]
	v_mfma_f32_16x16x32_bf16 v[106:109], v[160:163], v[192:195], v[106:109]
	v_mfma_f32_16x16x32_bf16 v[94:97], v[152:155], v[200:203], v[94:97]
	v_mfma_f32_16x16x32_bf16 v[90:93], v[160:163], v[200:203], v[90:93]
	v_mfma_f32_16x16x32_bf16 v[78:81], v[152:155], v[208:211], v[78:81]
	v_mfma_f32_16x16x32_bf16 v[74:77], v[160:163], v[208:211], v[74:77]
	s_setprio 0
	s_setprio 1
	v_mfma_f32_16x16x32_bf16 v[118:121], v[164:167], v[180:183], v[118:121]
	v_mfma_f32_16x16x32_bf16 v[114:117], v[172:175], v[180:183], v[114:117]
	v_mfma_f32_16x16x32_bf16 v[102:105], v[164:167], v[188:191], v[102:105]
	v_mfma_f32_16x16x32_bf16 v[98:101], v[172:175], v[188:191], v[98:101]
	v_mfma_f32_16x16x32_bf16 v[86:89], v[164:167], v[196:199], v[86:89]
	v_mfma_f32_16x16x32_bf16 v[82:85], v[172:175], v[196:199], v[82:85]
	v_mfma_f32_16x16x32_bf16 v[70:73], v[164:167], v[204:207], v[70:73]
	v_mfma_f32_16x16x32_bf16 v[66:69], v[172:175], v[204:207], v[66:69]
	v_mfma_f32_16x16x32_bf16 v[118:121], v[168:171], v[184:187], v[118:121]
	v_mfma_f32_16x16x32_bf16 v[114:117], v[176:179], v[184:187], v[114:117]
	v_mfma_f32_16x16x32_bf16 v[102:105], v[168:171], v[192:195], v[102:105]
	v_mfma_f32_16x16x32_bf16 v[98:101], v[176:179], v[192:195], v[98:101]
	v_mfma_f32_16x16x32_bf16 v[86:89], v[168:171], v[200:203], v[86:89]
	v_mfma_f32_16x16x32_bf16 v[82:85], v[176:179], v[200:203], v[82:85]
	v_mfma_f32_16x16x32_bf16 v[70:73], v[168:171], v[208:211], v[70:73]
	v_mfma_f32_16x16x32_bf16 v[66:69], v[176:179], v[208:211], v[66:69]
	s_setprio 0
	s_barrier
	s_add_i32 s18, s50, s27
	v_lshl_add_u64 v[212:213], v[212:213], 0, s[12:13]
	s_mov_b32 m0, s18
	ds_read_b128 v[180:183], v150 offset:49152
	ds_read_b128 v[184:187], v150 offset:50176
	ds_read_b128 v[188:191], v150 offset:51200
	ds_read_b128 v[192:195], v150 offset:52224
	ds_read_b128 v[196:199], v150 offset:53248
	ds_read_b128 v[200:203], v150 offset:54272
	ds_read_b128 v[204:207], v150 offset:55296
	ds_read_b128 v[208:211], v150 offset:56320
	global_load_lds_dwordx4 v[212:213], off
	s_add_i32 m0, s18, 0x2000
	s_add_u32 s18, s22, 0x160080
	v_lshl_add_u64 v[212:213], v[214:215], 0, s[12:13]
	s_addc_u32 s19, s23, 0
	s_add_i32 s22, s51, s27
	global_load_lds_dwordx4 v[212:213], off
	v_lshl_add_u64 v[212:213], s[18:19], 0, v[130:131]
	s_mov_b32 m0, s22
	s_nop 0
	global_load_lds_dwordx4 v[212:213], off
	v_lshl_add_u64 v[212:213], s[18:19], 0, v[132:133]
	s_add_i32 m0, s22, 0x2000
	s_nop 0
	global_load_lds_dwordx4 v[212:213], off
	v_lshl_add_u64 v[212:213], v[216:217], 0, s[12:13]
	s_mov_b32 m0, s37
	s_nop 0
	global_load_lds_dwordx4 v[212:213], off
	v_lshl_add_u64 v[212:213], v[218:219], 0, s[12:13]
	s_mov_b32 m0, s38
	s_nop 0
	global_load_lds_dwordx4 v[212:213], off
	s_waitcnt vmcnt(8)
	s_waitcnt lgkmcnt(0)
	s_barrier
	s_setprio 1
	s_waitcnt lgkmcnt(0)
	v_mfma_f32_16x16x32_bf16 v[62:65], v[142:145], v[180:183], v[62:65]
	v_mfma_f32_16x16x32_bf16 v[58:61], v[156:159], v[180:183], v[58:61]
	v_mfma_f32_16x16x32_bf16 v[46:49], v[142:145], v[188:191], v[46:49]
	v_mfma_f32_16x16x32_bf16 v[42:45], v[156:159], v[188:191], v[42:45]
	v_mfma_f32_16x16x32_bf16 v[30:33], v[142:145], v[196:199], v[30:33]
	v_mfma_f32_16x16x32_bf16 v[26:29], v[156:159], v[196:199], v[26:29]
	v_mfma_f32_16x16x32_bf16 v[14:17], v[142:145], v[204:207], v[14:17]
	v_mfma_f32_16x16x32_bf16 v[10:13], v[156:159], v[204:207], v[10:13]
	v_mfma_f32_16x16x32_bf16 v[62:65], v[152:155], v[184:187], v[62:65]
	v_mfma_f32_16x16x32_bf16 v[58:61], v[160:163], v[184:187], v[58:61]
	v_mfma_f32_16x16x32_bf16 v[46:49], v[152:155], v[192:195], v[46:49]
	v_mfma_f32_16x16x32_bf16 v[42:45], v[160:163], v[192:195], v[42:45]
	v_mfma_f32_16x16x32_bf16 v[30:33], v[152:155], v[200:203], v[30:33]
	v_mfma_f32_16x16x32_bf16 v[26:29], v[160:163], v[200:203], v[26:29]
	v_mfma_f32_16x16x32_bf16 v[14:17], v[152:155], v[208:211], v[14:17]
	v_mfma_f32_16x16x32_bf16 v[10:13], v[160:163], v[208:211], v[10:13]
	s_setprio 0
	s_setprio 1
	v_mfma_f32_16x16x32_bf16 v[54:57], v[164:167], v[180:183], v[54:57]
	v_mfma_f32_16x16x32_bf16 v[50:53], v[172:175], v[180:183], v[50:53]
	v_mfma_f32_16x16x32_bf16 v[38:41], v[164:167], v[188:191], v[38:41]
	v_mfma_f32_16x16x32_bf16 v[34:37], v[172:175], v[188:191], v[34:37]
	v_mfma_f32_16x16x32_bf16 v[22:25], v[164:167], v[196:199], v[22:25]
	v_mfma_f32_16x16x32_bf16 v[18:21], v[172:175], v[196:199], v[18:21]
	v_mfma_f32_16x16x32_bf16 v[6:9], v[164:167], v[204:207], v[6:9]
	v_mfma_f32_16x16x32_bf16 v[2:5], v[172:175], v[204:207], v[2:5]
	v_mfma_f32_16x16x32_bf16 v[54:57], v[168:171], v[184:187], v[54:57]
	v_mfma_f32_16x16x32_bf16 v[50:53], v[176:179], v[184:187], v[50:53]
	v_mfma_f32_16x16x32_bf16 v[38:41], v[168:171], v[192:195], v[38:41]
	v_mfma_f32_16x16x32_bf16 v[34:37], v[176:179], v[192:195], v[34:37]
	v_mfma_f32_16x16x32_bf16 v[22:25], v[168:171], v[200:203], v[22:25]
	v_mfma_f32_16x16x32_bf16 v[18:21], v[176:179], v[200:203], v[18:21]
	v_mfma_f32_16x16x32_bf16 v[6:9], v[168:171], v[208:211], v[6:9]
	v_mfma_f32_16x16x32_bf16 v[2:5], v[176:179], v[208:211], v[2:5]
	s_setprio 0
	s_add_i32 s49, s49, 2
	s_add_u32 s47, s47, 0x100
	s_addc_u32 s48, s48, 0
	s_cmpk_gt_u32 s49, 0x55
	s_mov_b64 s[18:19], s[20:21]
	s_barrier
	s_cbranch_scc0 .LBB0_3378
	s_and_b64 vcc, exec, s[14:15]
	s_cbranch_vccz .LBB0_3381
	s_barrier

.LBB0_3426:
	ds_read_b128 v[140:143], v181
	ds_read_b128 v[144:147], v181 offset:1024
	ds_read_b128 v[148:151], v181 offset:2048
	ds_read_b128 v[152:155], v181 offset:3072
	ds_read_b128 v[156:159], v182
	ds_read_b128 v[160:163], v182 offset:1024
	ds_read_b128 v[164:167], v182 offset:2048
	ds_read_b128 v[168:171], v182 offset:3072
	s_add_u32 s6, s40, 0x100
	s_addc_u32 s7, s41, 0
	s_cmpk_eq_i32 s68, 0x54
	s_cselect_b32 s45, s37, s7
	s_cselect_b32 s44, s36, s6
	s_cselect_b32 s43, s39, s67
	s_cselect_b32 s42, s38, s66
	v_lshl_add_u64 v[176:177], s[40:41], 0, v[132:133]
	s_add_i32 m0, s23, 0xc000
	ds_read_b128 v[172:175], v183
	ds_read_b128 v[186:189], v183 offset:1024
	ds_read_b128 v[190:193], v183 offset:2048
	ds_read_b128 v[194:197], v183 offset:3072
	ds_read_b128 v[198:201], v183 offset:4096
	ds_read_b128 v[202:205], v183 offset:5120
	ds_read_b128 v[206:209], v183 offset:6144
	ds_read_b128 v[210:213], v183 offset:7168
	global_load_lds_dwordx4 v[176:177], off
	v_lshl_add_u64 v[176:177], s[40:41], 0, v[134:135]
	s_add_i32 m0, s23, 0xe000
	s_nop 0
	global_load_lds_dwordx4 v[176:177], off
	s_waitcnt vmcnt(8)
	s_waitcnt lgkmcnt(0)
	s_barrier
	s_setprio 1
	s_waitcnt lgkmcnt(0)
	v_mfma_f32_16x16x32_bf16 v[124:127], v[140:143], v[172:175], v[124:127]
	v_mfma_f32_16x16x32_bf16 v[120:123], v[148:151], v[172:175], v[120:123]
	v_mfma_f32_16x16x32_bf16 v[108:111], v[140:143], v[190:193], v[108:111]
	v_mfma_f32_16x16x32_bf16 v[104:107], v[148:151], v[190:193], v[104:107]
	v_mfma_f32_16x16x32_bf16 v[92:95], v[140:143], v[198:201], v[92:95]
	v_mfma_f32_16x16x32_bf16 v[88:91], v[148:151], v[198:201], v[88:91]
	v_mfma_f32_16x16x32_bf16 v[76:79], v[140:143], v[206:209], v[76:79]
	v_mfma_f32_16x16x32_bf16 v[72:75], v[148:151], v[206:209], v[72:75]
	v_mfma_f32_16x16x32_bf16 v[124:127], v[144:147], v[186:189], v[124:127]
	v_mfma_f32_16x16x32_bf16 v[120:123], v[152:155], v[186:189], v[120:123]
	v_mfma_f32_16x16x32_bf16 v[108:111], v[144:147], v[194:197], v[108:111]
	v_mfma_f32_16x16x32_bf16 v[104:107], v[152:155], v[194:197], v[104:107]
	v_mfma_f32_16x16x32_bf16 v[92:95], v[144:147], v[202:205], v[92:95]
	v_mfma_f32_16x16x32_bf16 v[88:91], v[152:155], v[202:205], v[88:91]
	v_mfma_f32_16x16x32_bf16 v[76:79], v[144:147], v[210:213], v[76:79]
	v_mfma_f32_16x16x32_bf16 v[72:75], v[152:155], v[210:213], v[72:75]
	s_setprio 0
	s_setprio 1
	v_mfma_f32_16x16x32_bf16 v[116:119], v[156:159], v[172:175], v[116:119]
	v_mfma_f32_16x16x32_bf16 v[112:115], v[164:167], v[172:175], v[112:115]
	v_mfma_f32_16x16x32_bf16 v[100:103], v[156:159], v[190:193], v[100:103]
	v_mfma_f32_16x16x32_bf16 v[96:99], v[164:167], v[190:193], v[96:99]
	v_mfma_f32_16x16x32_bf16 v[84:87], v[156:159], v[198:201], v[84:87]
	v_mfma_f32_16x16x32_bf16 v[80:83], v[164:167], v[198:201], v[80:83]
	v_mfma_f32_16x16x32_bf16 v[68:71], v[156:159], v[206:209], v[68:71]
	v_mfma_f32_16x16x32_bf16 v[64:67], v[164:167], v[206:209], v[64:67]
	v_mfma_f32_16x16x32_bf16 v[116:119], v[160:163], v[186:189], v[116:119]
	v_mfma_f32_16x16x32_bf16 v[112:115], v[168:171], v[186:189], v[112:115]
	v_mfma_f32_16x16x32_bf16 v[100:103], v[160:163], v[194:197], v[100:103]
	v_mfma_f32_16x16x32_bf16 v[96:99], v[168:171], v[194:197], v[96:99]
	v_mfma_f32_16x16x32_bf16 v[84:87], v[160:163], v[202:205], v[84:87]
	v_mfma_f32_16x16x32_bf16 v[80:83], v[168:171], v[202:205], v[80:83]
	v_mfma_f32_16x16x32_bf16 v[68:71], v[160:163], v[210:213], v[68:71]
	v_mfma_f32_16x16x32_bf16 v[64:67], v[168:171], v[210:213], v[64:67]
	s_setprio 0
	s_barrier
	s_add_i32 s40, s59, s21
	v_lshl_add_u64 v[176:177], s[42:43], 0, v[128:129]
	s_mov_b32 m0, s40
	ds_read_b128 v[172:175], v183 offset:16384
	ds_read_b128 v[186:189], v183 offset:17408
	ds_read_b128 v[190:193], v183 offset:18432
	ds_read_b128 v[194:197], v183 offset:19456
	ds_read_b128 v[198:201], v183 offset:20480
	ds_read_b128 v[202:205], v183 offset:21504
	ds_read_b128 v[206:209], v183 offset:22528
	ds_read_b128 v[210:213], v183 offset:23552
	global_load_lds_dwordx4 v[176:177], off
	s_add_i32 m0, s40, 0x2000
	s_add_u32 s40, s42, 0x160000
	v_lshl_add_u64 v[214:215], s[42:43], 0, v[130:131]
	s_addc_u32 s41, s43, 0
	s_add_i32 s69, s60, s21
	global_load_lds_dwordx4 v[214:215], off
	v_lshl_add_u64 v[216:217], s[40:41], 0, v[128:129]
	s_mov_b32 m0, s69
	v_lshl_add_u64 v[218:219], s[44:45], 0, v[130:131]
	global_load_lds_dwordx4 v[216:217], off
	v_lshl_add_u64 v[216:217], s[40:41], 0, v[130:131]
	s_add_i32 m0, s69, 0x2000
	s_nop 0
	global_load_lds_dwordx4 v[216:217], off
	v_lshl_add_u64 v[216:217], s[44:45], 0, v[128:129]
	s_mov_b32 m0, s23
	s_nop 0
	global_load_lds_dwordx4 v[216:217], off
	s_mov_b32 m0, s47
	s_nop 0
	global_load_lds_dwordx4 v[218:219], off
	s_waitcnt vmcnt(8)
	s_waitcnt lgkmcnt(0)
	s_barrier
	s_setprio 1
	s_waitcnt lgkmcnt(0)
	v_mfma_f32_16x16x32_bf16 v[60:63], v[140:143], v[172:175], v[60:63]
	v_mfma_f32_16x16x32_bf16 v[56:59], v[148:151], v[172:175], v[56:59]
	v_mfma_f32_16x16x32_bf16 v[44:47], v[140:143], v[190:193], v[44:47]
	v_mfma_f32_16x16x32_bf16 v[40:43], v[148:151], v[190:193], v[40:43]
	v_mfma_f32_16x16x32_bf16 v[28:31], v[140:143], v[198:201], v[28:31]
	v_mfma_f32_16x16x32_bf16 v[24:27], v[148:151], v[198:201], v[24:27]
	v_mfma_f32_16x16x32_bf16 v[12:15], v[140:143], v[206:209], v[12:15]
	v_mfma_f32_16x16x32_bf16 v[8:11], v[148:151], v[206:209], v[8:11]
	v_mfma_f32_16x16x32_bf16 v[60:63], v[144:147], v[186:189], v[60:63]
	v_mfma_f32_16x16x32_bf16 v[56:59], v[152:155], v[186:189], v[56:59]
	v_mfma_f32_16x16x32_bf16 v[44:47], v[144:147], v[194:197], v[44:47]
	v_mfma_f32_16x16x32_bf16 v[40:43], v[152:155], v[194:197], v[40:43]
	v_mfma_f32_16x16x32_bf16 v[28:31], v[144:147], v[202:205], v[28:31]
	v_mfma_f32_16x16x32_bf16 v[24:27], v[152:155], v[202:205], v[24:27]
	v_mfma_f32_16x16x32_bf16 v[12:15], v[144:147], v[210:213], v[12:15]
	v_mfma_f32_16x16x32_bf16 v[8:11], v[152:155], v[210:213], v[8:11]
	s_setprio 0
	s_setprio 1
	v_mfma_f32_16x16x32_bf16 v[52:55], v[156:159], v[172:175], v[52:55]
	v_mfma_f32_16x16x32_bf16 v[48:51], v[164:167], v[172:175], v[48:51]
	v_mfma_f32_16x16x32_bf16 v[36:39], v[156:159], v[190:193], v[36:39]
	v_mfma_f32_16x16x32_bf16 v[32:35], v[164:167], v[190:193], v[32:35]
	v_mfma_f32_16x16x32_bf16 v[20:23], v[156:159], v[198:201], v[20:23]
	v_mfma_f32_16x16x32_bf16 v[16:19], v[164:167], v[198:201], v[16:19]
	v_mfma_f32_16x16x32_bf16 v[4:7], v[156:159], v[206:209], v[4:7]
	v_mfma_f32_16x16x32_bf16 v[0:3], v[164:167], v[206:209], v[0:3]
	v_mfma_f32_16x16x32_bf16 v[52:55], v[160:163], v[186:189], v[52:55]
	v_mfma_f32_16x16x32_bf16 v[48:51], v[168:171], v[186:189], v[48:51]
	v_mfma_f32_16x16x32_bf16 v[36:39], v[160:163], v[194:197], v[36:39]
	v_mfma_f32_16x16x32_bf16 v[32:35], v[168:171], v[194:197], v[32:35]
	v_mfma_f32_16x16x32_bf16 v[20:23], v[160:163], v[202:205], v[20:23]
	v_mfma_f32_16x16x32_bf16 v[16:19], v[168:171], v[202:205], v[16:19]
	v_mfma_f32_16x16x32_bf16 v[4:7], v[160:163], v[210:213], v[4:7]
	v_mfma_f32_16x16x32_bf16 v[0:3], v[168:171], v[210:213], v[0:3]
	s_setprio 0
	s_barrier
	s_add_i32 s69, 0, 0x18000
	s_add_i32 s70, 0, 0x1c000
	v_add_u32_e32 v152, s69, v180
	v_add_u32_e32 v168, s70, v180
	ds_read_b128 v[140:143], v152
	ds_read_b128 v[144:147], v152 offset:1024
	ds_read_b128 v[148:151], v152 offset:2048
	ds_read_b128 v[152:155], v152 offset:3072
	ds_read_b128 v[156:159], v168
	ds_read_b128 v[160:163], v168 offset:1024
	ds_read_b128 v[164:167], v168 offset:2048
	ds_read_b128 v[168:171], v168 offset:3072
	s_add_u32 s40, s44, 0x160000
	s_addc_u32 s41, s45, 0
	s_mov_b32 m0, s48
	v_lshl_add_u64 v[220:221], s[40:41], 0, v[128:129]
	ds_read_b128 v[172:175], v183 offset:32768
	ds_read_b128 v[186:189], v183 offset:33792
	ds_read_b128 v[190:193], v183 offset:34816
	ds_read_b128 v[194:197], v183 offset:35840
	ds_read_b128 v[198:201], v183 offset:36864
	ds_read_b128 v[202:205], v183 offset:37888
	ds_read_b128 v[206:209], v183 offset:38912
	ds_read_b128 v[210:213], v183 offset:39936
	global_load_lds_dwordx4 v[220:221], off
	v_lshl_add_u64 v[220:221], s[40:41], 0, v[130:131]
	s_mov_b32 m0, s49
	s_nop 0
	global_load_lds_dwordx4 v[220:221], off
	s_waitcnt vmcnt(8)
	s_waitcnt lgkmcnt(0)
	s_barrier
	s_setprio 1
	s_waitcnt lgkmcnt(0)
	v_mfma_f32_16x16x32_bf16 v[124:127], v[140:143], v[172:175], v[124:127]
	v_mfma_f32_16x16x32_bf16 v[120:123], v[148:151], v[172:175], v[120:123]
	v_mfma_f32_16x16x32_bf16 v[108:111], v[140:143], v[190:193], v[108:111]
	v_mfma_f32_16x16x32_bf16 v[104:107], v[148:151], v[190:193], v[104:107]
	v_mfma_f32_16x16x32_bf16 v[92:95], v[140:143], v[198:201], v[92:95]
	v_mfma_f32_16x16x32_bf16 v[88:91], v[148:151], v[198:201], v[88:91]
	v_mfma_f32_16x16x32_bf16 v[76:79], v[140:143], v[206:209], v[76:79]
	v_mfma_f32_16x16x32_bf16 v[72:75], v[148:151], v[206:209], v[72:75]
	v_mfma_f32_16x16x32_bf16 v[124:127], v[144:147], v[186:189], v[124:127]
	v_mfma_f32_16x16x32_bf16 v[120:123], v[152:155], v[186:189], v[120:123]
	v_mfma_f32_16x16x32_bf16 v[108:111], v[144:147], v[194:197], v[108:111]
	v_mfma_f32_16x16x32_bf16 v[104:107], v[152:155], v[194:197], v[104:107]
	v_mfma_f32_16x16x32_bf16 v[92:95], v[144:147], v[202:205], v[92:95]
	v_mfma_f32_16x16x32_bf16 v[88:91], v[152:155], v[202:205], v[88:91]
	v_mfma_f32_16x16x32_bf16 v[76:79], v[144:147], v[210:213], v[76:79]
	v_mfma_f32_16x16x32_bf16 v[72:75], v[152:155], v[210:213], v[72:75]
	s_setprio 0
	s_setprio 1
	v_mfma_f32_16x16x32_bf16 v[116:119], v[156:159], v[172:175], v[116:119]
	v_mfma_f32_16x16x32_bf16 v[112:115], v[164:167], v[172:175], v[112:115]
	v_mfma_f32_16x16x32_bf16 v[100:103], v[156:159], v[190:193], v[100:103]
	v_mfma_f32_16x16x32_bf16 v[96:99], v[164:167], v[190:193], v[96:99]
	v_mfma_f32_16x16x32_bf16 v[84:87], v[156:159], v[198:201], v[84:87]
	v_mfma_f32_16x16x32_bf16 v[80:83], v[164:167], v[198:201], v[80:83]
	v_mfma_f32_16x16x32_bf16 v[68:71], v[156:159], v[206:209], v[68:71]
	v_mfma_f32_16x16x32_bf16 v[64:67], v[164:167], v[206:209], v[64:67]
	v_mfma_f32_16x16x32_bf16 v[116:119], v[160:163], v[186:189], v[116:119]
	v_mfma_f32_16x16x32_bf16 v[112:115], v[168:171], v[186:189], v[112:115]
	v_mfma_f32_16x16x32_bf16 v[100:103], v[160:163], v[194:197], v[100:103]
	v_mfma_f32_16x16x32_bf16 v[96:99], v[168:171], v[194:197], v[96:99]
	v_mfma_f32_16x16x32_bf16 v[84:87], v[160:163], v[202:205], v[84:87]
	v_mfma_f32_16x16x32_bf16 v[80:83], v[168:171], v[202:205], v[80:83]
	v_mfma_f32_16x16x32_bf16 v[68:71], v[160:163], v[210:213], v[68:71]
	v_mfma_f32_16x16x32_bf16 v[64:67], v[168:171], v[210:213], v[64:67]
	s_setprio 0
	s_barrier
	s_add_i32 s40, s69, s21
	v_lshl_add_u64 v[176:177], v[176:177], 0, s[14:15]
	s_mov_b32 m0, s40
	ds_read_b128 v[172:175], v183 offset:49152
	ds_read_b128 v[186:189], v183 offset:50176
	ds_read_b128 v[190:193], v183 offset:51200
	ds_read_b128 v[194:197], v183 offset:52224
	ds_read_b128 v[198:201], v183 offset:53248
	ds_read_b128 v[202:205], v183 offset:54272
	ds_read_b128 v[206:209], v183 offset:55296
	ds_read_b128 v[210:213], v183 offset:56320
	global_load_lds_dwordx4 v[176:177], off
	s_add_i32 m0, s40, 0x2000
	s_add_u32 s40, s42, 0x160080
	v_lshl_add_u64 v[176:177], v[214:215], 0, s[14:15]
	s_addc_u32 s41, s43, 0
	s_add_i32 s42, s70, s21
	global_load_lds_dwordx4 v[176:177], off
	v_lshl_add_u64 v[176:177], s[40:41], 0, v[128:129]
	s_mov_b32 m0, s42
	s_nop 0
	global_load_lds_dwordx4 v[176:177], off
	v_lshl_add_u64 v[176:177], s[40:41], 0, v[130:131]
	s_add_i32 m0, s42, 0x2000
	s_nop 0
	global_load_lds_dwordx4 v[176:177], off
	v_lshl_add_u64 v[176:177], v[216:217], 0, s[14:15]
	s_mov_b32 m0, s56
	s_nop 0
	global_load_lds_dwordx4 v[176:177], off
	v_lshl_add_u64 v[176:177], v[218:219], 0, s[14:15]
	s_mov_b32 m0, s57
	s_nop 0
	global_load_lds_dwordx4 v[176:177], off
	s_waitcnt vmcnt(8)
	s_waitcnt lgkmcnt(0)
	s_barrier
	s_setprio 1
	s_waitcnt lgkmcnt(0)
	v_mfma_f32_16x16x32_bf16 v[60:63], v[140:143], v[172:175], v[60:63]
	v_mfma_f32_16x16x32_bf16 v[56:59], v[148:151], v[172:175], v[56:59]
	v_mfma_f32_16x16x32_bf16 v[44:47], v[140:143], v[190:193], v[44:47]
	v_mfma_f32_16x16x32_bf16 v[40:43], v[148:151], v[190:193], v[40:43]
	v_mfma_f32_16x16x32_bf16 v[28:31], v[140:143], v[198:201], v[28:31]
	v_mfma_f32_16x16x32_bf16 v[24:27], v[148:151], v[198:201], v[24:27]
	v_mfma_f32_16x16x32_bf16 v[12:15], v[140:143], v[206:209], v[12:15]
	v_mfma_f32_16x16x32_bf16 v[8:11], v[148:151], v[206:209], v[8:11]
	v_mfma_f32_16x16x32_bf16 v[60:63], v[144:147], v[186:189], v[60:63]
	v_mfma_f32_16x16x32_bf16 v[56:59], v[152:155], v[186:189], v[56:59]
	v_mfma_f32_16x16x32_bf16 v[44:47], v[144:147], v[194:197], v[44:47]
	v_mfma_f32_16x16x32_bf16 v[40:43], v[152:155], v[194:197], v[40:43]
	v_mfma_f32_16x16x32_bf16 v[28:31], v[144:147], v[202:205], v[28:31]
	v_mfma_f32_16x16x32_bf16 v[24:27], v[152:155], v[202:205], v[24:27]
	v_mfma_f32_16x16x32_bf16 v[12:15], v[144:147], v[210:213], v[12:15]
	v_mfma_f32_16x16x32_bf16 v[8:11], v[152:155], v[210:213], v[8:11]
	s_setprio 0
	s_setprio 1
	v_mfma_f32_16x16x32_bf16 v[52:55], v[156:159], v[172:175], v[52:55]
	v_mfma_f32_16x16x32_bf16 v[48:51], v[164:167], v[172:175], v[48:51]
	v_mfma_f32_16x16x32_bf16 v[36:39], v[156:159], v[190:193], v[36:39]
	v_mfma_f32_16x16x32_bf16 v[32:35], v[164:167], v[190:193], v[32:35]
	v_mfma_f32_16x16x32_bf16 v[20:23], v[156:159], v[198:201], v[20:23]
	v_mfma_f32_16x16x32_bf16 v[16:19], v[164:167], v[198:201], v[16:19]
	v_mfma_f32_16x16x32_bf16 v[4:7], v[156:159], v[206:209], v[4:7]
	v_mfma_f32_16x16x32_bf16 v[0:3], v[164:167], v[206:209], v[0:3]
	v_mfma_f32_16x16x32_bf16 v[52:55], v[160:163], v[186:189], v[52:55]
	v_mfma_f32_16x16x32_bf16 v[48:51], v[168:171], v[186:189], v[48:51]
	v_mfma_f32_16x16x32_bf16 v[36:39], v[160:163], v[194:197], v[36:39]
	v_mfma_f32_16x16x32_bf16 v[32:35], v[168:171], v[194:197], v[32:35]
	v_mfma_f32_16x16x32_bf16 v[20:23], v[160:163], v[202:205], v[20:23]
	v_mfma_f32_16x16x32_bf16 v[16:19], v[168:171], v[202:205], v[16:19]
	v_mfma_f32_16x16x32_bf16 v[4:7], v[160:163], v[210:213], v[4:7]
	v_mfma_f32_16x16x32_bf16 v[0:3], v[168:171], v[210:213], v[0:3]
	s_setprio 0
	s_add_i32 s68, s68, 2
	s_add_u32 s66, s66, 0x100
	s_addc_u32 s67, s67, 0
	s_cmpk_gt_u32 s68, 0x55
	s_mov_b64 s[40:41], s[6:7]
	s_barrier
	s_cbranch_scc0 .LBB0_3426
	s_and_b64 vcc, exec, s[18:19]
	s_cbranch_vccz .LBB0_3429
	s_barrier
